# combo6: combo3b + fragment reads ordered k0-first with lgkmcnt(4)/8 MFMA/lgkmcnt(0)/8 MFMA in the 8-read blocks
# speedup vs baseline: 1.0060x; 1.0060x over previous
; #define PG8_STAGE(bufoff, gbase, voff) do { _Pragma("unroll") for (int _i = 0; _i < 2; ++_i) \
;     __builtin_amdgcn_global_load_lds((const unsigned*)((const char*)(gbase) + (voff)[_i]), (LAS unsigned*)(lds + (bufoff) + ldsw + _i * 8192), 16, 0, 0); } while (0)
; #define PG8_LDA(dst, b, h) do { _Pragma("unroll") for (int m = 0; m < 4; ++m) _Pragma("unroll") for (int k = 0; k < 2; ++k) dst[m][k] = *(const LAS bf16x8*)(lds + PG8_SA(b, h) + aoff + m * 2048 + k * 1024); } while (0)
; #define PG8_LDB(dst, b, h) do { _Pragma("unroll") for (int n = 0; n < 2; ++n) _Pragma("unroll") for (int k = 0; k < 2; ++k) dst[n][k] = *(const LAS bf16x8*)(lds + PG8_SB(b, h) + boff + n * 2048 + k * 1024); } while (0)
; #define PG8_WAIT_V(n) asm volatile("s_waitcnt vmcnt(" #n ")" ::: "memory")
; template <class Epi, class Sched = StaticOrder>
; DI void gemm_phase(LAS unsigned char* lds, const Gemm g, const Sched& S, const Epi& E) {
;     ...
;     for (int t = 0; t < nt; t += 2) {
;       const bool last = (t == nt - 2);
;       const char* a1 = cA + (size_t)(t + 1) * kstep;
;       const char* a2 = last ? nA : cA + (size_t)(t + 2) * kstep; const char* b2 = last ? nB : cB + (size_t)(t + 2) * kstep;
;       const char* a3 = a2 + kstep; const char* b3 = b2 + kstep;
;       PG8_LDB(B0, 0, 0); PG8_SCHED; PG8_LDA(At, 0, 0); PG8_STAGE(PG8_SA(1, 1), a1 + hstep, voffA);
;       PG8_WAIT_L(8); PG8_BAR; PG8_WAIT_L(0); PG8_MMA(0, 0, At, B0); PG8_BAR; PG8_SCHED;
;       PG8_LDB(B1, 0, 1); PG8_STAGE(PG8_SB(0, 0), b2, voffB);
;       PG8_BAR; PG8_WAIT_L(0); PG8_MMA(0, 1, At, B1); PG8_BAR;
;       PG8_LDA(At, 0, 1); PG8_STAGE(PG8_SA(0, 0), a2, voffA);
;       PG8_BAR; PG8_WAIT_L(0); PG8_MMA(1, 0, At, B0); PG8_BAR; PG8_SCHED;
;       PG8_STAGE(PG8_SB(0, 1), b2 + hstep, voffB);
;       PG8_WAIT_V(6); PG8_BAR; PG8_MMA(1, 1, At, B1); PG8_BAR;
;       PG8_LDB(B0, 1, 0); PG8_SCHED; PG8_LDA(At, 1, 0); PG8_STAGE(PG8_SA(0, 1), a2 + hstep, voffA);
;       PG8_WAIT_L(8); PG8_BAR; PG8_WAIT_L(0); PG8_MMA(0, 0, At, B0); PG8_BAR; PG8_SCHED;
;       PG8_LDB(B1, 1, 1); PG8_STAGE(PG8_SB(1, 0), b3, voffB);
;       PG8_BAR; PG8_WAIT_L(0); PG8_MMA(0, 1, At, B1); PG8_BAR;
;       PG8_LDA(At, 1, 1); PG8_STAGE(PG8_SA(1, 0), a3, voffA);
;       PG8_BAR; PG8_WAIT_L(0); PG8_MMA(1, 0, At, B0); PG8_BAR; PG8_SCHED;
;       PG8_STAGE(PG8_SB(1, 1), b3 + hstep, voffB);
;       PG8_WAIT_V(6); PG8_BAR; PG8_MMA(1, 1, At, B1); PG8_BAR;
.LBB0_346:
	s_add_u32 s8, s6, 0xfff80080
	s_addc_u32 s9, s7, -1
	s_cmp_eq_u32 s52, 28
	s_cselect_b32 s11, s31, s9
	s_cselect_b32 s10, s42, s8
	s_cselect_b32 s9, s29, s45
	s_cselect_b32 s8, s43, s44
	s_add_i32 m0, s48, 0xc000
	ds_read_b128 v[162:165], v174
	ds_read_b128 v[178:181], v174 offset:2048
	ds_read_b128 v[186:189], v174 offset:4096
	ds_read_b128 v[194:197], v174 offset:6144
	ds_read_b128 v[166:169], v174 offset:1024
	ds_read_b128 v[182:185], v174 offset:3072
	ds_read_b128 v[190:193], v174 offset:5120
	ds_read_b128 v[198:201], v174 offset:7168
	global_load_lds_dwordx4 v146, s[6:7]
	s_add_i32 m0, s48, 0xe000
	s_nop 0
	global_load_lds_dwordx4 v148, s[6:7]
	s_waitcnt lgkmcnt(8)
	s_setprio 1
	s_barrier
	s_waitcnt lgkmcnt(4)
	v_mfma_f32_16x16x32_bf16 v[124:127], v[128:131], v[162:165], v[124:127]
	v_mfma_f32_16x16x32_bf16 v[120:123], v[154:157], v[162:165], v[120:123]
	v_mfma_f32_16x16x32_bf16 v[108:111], v[128:131], v[178:181], v[108:111]
	v_mfma_f32_16x16x32_bf16 v[104:107], v[154:157], v[178:181], v[104:107]
	v_mfma_f32_16x16x32_bf16 v[100:103], v[128:131], v[186:189], v[100:103]
	v_mfma_f32_16x16x32_bf16 v[92:95], v[154:157], v[186:189], v[92:95]
	v_mfma_f32_16x16x32_bf16 v[84:87], v[128:131], v[194:197], v[84:87]
	v_mfma_f32_16x16x32_bf16 v[76:79], v[154:157], v[194:197], v[76:79]
	s_waitcnt lgkmcnt(0)
	v_mfma_f32_16x16x32_bf16 v[124:127], v[132:135], v[166:169], v[124:127]
	v_mfma_f32_16x16x32_bf16 v[120:123], v[158:161], v[166:169], v[120:123]
	v_mfma_f32_16x16x32_bf16 v[108:111], v[132:135], v[182:185], v[108:111]
	v_mfma_f32_16x16x32_bf16 v[104:107], v[158:161], v[182:185], v[104:107]
	v_mfma_f32_16x16x32_bf16 v[100:103], v[132:135], v[190:193], v[100:103]
	v_mfma_f32_16x16x32_bf16 v[92:95], v[158:161], v[190:193], v[92:95]
	v_mfma_f32_16x16x32_bf16 v[84:87], v[132:135], v[198:201], v[84:87]
	v_mfma_f32_16x16x32_bf16 v[76:79], v[158:161], v[198:201], v[76:79]
	s_barrier
	s_setprio 0
	s_add_i32 s53, s65, s41
	s_add_u32 s98, s8, 0x80
	s_addc_u32 s99, s9, 0
	s_add_u32 s100, s10, 0x80
	s_addc_u32 s101, s11, 0
	s_mov_b32 m0, s53
	ds_read_b128 v[202:205], v175
	ds_read_b128 v[206:209], v175 offset:1024
	ds_read_b128 v[212:215], v175 offset:2048
	ds_read_b128 v[216:219], v175 offset:3072
	global_load_lds_dwordx4 v140, s[8:9]
	s_add_i32 m0, s53, 0x2000
	s_nop 0
	global_load_lds_dwordx4 v136, s[8:9]
	s_setprio 1
	s_barrier
	s_waitcnt lgkmcnt(0)
	v_mfma_f32_16x16x32_bf16 v[116:119], v[202:205], v[162:165], v[116:119]
	v_mfma_f32_16x16x32_bf16 v[112:115], v[212:215], v[162:165], v[112:115]
	v_mfma_f32_16x16x32_bf16 v[96:99], v[202:205], v[178:181], v[96:99]
	v_mfma_f32_16x16x32_bf16 v[88:91], v[212:215], v[178:181], v[88:91]
	v_mfma_f32_16x16x32_bf16 v[80:83], v[202:205], v[186:189], v[80:83]
	v_mfma_f32_16x16x32_bf16 v[72:75], v[212:215], v[186:189], v[72:75]
	v_mfma_f32_16x16x32_bf16 v[68:71], v[202:205], v[194:197], v[68:71]
	v_mfma_f32_16x16x32_bf16 v[64:67], v[212:215], v[194:197], v[64:67]
	v_mfma_f32_16x16x32_bf16 v[116:119], v[206:209], v[166:169], v[116:119]
	v_mfma_f32_16x16x32_bf16 v[112:115], v[216:219], v[166:169], v[112:115]
	v_mfma_f32_16x16x32_bf16 v[96:99], v[206:209], v[182:185], v[96:99]
	v_mfma_f32_16x16x32_bf16 v[88:91], v[216:219], v[182:185], v[88:91]
	v_mfma_f32_16x16x32_bf16 v[80:83], v[206:209], v[190:193], v[80:83]
	v_mfma_f32_16x16x32_bf16 v[72:75], v[216:219], v[190:193], v[72:75]
	v_mfma_f32_16x16x32_bf16 v[68:71], v[206:209], v[198:201], v[68:71]
	v_mfma_f32_16x16x32_bf16 v[64:67], v[216:219], v[198:201], v[64:67]
	s_barrier
	s_setprio 0
	s_mov_b32 m0, s48
	ds_read_b128 v[162:165], v174 offset:16384
	ds_read_b128 v[178:181], v174 offset:18432
	ds_read_b128 v[186:189], v174 offset:20480
	ds_read_b128 v[194:197], v174 offset:22528
	ds_read_b128 v[166:169], v174 offset:17408
	ds_read_b128 v[182:185], v174 offset:19456
	ds_read_b128 v[190:193], v174 offset:21504
	ds_read_b128 v[198:201], v174 offset:23552
	global_load_lds_dwordx4 v142, s[10:11]
	s_mov_b32 m0, s49
	s_nop 0
	global_load_lds_dwordx4 v138, s[10:11]
	s_waitcnt vmcnt(10)
	s_setprio 1
	s_barrier
	s_waitcnt lgkmcnt(4)
	v_mfma_f32_16x16x32_bf16 v[60:63], v[128:131], v[162:165], v[60:63]
	v_mfma_f32_16x16x32_bf16 v[56:59], v[154:157], v[162:165], v[56:59]
	v_mfma_f32_16x16x32_bf16 v[52:55], v[128:131], v[178:181], v[52:55]
	v_mfma_f32_16x16x32_bf16 v[44:47], v[154:157], v[178:181], v[44:47]
	v_mfma_f32_16x16x32_bf16 v[36:39], v[128:131], v[186:189], v[36:39]
	v_mfma_f32_16x16x32_bf16 v[28:31], v[154:157], v[186:189], v[28:31]
	v_mfma_f32_16x16x32_bf16 v[20:23], v[128:131], v[194:197], v[20:23]
	v_mfma_f32_16x16x32_bf16 v[12:15], v[154:157], v[194:197], v[12:15]
	s_waitcnt lgkmcnt(0)
	v_mfma_f32_16x16x32_bf16 v[60:63], v[132:135], v[166:169], v[60:63]
	v_mfma_f32_16x16x32_bf16 v[56:59], v[158:161], v[166:169], v[56:59]
	v_mfma_f32_16x16x32_bf16 v[52:55], v[132:135], v[182:185], v[52:55]
	v_mfma_f32_16x16x32_bf16 v[44:47], v[158:161], v[182:185], v[44:47]
	v_mfma_f32_16x16x32_bf16 v[36:39], v[132:135], v[190:193], v[36:39]
	v_mfma_f32_16x16x32_bf16 v[28:31], v[158:161], v[190:193], v[28:31]
	v_mfma_f32_16x16x32_bf16 v[20:23], v[132:135], v[198:201], v[20:23]
	v_mfma_f32_16x16x32_bf16 v[12:15], v[158:161], v[198:201], v[12:15]
	s_barrier
	s_setprio 0
	s_add_u32 s54, s8, 0x80000
	s_addc_u32 s55, s9, 0
	s_add_i32 s53, s72, s41
	s_mov_b32 m0, s53
	s_nop 0
	global_load_lds_dwordx4 v140, s[54:55]
	s_add_i32 m0, s53, 0x2000
	s_nop 0
	global_load_lds_dwordx4 v136, s[54:55]
	s_add_i32 s53, 0, 0x18000
	v_add_u32_e32 v158, s53, v171
	ds_read_b128 v[128:131], v158
	ds_read_b128 v[132:135], v158 offset:1024
	ds_read_b128 v[154:157], v158 offset:2048
	ds_read_b128 v[158:161], v158 offset:3072
	s_waitcnt vmcnt(6)
	s_setprio 1
	s_barrier
; #define PG8_STAGE(bufoff, gbase, voff) do { _Pragma("unroll") for (int _i = 0; _i < 2; ++_i) \
;     __builtin_amdgcn_global_load_lds((const unsigned*)((const char*)(gbase) + (voff)[_i]), (LAS unsigned*)(lds + (bufoff) + ldsw + _i * 8192), 16, 0, 0); } while (0)
; #define PG8_LDA(dst, b, h) do { _Pragma("unroll") for (int m = 0; m < 4; ++m) _Pragma("unroll") for (int k = 0; k < 2; ++k) dst[m][k] = *(const LAS bf16x8*)(lds + PG8_SA(b, h) + aoff + m * 2048 + k * 1024); } while (0)
; #define PG8_LDB(dst, b, h) do { _Pragma("unroll") for (int n = 0; n < 2; ++n) _Pragma("unroll") for (int k = 0; k < 2; ++k) dst[n][k] = *(const LAS bf16x8*)(lds + PG8_SB(b, h) + boff + n * 2048 + k * 1024); } while (0)
; #define PG8_WAIT_V(n) asm volatile("s_waitcnt vmcnt(" #n ")" ::: "memory")
; template <class Epi, class Sched = StaticOrder>
; DI void gemm_phase(LAS unsigned char* lds, const Gemm g, const Sched& S, const Epi& E) {
;     ...
;     for (int t = 0; t < nt; t += 2) {
;       const bool last = (t == nt - 2);
;       const char* a1 = cA + (size_t)(t + 1) * kstep;
;       const char* a2 = last ? nA : cA + (size_t)(t + 2) * kstep; const char* b2 = last ? nB : cB + (size_t)(t + 2) * kstep;
;       const char* a3 = a2 + kstep; const char* b3 = b2 + kstep;
;       PG8_LDB(B0, 0, 0); PG8_SCHED; PG8_LDA(At, 0, 0); PG8_STAGE(PG8_SA(1, 1), a1 + hstep, voffA);
;       PG8_WAIT_L(8); PG8_BAR; PG8_WAIT_L(0); PG8_MMA(0, 0, At, B0); PG8_BAR; PG8_SCHED;
;       PG8_LDB(B1, 0, 1); PG8_STAGE(PG8_SB(0, 0), b2, voffB);
;       PG8_BAR; PG8_WAIT_L(0); PG8_MMA(0, 1, At, B1); PG8_BAR;
;       PG8_LDA(At, 0, 1); PG8_STAGE(PG8_SA(0, 0), a2, voffA);
;       PG8_BAR; PG8_WAIT_L(0); PG8_MMA(1, 0, At, B0); PG8_BAR; PG8_SCHED;
;       PG8_STAGE(PG8_SB(0, 1), b2 + hstep, voffB);
;       PG8_WAIT_V(6); PG8_BAR; PG8_MMA(1, 1, At, B1); PG8_BAR;
;       PG8_LDB(B0, 1, 0); PG8_SCHED; PG8_LDA(At, 1, 0); PG8_STAGE(PG8_SA(0, 1), a2 + hstep, voffA);
;       PG8_WAIT_L(8); PG8_BAR; PG8_WAIT_L(0); PG8_MMA(0, 0, At, B0); PG8_BAR; PG8_SCHED;
;       PG8_LDB(B1, 1, 1); PG8_STAGE(PG8_SB(1, 0), b3, voffB);
;       PG8_BAR; PG8_WAIT_L(0); PG8_MMA(0, 1, At, B1); PG8_BAR;
;       PG8_LDA(At, 1, 1); PG8_STAGE(PG8_SA(1, 0), a3, voffA);
;       PG8_BAR; PG8_WAIT_L(0); PG8_MMA(1, 0, At, B0); PG8_BAR; PG8_SCHED;
;       PG8_STAGE(PG8_SB(1, 1), b3 + hstep, voffB);
;       PG8_WAIT_V(6); PG8_BAR; PG8_MMA(1, 1, At, B1); PG8_BAR;
	v_mfma_f32_16x16x32_bf16 v[48:51], v[202:205], v[162:165], v[48:51]
	v_mfma_f32_16x16x32_bf16 v[40:43], v[212:215], v[162:165], v[40:43]
	v_mfma_f32_16x16x32_bf16 v[32:35], v[202:205], v[178:181], v[32:35]
	v_mfma_f32_16x16x32_bf16 v[24:27], v[212:215], v[178:181], v[24:27]
	v_mfma_f32_16x16x32_bf16 v[16:19], v[202:205], v[186:189], v[16:19]
	v_mfma_f32_16x16x32_bf16 v[8:11], v[212:215], v[186:189], v[8:11]
	v_mfma_f32_16x16x32_bf16 v[4:7], v[202:205], v[194:197], v[4:7]
	v_mfma_f32_16x16x32_bf16 v[0:3], v[212:215], v[194:197], v[0:3]
	v_mfma_f32_16x16x32_bf16 v[48:51], v[206:209], v[166:169], v[48:51]
	v_mfma_f32_16x16x32_bf16 v[40:43], v[216:219], v[166:169], v[40:43]
	v_mfma_f32_16x16x32_bf16 v[32:35], v[206:209], v[182:185], v[32:35]
	v_mfma_f32_16x16x32_bf16 v[24:27], v[216:219], v[182:185], v[24:27]
	v_mfma_f32_16x16x32_bf16 v[16:19], v[206:209], v[190:193], v[16:19]
	v_mfma_f32_16x16x32_bf16 v[8:11], v[216:219], v[190:193], v[8:11]
	v_mfma_f32_16x16x32_bf16 v[4:7], v[206:209], v[198:201], v[4:7]
	v_mfma_f32_16x16x32_bf16 v[0:3], v[216:219], v[198:201], v[0:3]
	s_barrier
	s_setprio 0
	s_add_u32 s10, s10, 0x80000
	s_addc_u32 s11, s11, 0
	s_mov_b32 m0, s50
	ds_read_b128 v[162:165], v174 offset:32768
	ds_read_b128 v[178:181], v174 offset:34816
	ds_read_b128 v[186:189], v174 offset:36864
	ds_read_b128 v[194:197], v174 offset:38912
	ds_read_b128 v[166:169], v174 offset:33792
	ds_read_b128 v[182:185], v174 offset:35840
	ds_read_b128 v[190:193], v174 offset:37888
	ds_read_b128 v[198:201], v174 offset:39936
	global_load_lds_dwordx4 v142, s[10:11]
	s_mov_b32 m0, s51
	s_nop 0
	global_load_lds_dwordx4 v138, s[10:11]
	s_waitcnt lgkmcnt(8)
	s_setprio 1
	s_barrier
	s_waitcnt lgkmcnt(4)
	v_mfma_f32_16x16x32_bf16 v[124:127], v[128:131], v[162:165], v[124:127]
	v_mfma_f32_16x16x32_bf16 v[120:123], v[154:157], v[162:165], v[120:123]
	v_mfma_f32_16x16x32_bf16 v[108:111], v[128:131], v[178:181], v[108:111]
	v_mfma_f32_16x16x32_bf16 v[104:107], v[154:157], v[178:181], v[104:107]
	v_mfma_f32_16x16x32_bf16 v[100:103], v[128:131], v[186:189], v[100:103]
	v_mfma_f32_16x16x32_bf16 v[92:95], v[154:157], v[186:189], v[92:95]
	v_mfma_f32_16x16x32_bf16 v[84:87], v[128:131], v[194:197], v[84:87]
	v_mfma_f32_16x16x32_bf16 v[76:79], v[154:157], v[194:197], v[76:79]
	s_waitcnt lgkmcnt(0)
	v_mfma_f32_16x16x32_bf16 v[124:127], v[132:135], v[166:169], v[124:127]
	v_mfma_f32_16x16x32_bf16 v[120:123], v[158:161], v[166:169], v[120:123]
	v_mfma_f32_16x16x32_bf16 v[108:111], v[132:135], v[182:185], v[108:111]
	v_mfma_f32_16x16x32_bf16 v[104:107], v[158:161], v[182:185], v[104:107]
	v_mfma_f32_16x16x32_bf16 v[100:103], v[132:135], v[190:193], v[100:103]
	v_mfma_f32_16x16x32_bf16 v[92:95], v[158:161], v[190:193], v[92:95]
	v_mfma_f32_16x16x32_bf16 v[84:87], v[132:135], v[198:201], v[84:87]
	v_mfma_f32_16x16x32_bf16 v[76:79], v[158:161], v[198:201], v[76:79]
	s_barrier
	s_setprio 0
	s_add_i32 s10, 0, 0x1c000
	s_add_i32 s11, s53, s41
	v_add_u32_e32 v177, s10, v171
	s_mov_b32 m0, s11
	ds_read_b128 v[202:205], v177
	ds_read_b128 v[206:209], v177 offset:1024
	ds_read_b128 v[212:215], v177 offset:2048
	ds_read_b128 v[216:219], v177 offset:3072
	global_load_lds_dwordx4 v140, s[98:99]
	s_add_i32 m0, s11, 0x2000
	s_nop 0
	global_load_lds_dwordx4 v136, s[98:99]
	s_setprio 1
	s_barrier
	s_waitcnt lgkmcnt(0)
	v_mfma_f32_16x16x32_bf16 v[116:119], v[202:205], v[162:165], v[116:119]
	v_mfma_f32_16x16x32_bf16 v[112:115], v[212:215], v[162:165], v[112:115]
	v_mfma_f32_16x16x32_bf16 v[96:99], v[202:205], v[178:181], v[96:99]
	v_mfma_f32_16x16x32_bf16 v[88:91], v[212:215], v[178:181], v[88:91]
	v_mfma_f32_16x16x32_bf16 v[80:83], v[202:205], v[186:189], v[80:83]
	v_mfma_f32_16x16x32_bf16 v[72:75], v[212:215], v[186:189], v[72:75]
	v_mfma_f32_16x16x32_bf16 v[68:71], v[202:205], v[194:197], v[68:71]
	v_mfma_f32_16x16x32_bf16 v[64:67], v[212:215], v[194:197], v[64:67]
	v_mfma_f32_16x16x32_bf16 v[116:119], v[206:209], v[166:169], v[116:119]
	v_mfma_f32_16x16x32_bf16 v[112:115], v[216:219], v[166:169], v[112:115]
	v_mfma_f32_16x16x32_bf16 v[96:99], v[206:209], v[182:185], v[96:99]
	v_mfma_f32_16x16x32_bf16 v[88:91], v[216:219], v[182:185], v[88:91]
	v_mfma_f32_16x16x32_bf16 v[80:83], v[206:209], v[190:193], v[80:83]
	v_mfma_f32_16x16x32_bf16 v[72:75], v[216:219], v[190:193], v[72:75]
	v_mfma_f32_16x16x32_bf16 v[68:71], v[206:209], v[198:201], v[68:71]
	v_mfma_f32_16x16x32_bf16 v[64:67], v[216:219], v[198:201], v[64:67]
	s_barrier
	s_setprio 0
	s_mov_b32 m0, s56
	ds_read_b128 v[162:165], v174 offset:49152
	ds_read_b128 v[178:181], v174 offset:51200
	ds_read_b128 v[186:189], v174 offset:53248
	ds_read_b128 v[194:197], v174 offset:55296
	ds_read_b128 v[166:169], v174 offset:50176
	ds_read_b128 v[182:185], v174 offset:52224
	ds_read_b128 v[190:193], v174 offset:54272
	ds_read_b128 v[198:201], v174 offset:56320
	global_load_lds_dwordx4 v142, s[100:101]
	s_mov_b32 m0, s57
	s_nop 0
	global_load_lds_dwordx4 v138, s[100:101]
	s_waitcnt vmcnt(10)
	s_setprio 1
	s_barrier
	s_waitcnt lgkmcnt(4)
	v_mfma_f32_16x16x32_bf16 v[60:63], v[128:131], v[162:165], v[60:63]
	v_mfma_f32_16x16x32_bf16 v[56:59], v[154:157], v[162:165], v[56:59]
	v_mfma_f32_16x16x32_bf16 v[52:55], v[128:131], v[178:181], v[52:55]
	v_mfma_f32_16x16x32_bf16 v[44:47], v[154:157], v[178:181], v[44:47]
	v_mfma_f32_16x16x32_bf16 v[36:39], v[128:131], v[186:189], v[36:39]
	v_mfma_f32_16x16x32_bf16 v[28:31], v[154:157], v[186:189], v[28:31]
	v_mfma_f32_16x16x32_bf16 v[20:23], v[128:131], v[194:197], v[20:23]
	v_mfma_f32_16x16x32_bf16 v[12:15], v[154:157], v[194:197], v[12:15]
	s_waitcnt lgkmcnt(0)
	v_mfma_f32_16x16x32_bf16 v[60:63], v[132:135], v[166:169], v[60:63]
	v_mfma_f32_16x16x32_bf16 v[56:59], v[158:161], v[166:169], v[56:59]
	v_mfma_f32_16x16x32_bf16 v[52:55], v[132:135], v[182:185], v[52:55]
	v_mfma_f32_16x16x32_bf16 v[44:47], v[158:161], v[182:185], v[44:47]
	v_mfma_f32_16x16x32_bf16 v[36:39], v[132:135], v[190:193], v[36:39]
	v_mfma_f32_16x16x32_bf16 v[28:31], v[158:161], v[190:193], v[28:31]
	v_mfma_f32_16x16x32_bf16 v[20:23], v[132:135], v[198:201], v[20:23]
	v_mfma_f32_16x16x32_bf16 v[12:15], v[158:161], v[198:201], v[12:15]
	s_barrier
; #define PG8_STAGE(bufoff, gbase, voff) do { _Pragma("unroll") for (int _i = 0; _i < 2; ++_i) \
;     __builtin_amdgcn_global_load_lds((const unsigned*)((const char*)(gbase) + (voff)[_i]), (LAS unsigned*)(lds + (bufoff) + ldsw + _i * 8192), 16, 0, 0); } while (0)
; #define PG8_MMA(ai, bj, At, Bt) do { __builtin_amdgcn_s_setprio(1); _Pragma("unroll") for (int m = 0; m < 4; ++m) _Pragma("unroll") for (int n = 0; n < 2; ++n) _Pragma("unroll") for (int k = 0; k < 2; ++k) \
;     acc[ai][bj][m][n] = __builtin_amdgcn_mfma_f32_16x16x32_bf16(Bt[n][k], At[m][k], acc[ai][bj][m][n], 0, 0, 0); __builtin_amdgcn_s_setprio(0); } while (0)
; #define PG8_WAIT_V(n) asm volatile("s_waitcnt vmcnt(" #n ")" ::: "memory")
; #define PG8_WAIT_L(n) asm volatile("s_waitcnt lgkmcnt(" #n ")" ::: "memory")
; #define PG8_BAR __builtin_amdgcn_s_barrier()
; #define PG8_SCHED __builtin_amdgcn_sched_barrier(0)
; DI float row_rstd(const float* ssq, int row, int fq) {
;   const f32x4 a = *(const f32x4*)(ssq + (size_t)row * 32 + fq * 8), b = *(const f32x4*)(ssq + (size_t)row * 32 + fq * 8 + 4);
;   float sm = ((a[0] + a[1]) + (a[2] + a[3])) + ((b[0] + b[1]) + (b[2] + b[3]));
;   sm += __shfl_xor(sm, 16); sm += __shfl_xor(sm, 32);
;   return rsqrtf(sm * (1.0f / 2048.f) + 1e-6f);
; }
;   DI void operator()(const f32x4 (&acc)[2][2][4][2], const Unit& u, int wr, int wc, int fr, int fq) const {
;     const int row0 = u.pm * BM + wr * 64 + fr, col0 = u.pn * BM + wc * 32 + 8 * fq;
;     float rsv[2][4];
; #pragma unroll
;     for (int ai = 0; ai < 2; ++ai)
; #pragma unroll
;       for (int m = 0; m < 4; ++m) rsv[ai][m] = row_rstd(ssq, row0 + ai * HALF + m * 16, fq);
; template <class Epi, class Sched = StaticOrder>
; DI void gemm_phase(LAS unsigned char* lds, const Gemm g, const Sched& S, const Epi& E) {
;     ...
;       PG8_BAR; PG8_WAIT_L(0); PG8_MMA(1, 0, At, B0); PG8_BAR; PG8_SCHED;
;       PG8_STAGE(PG8_SB(1, 1), b3 + hstep, voffB);
;       PG8_WAIT_V(6); PG8_BAR; PG8_MMA(1, 1, At, B1); PG8_BAR;
;     }
;     E(acc, cur, wr, wc, fr, fq);
	s_setprio 0
	s_add_u32 s8, s8, 0x80080
	s_addc_u32 s9, s9, 0
	s_add_i32 s10, s10, s41
	s_mov_b32 m0, s10
	s_nop 0
	global_load_lds_dwordx4 v140, s[8:9]
	s_add_i32 m0, s10, 0x2000
	s_nop 0
	global_load_lds_dwordx4 v136, s[8:9]
	ds_read_b128 v[128:131], v173
	ds_read_b128 v[132:135], v173 offset:1024
	ds_read_b128 v[154:157], v173 offset:2048
	ds_read_b128 v[158:161], v173 offset:3072
	s_waitcnt vmcnt(6)
	s_setprio 1
	s_barrier
	v_mfma_f32_16x16x32_bf16 v[48:51], v[202:205], v[162:165], v[48:51]
	v_mfma_f32_16x16x32_bf16 v[40:43], v[212:215], v[162:165], v[40:43]
	v_mfma_f32_16x16x32_bf16 v[32:35], v[202:205], v[178:181], v[32:35]
	v_mfma_f32_16x16x32_bf16 v[24:27], v[212:215], v[178:181], v[24:27]
	v_mfma_f32_16x16x32_bf16 v[16:19], v[202:205], v[186:189], v[16:19]
	v_mfma_f32_16x16x32_bf16 v[8:11], v[212:215], v[186:189], v[8:11]
	v_mfma_f32_16x16x32_bf16 v[4:7], v[202:205], v[194:197], v[4:7]
	v_mfma_f32_16x16x32_bf16 v[0:3], v[212:215], v[194:197], v[0:3]
	v_mfma_f32_16x16x32_bf16 v[48:51], v[206:209], v[166:169], v[48:51]
	v_mfma_f32_16x16x32_bf16 v[40:43], v[216:219], v[166:169], v[40:43]
	v_mfma_f32_16x16x32_bf16 v[32:35], v[206:209], v[182:185], v[32:35]
	v_mfma_f32_16x16x32_bf16 v[24:27], v[216:219], v[182:185], v[24:27]
	v_mfma_f32_16x16x32_bf16 v[16:19], v[206:209], v[190:193], v[16:19]
	v_mfma_f32_16x16x32_bf16 v[8:11], v[216:219], v[190:193], v[8:11]
	v_mfma_f32_16x16x32_bf16 v[4:7], v[206:209], v[198:201], v[4:7]
	v_mfma_f32_16x16x32_bf16 v[0:3], v[216:219], v[198:201], v[0:3]
	s_add_i32 s52, s52, 2
	s_add_u32 s6, s6, 0x100
	s_addc_u32 s7, s7, 0
	s_add_u32 s44, s44, 0x100
	s_addc_u32 s45, s45, 0
	s_cmp_gt_u32 s52, 29
	s_barrier
	s_setprio 0
	s_cbranch_scc0 .LBB0_346
	s_waitcnt lgkmcnt(0)
	v_lshl_add_u32 v168, s4, 8, v170
	v_ashrrev_i32_e32 v169, 31, v168
	v_or_b32_e32 v154, 16, v168
	v_lshlrev_b64 v[128:129], 7, v[168:169]
	v_ashrrev_i32_e32 v155, 31, v154
	v_lshl_add_u64 v[128:129], v[144:145], 0, v[128:129]
	v_lshlrev_b64 v[156:157], 7, v[154:155]
	global_load_dwordx4 v[132:135], v[128:129], off
	s_nop 0
	global_load_dwordx4 v[128:131], v[128:129], off offset:16
	v_lshl_add_u64 v[156:157], v[144:145], 0, v[156:157]
	global_load_dwordx4 v[178:181], v[156:157], off
	global_load_dwordx4 v[182:185], v[156:157], off offset:16
	v_or_b32_e32 v160, 32, v168
	v_ashrrev_i32_e32 v161, 31, v160
	v_lshlrev_b64 v[156:157], 7, v[160:161]
	v_lshl_add_u64 v[156:157], v[144:145], 0, v[156:157]
	global_load_dwordx4 v[186:189], v[156:157], off
	global_load_dwordx4 v[190:193], v[156:157], off offset:16
	v_or_b32_e32 v156, 48, v168
	v_ashrrev_i32_e32 v157, 31, v156
	v_lshlrev_b64 v[158:159], 7, v[156:157]
	v_lshl_add_u64 v[158:159], v[144:145], 0, v[158:159]
	global_load_dwordx4 v[194:197], v[158:159], off
	global_load_dwordx4 v[198:201], v[158:159], off offset:16
	v_add_u32_e32 v164, 0x80, v168
	v_ashrrev_i32_e32 v165, 31, v164
	v_lshlrev_b64 v[158:159], 7, v[164:165]
	v_lshl_add_u64 v[158:159], v[144:145], 0, v[158:159]
	global_load_dwordx4 v[202:205], v[158:159], off
	global_load_dwordx4 v[206:209], v[158:159], off offset:16
	v_add_u32_e32 v158, 0x90, v168
	v_ashrrev_i32_e32 v159, 31, v158
	v_lshlrev_b64 v[162:163], 7, v[158:159]
	v_lshl_add_u64 v[162:163], v[144:145], 0, v[162:163]
	global_load_dwordx4 v[212:215], v[162:163], off
	global_load_dwordx4 v[216:219], v[162:163], off offset:16
	v_add_u32_e32 v166, 0xa0, v168
	v_ashrrev_i32_e32 v167, 31, v166
	v_lshlrev_b64 v[162:163], 7, v[166:167]
	v_lshl_add_u64 v[162:163], v[144:145], 0, v[162:163]
	global_load_dwordx4 v[220:223], v[162:163], off
	global_load_dwordx4 v[224:227], v[162:163], off offset:16
	v_add_u32_e32 v162, 0xb0, v168
	v_ashrrev_i32_e32 v163, 31, v162
	v_lshlrev_b64 v[228:229], 7, v[162:163]
	v_lshl_add_u64 v[232:233], v[144:145], 0, v[228:229]
	global_load_dwordx4 v[228:231], v[232:233], off
	s_nop 0
	global_load_dwordx4 v[232:235], v[232:233], off offset:16
	s_waitcnt vmcnt(0)
	v_mov_b32_e32 v236, v132
	v_mov_b32_e32 v237, v128
	v_mov_b32_e32 v128, v133
	v_mov_b32_e32 v132, v134
	v_mov_b32_e32 v133, v130
	v_mov_b32_e32 v130, v135
	v_pk_add_f32 v[130:131], v[132:133], v[130:131]
	v_mov_b32_e32 v132, v178
	v_mov_b32_e32 v133, v182
	v_mov_b32_e32 v182, v179
	v_mov_b32_e32 v134, v180
	v_mov_b32_e32 v135, v184
	v_mov_b32_e32 v184, v181
	v_pk_add_f32 v[128:129], v[236:237], v[128:129]
	v_pk_add_f32 v[132:133], v[132:133], v[182:183]
	v_pk_add_f32 v[134:135], v[134:135], v[184:185]
	v_pk_add_f32 v[128:129], v[128:129], v[130:131]
	v_pk_add_f32 v[130:131], v[132:133], v[134:135]
	v_mov_b32_e32 v133, v128
	v_mov_b32_e32 v132, v130
	v_and_b32_e32 v130, 64, v176
	v_add_u32_e32 v155, 64, v130
	v_xor_b32_e32 v130, 16, v176
	v_cmp_lt_i32_e32 vcc, v130, v155
	v_mov_b32_e32 v128, v131
	v_pk_add_f32 v[128:129], v[132:133], v[128:129]
	v_cndmask_b32_e32 v130, v176, v130, vcc
	v_lshlrev_b32_e32 v157, 2, v130
	ds_bpermute_b32 v131, v157, v129
	ds_bpermute_b32 v130, v157, v128
	v_mov_b32_e32 v178, v186
	v_mov_b32_e32 v179, v190
	v_mov_b32_e32 v190, v187
	v_mov_b32_e32 v186, v194
	s_waitcnt lgkmcnt(0)
	v_pk_add_f32 v[128:129], v[128:129], v[130:131]
	v_xor_b32_e32 v130, 32, v176
	v_cmp_lt_i32_e32 vcc, v130, v155
	v_mov_b32_e32 v187, v198
	v_mov_b32_e32 v198, v195
	v_cndmask_b32_e32 v130, v176, v130, vcc
	v_lshlrev_b32_e32 v155, 2, v130
	ds_bpermute_b32 v131, v155, v129
	ds_bpermute_b32 v130, v155, v128
	v_pk_add_f32 v[182:183], v[186:187], v[198:199]
	v_mov_b32_e32 v180, v188
	v_mov_b32_e32 v181, v192
	v_mov_b32_e32 v192, v189
	s_waitcnt lgkmcnt(0)
; DI unsigned pack2(float lo, float hi) { f32x2 v = {lo, hi}; bf16v2 r = __builtin_convertvector(v, bf16v2); return __builtin_bit_cast(unsigned, r); }
; DI float row_rstd(const float* ssq, int row, int fq) {
;   const f32x4 a = *(const f32x4*)(ssq + (size_t)row * 32 + fq * 8), b = *(const f32x4*)(ssq + (size_t)row * 32 + fq * 8 + 4);
;   float sm = ((a[0] + a[1]) + (a[2] + a[3])) + ((b[0] + b[1]) + (b[2] + b[3]));
;   sm += __shfl_xor(sm, 16); sm += __shfl_xor(sm, 32);
;   return rsqrtf(sm * (1.0f / 2048.f) + 1e-6f);
; }
;   DI void operator()(const f32x4 (&acc)[2][2][4][2], const Unit& u, int wr, int wc, int fr, int fq) const {
;     ...
;     for (int ai = 0; ai < 2; ++ai)
; #pragma unroll
;       for (int m = 0; m < 4; ++m) {
;         const int row = row0 + ai * HALF + m * 16;
;         const float rs = rsv[ai][m];
;         bf16_t* rowp = O + (size_t)row * ldc + col0;
; #pragma unroll
;         for (int bj = 0; bj < 2; ++bj) {
;           const f32x4 v0 = acc[ai][bj][m][0] * rs, v1 = acc[ai][bj][m][1] * rs;
;           u32x4 w; w.x = pack2(v0[0], v0[1]); w.y = pack2(v0[2], v0[3]); w.z = pack2(v1[0], v1[1]); w.w = pack2(v1[2], v1[3]);
;           *(u32x4*)(rowp + bj * HALF) = w;
	v_pk_add_f32 v[128:129], v[128:129], v[130:131]
	v_mov_b64_e32 v[130:131], s[26:27]
	v_pk_fma_f32 v[128:129], v[128:129], s[24:25], v[130:131] op_sel_hi:[1,0,0]
	v_mov_b32_e32 v188, v196
	v_mul_f32_e32 v159, 0x4b800000, v129
	v_cmp_gt_f32_e32 vcc, s73, v129
	v_mov_b32_e32 v189, v200
	v_mov_b32_e32 v200, v197
	v_cndmask_b32_e32 v129, v129, v159, vcc
	v_rsq_f32_e32 v129, v129
	v_pk_add_f32 v[178:179], v[178:179], v[190:191]
	v_pk_add_f32 v[180:181], v[180:181], v[192:193]
	v_pk_add_f32 v[184:185], v[188:189], v[200:201]
	v_mul_f32_e32 v159, 0x45800000, v129
	v_cndmask_b32_e32 v198, v129, v159, vcc
	v_pk_mul_f32 v[126:127], v[126:127], v[198:199] op_sel_hi:[1,0]
	v_pk_mul_f32 v[124:125], v[124:125], v[198:199] op_sel_hi:[1,0]
	v_pk_mul_f32 v[122:123], v[122:123], v[198:199] op_sel_hi:[1,0]
	v_pk_mul_f32 v[120:121], v[120:121], v[198:199] op_sel_hi:[1,0]
	v_cvt_pk_bf16_f32 v124, v124, v125
	v_cvt_pk_bf16_f32 v125, v126, v127
	v_cvt_pk_bf16_f32 v127, v122, v123
	v_lshl_or_b32 v122, s5, 8, v172
	v_cvt_pk_bf16_f32 v126, v120, v121
	v_ashrrev_i32_e32 v123, 31, v122
	v_mov_b64_e32 v[120:121], s[2:3]
	v_mad_i64_i32 v[168:169], s[4:5], v168, s76, v[120:121]
	v_lshlrev_b64 v[122:123], 1, v[122:123]
	v_lshl_add_u64 v[168:169], v[168:169], 0, v[122:123]
	global_store_dwordx4 v[168:169], v[124:127], off
	v_mov_b32_e32 v194, v202
	v_mov_b32_e32 v195, v206
	v_pk_add_f32 v[124:125], v[178:179], v[180:181]
	v_pk_add_f32 v[126:127], v[182:183], v[184:185]
	v_mov_b32_e32 v179, v124
	v_mov_b32_e32 v178, v126
	v_mov_b32_e32 v124, v127
	v_pk_add_f32 v[124:125], v[178:179], v[124:125]
	ds_bpermute_b32 v127, v157, v125
	ds_bpermute_b32 v126, v157, v124
	v_mov_b32_e32 v206, v203
	v_mov_b32_e32 v196, v204
	v_mov_b32_e32 v197, v208
	v_mov_b32_e32 v208, v205
	v_mov_b32_e32 v202, v212
	v_mov_b32_e32 v203, v216
	v_mov_b32_e32 v216, v213
	v_mov_b32_e32 v204, v214
	v_mov_b32_e32 v205, v218
	v_mov_b32_e32 v218, v215
	v_pk_add_f32 v[186:187], v[194:195], v[206:207]
	v_pk_add_f32 v[188:189], v[196:197], v[208:209]
	v_pk_add_f32 v[190:191], v[202:203], v[216:217]
	v_pk_add_f32 v[192:193], v[204:205], v[218:219]
	v_pk_mul_f32 v[178:179], v[114:115], v[198:199] op_sel_hi:[1,0]
	s_waitcnt lgkmcnt(0)
	v_pk_add_f32 v[114:115], v[124:125], v[126:127]
	v_pk_add_f32 v[126:127], v[186:187], v[188:189]
	v_pk_add_f32 v[180:181], v[190:191], v[192:193]
	v_mov_b32_e32 v183, v126
	v_mov_b32_e32 v182, v180
	v_mov_b32_e32 v126, v181
	v_pk_add_f32 v[126:127], v[182:183], v[126:127]
	ds_bpermute_b32 v125, v155, v115
	ds_bpermute_b32 v124, v155, v114
	ds_bpermute_b32 v181, v157, v127
	ds_bpermute_b32 v180, v157, v126
	v_mul_f32_e32 v129, 0x4b800000, v128
	v_cmp_gt_f32_e32 vcc, s73, v128
	s_waitcnt lgkmcnt(2)
	v_pk_add_f32 v[114:115], v[114:115], v[124:125]
	v_mov_b32_e32 v194, v220
	s_waitcnt lgkmcnt(0)
	v_pk_add_f32 v[124:125], v[126:127], v[180:181]
	ds_bpermute_b32 v127, v155, v125
	ds_bpermute_b32 v126, v155, v124
	v_pk_fma_f32 v[114:115], v[114:115], s[24:25], v[130:131] op_sel_hi:[1,0,0]
	v_cndmask_b32_e32 v159, v128, v129, vcc
	v_mul_f32_e32 v128, 0x4b800000, v115
	v_cmp_gt_f32_e64 s[4:5], s73, v115
	v_cmp_gt_f32_e64 s[6:7], s73, v114
	v_mov_b32_e32 v195, v224
	v_cndmask_b32_e64 v161, v115, v128, s[4:5]
	v_mul_f32_e32 v115, 0x4b800000, v114
	v_mov_b32_e32 v224, v221
	v_mov_b32_e32 v196, v222
	v_mov_b32_e32 v197, v226
	v_mov_b32_e32 v226, v223
	v_cndmask_b32_e64 v163, v114, v115, s[6:7]
	s_waitcnt lgkmcnt(0)
	v_pk_add_f32 v[114:115], v[124:125], v[126:127]
	v_pk_add_f32 v[132:133], v[194:195], v[224:225]
	v_pk_add_f32 v[134:135], v[196:197], v[226:227]
	v_mov_b32_e32 v194, v228
	v_mov_b32_e32 v195, v232
	v_mov_b32_e32 v232, v229
	v_mov_b32_e32 v196, v230
	v_mov_b32_e32 v197, v234
	v_mov_b32_e32 v234, v231
	v_pk_fma_f32 v[114:115], v[114:115], s[24:25], v[130:131] op_sel_hi:[1,0,0]
	v_pk_add_f32 v[194:195], v[194:195], v[232:233]
	v_pk_add_f32 v[196:197], v[196:197], v[234:235]
	v_mul_f32_e32 v124, 0x4b800000, v115
	v_cmp_gt_f32_e64 s[8:9], s73, v115
	v_pk_add_f32 v[126:127], v[194:195], v[196:197]
	v_cmp_gt_f32_e64 s[10:11], s73, v114
	v_cndmask_b32_e64 v165, v115, v124, s[8:9]
	v_pk_add_f32 v[124:125], v[132:133], v[134:135]
	v_mov_b32_e32 v128, v126
	v_mov_b32_e32 v129, v124
	v_mov_b32_e32 v124, v127
	v_pk_add_f32 v[124:125], v[128:129], v[124:125]
	ds_bpermute_b32 v127, v157, v125
	ds_bpermute_b32 v126, v157, v124
	v_rsq_f32_e32 v128, v159
	v_mul_f32_e32 v115, 0x4b800000, v114
	v_cndmask_b32_e64 v129, v114, v115, s[10:11]
	v_pk_mul_f32 v[116:117], v[116:117], v[198:199] op_sel_hi:[1,0]
	s_waitcnt lgkmcnt(0)
	v_pk_add_f32 v[114:115], v[124:125], v[126:127]
	ds_bpermute_b32 v125, v155, v115
	ds_bpermute_b32 v124, v155, v114
	v_mul_f32_e32 v126, 0x45800000, v128
	v_rsq_f32_e32 v127, v161
	v_cndmask_b32_e32 v126, v128, v126, vcc
	v_rsq_f32_e32 v128, v163
	s_waitcnt lgkmcnt(0)
; DI unsigned pack2(float lo, float hi) { f32x2 v = {lo, hi}; bf16v2 r = __builtin_convertvector(v, bf16v2); return __builtin_bit_cast(unsigned, r); }
;   DI void operator()(const f32x4 (&acc)[2][2][4][2], const Unit& u, int wr, int wc, int fr, int fq) const {
;     ...
;     for (int ai = 0; ai < 2; ++ai)
; #pragma unroll
;       for (int m = 0; m < 4; ++m) {
;         const int row = row0 + ai * HALF + m * 16;
;         const float rs = rsv[ai][m];
;         bf16_t* rowp = O + (size_t)row * ldc + col0;
; #pragma unroll
;         for (int bj = 0; bj < 2; ++bj) {
;           const f32x4 v0 = acc[ai][bj][m][0] * rs, v1 = acc[ai][bj][m][1] * rs;
;           u32x4 w; w.x = pack2(v0[0], v0[1]); w.y = pack2(v0[2], v0[3]); w.z = pack2(v1[0], v1[1]); w.w = pack2(v1[2], v1[3]);
;           *(u32x4*)(rowp + bj * HALF) = w;
;         }
;       }
	v_pk_add_f32 v[114:115], v[114:115], v[124:125]
	v_mul_f32_e32 v124, 0x45800000, v127
	v_cndmask_b32_e64 v124, v127, v124, s[4:5]
	v_mul_f32_e32 v127, 0x45800000, v128
	v_pk_fma_f32 v[114:115], v[114:115], s[24:25], v[130:131] op_sel_hi:[1,0,0]
	v_rsq_f32_e32 v125, v165
	v_cndmask_b32_e64 v128, v128, v127, s[6:7]
	v_rsq_f32_e32 v127, v129
	v_mul_f32_e32 v129, 0x4b800000, v115
	v_cmp_gt_f32_e32 vcc, s73, v115
	v_cmp_gt_f32_e64 s[4:5], s73, v114
	v_pk_mul_f32 v[118:119], v[118:119], v[198:199] op_sel_hi:[1,0]
	v_cndmask_b32_e32 v129, v115, v129, vcc
	v_mul_f32_e32 v115, 0x4b800000, v114
	v_cndmask_b32_e64 v131, v114, v115, s[4:5]
	v_cvt_pk_bf16_f32 v114, v116, v117
	v_rsq_f32_e32 v117, v129
	v_cvt_pk_bf16_f32 v115, v118, v119
	v_rsq_f32_e32 v119, v131
	v_mul_f32_e32 v116, 0x45800000, v125
	v_pk_mul_f32 v[112:113], v[112:113], v[198:199] op_sel_hi:[1,0]
	v_cndmask_b32_e64 v118, v125, v116, s[8:9]
	v_mul_f32_e32 v116, 0x45800000, v127
	v_cndmask_b32_e64 v130, v127, v116, s[10:11]
	v_cvt_pk_bf16_f32 v116, v112, v113
	v_mul_f32_e32 v112, 0x45800000, v117
	v_cndmask_b32_e32 v132, v117, v112, vcc
	v_mul_f32_e32 v112, 0x45800000, v119
	v_cvt_pk_bf16_f32 v117, v178, v179
	v_cndmask_b32_e64 v112, v119, v112, s[4:5]
	global_store_dwordx4 v[168:169], v[114:117], off offset:256
	v_pk_mul_f32 v[110:111], v[110:111], v[126:127] op_sel_hi:[1,0]
	v_pk_mul_f32 v[108:109], v[108:109], v[126:127] op_sel_hi:[1,0]
	v_mad_i64_i32 v[114:115], s[4:5], v154, s76, v[120:121]
	v_pk_mul_f32 v[116:117], v[106:107], v[126:127] op_sel_hi:[1,0]
	v_pk_mul_f32 v[106:107], v[104:105], v[126:127] op_sel_hi:[1,0]
	v_lshl_add_u64 v[114:115], v[114:115], 0, v[122:123]
	v_cvt_pk_bf16_f32 v104, v108, v109
	v_cvt_pk_bf16_f32 v105, v110, v111
	v_cvt_pk_bf16_f32 v106, v106, v107
	v_cvt_pk_bf16_f32 v107, v116, v117
	global_store_dwordx4 v[114:115], v[104:107], off
	v_pk_mul_f32 v[98:99], v[98:99], v[126:127] op_sel_hi:[1,0]
	v_pk_mul_f32 v[96:97], v[96:97], v[126:127] op_sel_hi:[1,0]
	v_pk_mul_f32 v[104:105], v[90:91], v[126:127] op_sel_hi:[1,0]
	v_pk_mul_f32 v[90:91], v[88:89], v[126:127] op_sel_hi:[1,0]
	v_cvt_pk_bf16_f32 v88, v96, v97
	v_cvt_pk_bf16_f32 v89, v98, v99
	v_cvt_pk_bf16_f32 v90, v90, v91
	v_cvt_pk_bf16_f32 v91, v104, v105
	global_store_dwordx4 v[114:115], v[88:91], off offset:256
	v_pk_mul_f32 v[94:95], v[94:95], v[124:125] op_sel_hi:[1,0]
	v_pk_mul_f32 v[92:93], v[92:93], v[124:125] op_sel_hi:[1,0]
	v_mad_i64_i32 v[88:89], s[4:5], v160, s76, v[120:121]
	v_lshl_add_u64 v[96:97], v[88:89], 0, v[122:123]
	v_pk_mul_f32 v[90:91], v[102:103], v[124:125] op_sel_hi:[1,0]
	v_pk_mul_f32 v[88:89], v[100:101], v[124:125] op_sel_hi:[1,0]
	v_pk_mul_f32 v[82:83], v[82:83], v[124:125] op_sel_hi:[1,0]
	v_cvt_pk_bf16_f32 v88, v88, v89
	v_cvt_pk_bf16_f32 v89, v90, v91
	v_cvt_pk_bf16_f32 v90, v92, v93
	v_cvt_pk_bf16_f32 v91, v94, v95
	global_store_dwordx4 v[96:97], v[88:91], off
	v_pk_mul_f32 v[80:81], v[80:81], v[124:125] op_sel_hi:[1,0]
	v_pk_mul_f32 v[78:79], v[78:79], v[128:129] op_sel_hi:[1,0]
	v_pk_mul_f32 v[88:89], v[74:75], v[124:125] op_sel_hi:[1,0]
	v_pk_mul_f32 v[74:75], v[72:73], v[124:125] op_sel_hi:[1,0]
	v_cvt_pk_bf16_f32 v72, v80, v81
	v_cvt_pk_bf16_f32 v73, v82, v83
	v_cvt_pk_bf16_f32 v74, v74, v75
	v_cvt_pk_bf16_f32 v75, v88, v89
	global_store_dwordx4 v[96:97], v[72:75], off offset:256
	v_pk_mul_f32 v[76:77], v[76:77], v[128:129] op_sel_hi:[1,0]
	v_pk_mul_f32 v[70:71], v[70:71], v[128:129] op_sel_hi:[1,0]
	v_mad_i64_i32 v[72:73], s[4:5], v156, s76, v[120:121]
	v_lshl_add_u64 v[80:81], v[72:73], 0, v[122:123]
	v_pk_mul_f32 v[74:75], v[86:87], v[128:129] op_sel_hi:[1,0]
	v_pk_mul_f32 v[72:73], v[84:85], v[128:129] op_sel_hi:[1,0]
	v_pk_mul_f32 v[68:69], v[68:69], v[128:129] op_sel_hi:[1,0]
	v_cvt_pk_bf16_f32 v72, v72, v73
	v_cvt_pk_bf16_f32 v73, v74, v75
	v_cvt_pk_bf16_f32 v74, v76, v77
	v_cvt_pk_bf16_f32 v75, v78, v79
	global_store_dwordx4 v[80:81], v[72:75], off
	v_pk_mul_f32 v[62:63], v[62:63], v[118:119] op_sel_hi:[1,0]
	v_pk_mul_f32 v[60:61], v[60:61], v[118:119] op_sel_hi:[1,0]
	v_pk_mul_f32 v[72:73], v[66:67], v[128:129] op_sel_hi:[1,0]
	v_pk_mul_f32 v[66:67], v[64:65], v[128:129] op_sel_hi:[1,0]
; DI unsigned pack2(float lo, float hi) { f32x2 v = {lo, hi}; bf16v2 r = __builtin_convertvector(v, bf16v2); return __builtin_bit_cast(unsigned, r); }
; #define PG8_WAIT_V(n) asm volatile("s_waitcnt vmcnt(" #n ")" ::: "memory")
; #define PG8_BAR __builtin_amdgcn_s_barrier()
;   DI void operator()(const f32x4 (&acc)[2][2][4][2], const Unit& u, int wr, int wc, int fr, int fq) const {
;     ...
;     for (int ai = 0; ai < 2; ++ai)
; #pragma unroll
;       for (int m = 0; m < 4; ++m) {
;         const int row = row0 + ai * HALF + m * 16;
;         const float rs = rsv[ai][m];
;         bf16_t* rowp = O + (size_t)row * ldc + col0;
; #pragma unroll
;         for (int bj = 0; bj < 2; ++bj) {
;           const f32x4 v0 = acc[ai][bj][m][0] * rs, v1 = acc[ai][bj][m][1] * rs;
;           u32x4 w; w.x = pack2(v0[0], v0[1]); w.y = pack2(v0[2], v0[3]); w.z = pack2(v1[0], v1[1]); w.w = pack2(v1[2], v1[3]);
;           *(u32x4*)(rowp + bj * HALF) = w;
;         }
;       }
; template <class Epi, class Sched = StaticOrder>
; DI void gemm_phase(LAS unsigned char* lds, const Gemm g, const Sched& S, const Epi& E) {
;     ...
;     cur = nxt; cA = nA; cB = nB; ++ui;
;   }
;   PG8_WAIT_V(0);
;   if (wr == 0) PG8_BAR;
	v_cvt_pk_bf16_f32 v64, v68, v69
	v_cvt_pk_bf16_f32 v65, v70, v71
	v_cvt_pk_bf16_f32 v66, v66, v67
	v_cvt_pk_bf16_f32 v67, v72, v73
	global_store_dwordx4 v[80:81], v[64:67], off offset:256
	v_pk_mul_f32 v[50:51], v[50:51], v[118:119] op_sel_hi:[1,0]
	v_pk_mul_f32 v[48:49], v[48:49], v[118:119] op_sel_hi:[1,0]
	v_mad_i64_i32 v[64:65], s[4:5], v164, s76, v[120:121]
	v_pk_mul_f32 v[66:67], v[58:59], v[118:119] op_sel_hi:[1,0]
	v_pk_mul_f32 v[58:59], v[56:57], v[118:119] op_sel_hi:[1,0]
	v_lshl_add_u64 v[64:65], v[64:65], 0, v[122:123]
	v_cvt_pk_bf16_f32 v56, v60, v61
	v_cvt_pk_bf16_f32 v57, v62, v63
	v_cvt_pk_bf16_f32 v58, v58, v59
	v_cvt_pk_bf16_f32 v59, v66, v67
	global_store_dwordx4 v[64:65], v[56:59], off
	v_pk_mul_f32 v[46:47], v[46:47], v[130:131] op_sel_hi:[1,0]
	v_pk_mul_f32 v[44:45], v[44:45], v[130:131] op_sel_hi:[1,0]
	v_pk_mul_f32 v[56:57], v[42:43], v[118:119] op_sel_hi:[1,0]
	v_pk_mul_f32 v[42:43], v[40:41], v[118:119] op_sel_hi:[1,0]
	v_cvt_pk_bf16_f32 v40, v48, v49
	v_cvt_pk_bf16_f32 v41, v50, v51
	v_cvt_pk_bf16_f32 v42, v42, v43
	v_cvt_pk_bf16_f32 v43, v56, v57
	global_store_dwordx4 v[64:65], v[40:43], off offset:256
	v_pk_mul_f32 v[34:35], v[34:35], v[130:131] op_sel_hi:[1,0]
	v_pk_mul_f32 v[32:33], v[32:33], v[130:131] op_sel_hi:[1,0]
	v_mad_i64_i32 v[40:41], s[4:5], v158, s76, v[120:121]
	v_lshl_add_u64 v[48:49], v[40:41], 0, v[122:123]
	v_pk_mul_f32 v[42:43], v[54:55], v[130:131] op_sel_hi:[1,0]
	v_pk_mul_f32 v[40:41], v[52:53], v[130:131] op_sel_hi:[1,0]
	v_pk_mul_f32 v[30:31], v[30:31], v[132:133] op_sel_hi:[1,0]
	v_cvt_pk_bf16_f32 v40, v40, v41
	v_cvt_pk_bf16_f32 v41, v42, v43
	v_cvt_pk_bf16_f32 v42, v44, v45
	v_cvt_pk_bf16_f32 v43, v46, v47
	global_store_dwordx4 v[48:49], v[40:43], off
	v_pk_mul_f32 v[28:29], v[28:29], v[132:133] op_sel_hi:[1,0]
	v_pk_mul_f32 v[18:19], v[18:19], v[132:133] op_sel_hi:[1,0]
	v_pk_mul_f32 v[40:41], v[26:27], v[130:131] op_sel_hi:[1,0]
	v_pk_mul_f32 v[26:27], v[24:25], v[130:131] op_sel_hi:[1,0]
	v_cvt_pk_bf16_f32 v24, v32, v33
	v_cvt_pk_bf16_f32 v25, v34, v35
	v_cvt_pk_bf16_f32 v26, v26, v27
	v_cvt_pk_bf16_f32 v27, v40, v41
	global_store_dwordx4 v[48:49], v[24:27], off offset:256
	v_pk_mul_f32 v[16:17], v[16:17], v[132:133] op_sel_hi:[1,0]
	v_pk_mul_f32 v[14:15], v[14:15], v[112:113] op_sel_hi:[1,0]
	v_mad_i64_i32 v[24:25], s[4:5], v166, s76, v[120:121]
	v_lshl_add_u64 v[32:33], v[24:25], 0, v[122:123]
	v_pk_mul_f32 v[26:27], v[38:39], v[132:133] op_sel_hi:[1,0]
	v_pk_mul_f32 v[24:25], v[36:37], v[132:133] op_sel_hi:[1,0]
	v_pk_mul_f32 v[12:13], v[12:13], v[112:113] op_sel_hi:[1,0]
	v_cvt_pk_bf16_f32 v24, v24, v25
	v_cvt_pk_bf16_f32 v25, v26, v27
	v_cvt_pk_bf16_f32 v26, v28, v29
	v_cvt_pk_bf16_f32 v27, v30, v31
	global_store_dwordx4 v[32:33], v[24:27], off
	v_pk_mul_f32 v[6:7], v[6:7], v[112:113] op_sel_hi:[1,0]
	v_pk_mul_f32 v[4:5], v[4:5], v[112:113] op_sel_hi:[1,0]
	v_pk_mul_f32 v[24:25], v[10:11], v[132:133] op_sel_hi:[1,0]
	v_pk_mul_f32 v[10:11], v[8:9], v[132:133] op_sel_hi:[1,0]
	v_cvt_pk_bf16_f32 v8, v16, v17
	v_cvt_pk_bf16_f32 v9, v18, v19
	v_cvt_pk_bf16_f32 v10, v10, v11
	v_cvt_pk_bf16_f32 v11, v24, v25
	global_store_dwordx4 v[32:33], v[8:11], off offset:256
	s_and_b64 vcc, exec, s[0:1]
	s_mov_b64 s[8:9], s[36:37]
	v_mad_i64_i32 v[8:9], s[4:5], v162, s76, v[120:121]
	v_lshl_add_u64 v[16:17], v[8:9], 0, v[122:123]
	v_pk_mul_f32 v[10:11], v[22:23], v[112:113] op_sel_hi:[1,0]
	v_pk_mul_f32 v[8:9], v[20:21], v[112:113] op_sel_hi:[1,0]
	s_mov_b32 s5, s28
	v_cvt_pk_bf16_f32 v8, v8, v9
	v_cvt_pk_bf16_f32 v9, v10, v11
	v_cvt_pk_bf16_f32 v10, v12, v13
	v_cvt_pk_bf16_f32 v11, v14, v15
	global_store_dwordx4 v[16:17], v[8:11], off
	s_mov_b32 s4, s30
	s_mov_b64 s[6:7], s[34:35]
	v_pk_mul_f32 v[8:9], v[2:3], v[112:113] op_sel_hi:[1,0]
	v_pk_mul_f32 v[2:3], v[0:1], v[112:113] op_sel_hi:[1,0]
	v_cvt_pk_bf16_f32 v0, v4, v5
	v_cvt_pk_bf16_f32 v1, v6, v7
	v_cvt_pk_bf16_f32 v2, v2, v3
	v_cvt_pk_bf16_f32 v3, v8, v9
	global_store_dwordx4 v[16:17], v[0:3], off offset:256
	s_cbranch_vccz .LBB0_343
	s_waitcnt vmcnt(0)
	s_cmpk_gt_u32 s27, 0xff
	s_cbranch_scc1 .LBB0_350
	s_barrier

; #define PG8_STAGE(bufoff, gbase, voff) do { _Pragma("unroll") for (int _i = 0; _i < 2; ++_i) \
;     __builtin_amdgcn_global_load_lds((const unsigned*)((const char*)(gbase) + (voff)[_i]), (LAS unsigned*)(lds + (bufoff) + ldsw + _i * 8192), 16, 0, 0); } while (0)
; #define PG8_LDA(dst, b, h) do { _Pragma("unroll") for (int m = 0; m < 4; ++m) _Pragma("unroll") for (int k = 0; k < 2; ++k) dst[m][k] = *(const LAS bf16x8*)(lds + PG8_SA(b, h) + aoff + m * 2048 + k * 1024); } while (0)
; #define PG8_LDB(dst, b, h) do { _Pragma("unroll") for (int n = 0; n < 2; ++n) _Pragma("unroll") for (int k = 0; k < 2; ++k) dst[n][k] = *(const LAS bf16x8*)(lds + PG8_SB(b, h) + boff + n * 2048 + k * 1024); } while (0)
; #define PG8_MMA(ai, bj, At, Bt) do { __builtin_amdgcn_s_setprio(1); _Pragma("unroll") for (int m = 0; m < 4; ++m) _Pragma("unroll") for (int n = 0; n < 2; ++n) _Pragma("unroll") for (int k = 0; k < 2; ++k) \
;     acc[ai][bj][m][n] = __builtin_amdgcn_mfma_f32_16x16x32_bf16(Bt[n][k], At[m][k], acc[ai][bj][m][n], 0, 0, 0); __builtin_amdgcn_s_setprio(0); } while (0)
; #define PG8_WAIT_V(n) asm volatile("s_waitcnt vmcnt(" #n ")" ::: "memory")
; #define PG8_WAIT_L(n) asm volatile("s_waitcnt lgkmcnt(" #n ")" ::: "memory")
; template <class Epi, class Sched = StaticOrder>
; DI void gemm_phase(LAS unsigned char* lds, const Gemm g, const Sched& S, const Epi& E) {
;     ...
;     for (int t = 0; t < nt; t += 2) {
;       const bool last = (t == nt - 2);
;       const char* a1 = cA + (size_t)(t + 1) * kstep;
;       const char* a2 = last ? nA : cA + (size_t)(t + 2) * kstep; const char* b2 = last ? nB : cB + (size_t)(t + 2) * kstep;
;       const char* a3 = a2 + kstep; const char* b3 = b2 + kstep;
;       PG8_LDB(B0, 0, 0); PG8_SCHED; PG8_LDA(At, 0, 0); PG8_STAGE(PG8_SA(1, 1), a1 + hstep, voffA);
;       PG8_WAIT_L(8); PG8_BAR; PG8_WAIT_L(0); PG8_MMA(0, 0, At, B0); PG8_BAR; PG8_SCHED;
;       PG8_LDB(B1, 0, 1); PG8_STAGE(PG8_SB(0, 0), b2, voffB);
;       PG8_BAR; PG8_WAIT_L(0); PG8_MMA(0, 1, At, B1); PG8_BAR;
;       PG8_LDA(At, 0, 1); PG8_STAGE(PG8_SA(0, 0), a2, voffA);
;       PG8_BAR; PG8_WAIT_L(0); PG8_MMA(1, 0, At, B0); PG8_BAR; PG8_SCHED;
;       PG8_STAGE(PG8_SB(0, 1), b2 + hstep, voffB);
;       PG8_WAIT_V(6); PG8_BAR; PG8_MMA(1, 1, At, B1); PG8_BAR;
;       PG8_LDB(B0, 1, 0); PG8_SCHED; PG8_LDA(At, 1, 0); PG8_STAGE(PG8_SA(0, 1), a2 + hstep, voffA);
.LBB0_728:
	s_add_u32 s24, s22, 0xfff80080
	s_addc_u32 s25, s23, -1
	s_cmp_eq_u32 s53, 28
	s_cselect_b32 s27, s17, s25
	s_cselect_b32 s26, s43, s24
	s_cselect_b32 s25, s15, s52
	s_cselect_b32 s24, s44, s45
	s_add_i32 m0, s37, 0xc000
	ds_read_b128 v[144:147], v208
	ds_read_b128 v[152:155], v208 offset:2048
	ds_read_b128 v[160:163], v208 offset:4096
	ds_read_b128 v[168:171], v208 offset:6144
	ds_read_b128 v[148:151], v208 offset:1024
	ds_read_b128 v[156:159], v208 offset:3072
	ds_read_b128 v[164:167], v208 offset:5120
	ds_read_b128 v[172:175], v208 offset:7168
	global_load_lds_dwordx4 v184, s[22:23]
	s_add_i32 m0, s37, 0xe000
	s_nop 0
	global_load_lds_dwordx4 v186, s[22:23]
	s_waitcnt lgkmcnt(8)
	s_setprio 1
	s_barrier
	s_waitcnt lgkmcnt(4)
	v_mfma_f32_16x16x32_bf16 v[124:127], v[128:131], v[144:147], v[124:127]
	v_mfma_f32_16x16x32_bf16 v[120:123], v[136:139], v[144:147], v[120:123]
	v_mfma_f32_16x16x32_bf16 v[108:111], v[128:131], v[152:155], v[108:111]
	v_mfma_f32_16x16x32_bf16 v[104:107], v[136:139], v[152:155], v[104:107]
	v_mfma_f32_16x16x32_bf16 v[92:95], v[128:131], v[160:163], v[92:95]
	v_mfma_f32_16x16x32_bf16 v[88:91], v[136:139], v[160:163], v[88:91]
	v_mfma_f32_16x16x32_bf16 v[76:79], v[128:131], v[168:171], v[76:79]
	v_mfma_f32_16x16x32_bf16 v[72:75], v[136:139], v[168:171], v[72:75]
	s_waitcnt lgkmcnt(0)
	v_mfma_f32_16x16x32_bf16 v[124:127], v[132:135], v[148:151], v[124:127]
	v_mfma_f32_16x16x32_bf16 v[120:123], v[140:143], v[148:151], v[120:123]
	v_mfma_f32_16x16x32_bf16 v[108:111], v[132:135], v[156:159], v[108:111]
	v_mfma_f32_16x16x32_bf16 v[104:107], v[140:143], v[156:159], v[104:107]
	v_mfma_f32_16x16x32_bf16 v[92:95], v[132:135], v[164:167], v[92:95]
	v_mfma_f32_16x16x32_bf16 v[88:91], v[140:143], v[164:167], v[88:91]
	v_mfma_f32_16x16x32_bf16 v[76:79], v[132:135], v[172:175], v[76:79]
	v_mfma_f32_16x16x32_bf16 v[72:75], v[140:143], v[172:175], v[72:75]
	s_barrier
	s_setprio 0
	s_add_i32 s54, s50, s35
	s_add_u32 s98, s24, 0x80
	s_addc_u32 s99, s25, 0
	s_add_u32 s100, s26, 0x80
	s_addc_u32 s101, s27, 0
	s_mov_b32 m0, s54
	ds_read_b128 v[192:195], v209
	ds_read_b128 v[196:199], v209 offset:1024
	ds_read_b128 v[200:203], v209 offset:2048
	ds_read_b128 v[212:215], v209 offset:3072
	global_load_lds_dwordx4 v180, s[24:25]
	s_add_i32 m0, s54, 0x2000
	s_nop 0
	global_load_lds_dwordx4 v176, s[24:25]
	s_setprio 1
	s_barrier
	s_waitcnt lgkmcnt(0)
	v_mfma_f32_16x16x32_bf16 v[116:119], v[192:195], v[144:147], v[116:119]
	v_mfma_f32_16x16x32_bf16 v[112:115], v[200:203], v[144:147], v[112:115]
	v_mfma_f32_16x16x32_bf16 v[100:103], v[192:195], v[152:155], v[100:103]
	v_mfma_f32_16x16x32_bf16 v[96:99], v[200:203], v[152:155], v[96:99]
	v_mfma_f32_16x16x32_bf16 v[84:87], v[192:195], v[160:163], v[84:87]
	v_mfma_f32_16x16x32_bf16 v[80:83], v[200:203], v[160:163], v[80:83]
	v_mfma_f32_16x16x32_bf16 v[68:71], v[192:195], v[168:171], v[68:71]
	v_mfma_f32_16x16x32_bf16 v[64:67], v[200:203], v[168:171], v[64:67]
	v_mfma_f32_16x16x32_bf16 v[116:119], v[196:199], v[148:151], v[116:119]
	v_mfma_f32_16x16x32_bf16 v[112:115], v[212:215], v[148:151], v[112:115]
	v_mfma_f32_16x16x32_bf16 v[100:103], v[196:199], v[156:159], v[100:103]
	v_mfma_f32_16x16x32_bf16 v[96:99], v[212:215], v[156:159], v[96:99]
	v_mfma_f32_16x16x32_bf16 v[84:87], v[196:199], v[164:167], v[84:87]
	v_mfma_f32_16x16x32_bf16 v[80:83], v[212:215], v[164:167], v[80:83]
	v_mfma_f32_16x16x32_bf16 v[68:71], v[196:199], v[172:175], v[68:71]
	v_mfma_f32_16x16x32_bf16 v[64:67], v[212:215], v[172:175], v[64:67]
	s_barrier
	s_setprio 0
	s_mov_b32 m0, s37
	ds_read_b128 v[144:147], v208 offset:16384
	ds_read_b128 v[152:155], v208 offset:18432
	ds_read_b128 v[160:163], v208 offset:20480
	ds_read_b128 v[168:171], v208 offset:22528
	ds_read_b128 v[148:151], v208 offset:17408
	ds_read_b128 v[156:159], v208 offset:19456
	ds_read_b128 v[164:167], v208 offset:21504
	ds_read_b128 v[172:175], v208 offset:23552
	global_load_lds_dwordx4 v182, s[26:27]
	s_mov_b32 m0, s38
	s_nop 0
	global_load_lds_dwordx4 v178, s[26:27]
	s_waitcnt vmcnt(10)
	s_setprio 1
	s_barrier
	s_waitcnt lgkmcnt(4)
	v_mfma_f32_16x16x32_bf16 v[60:63], v[128:131], v[144:147], v[60:63]
	v_mfma_f32_16x16x32_bf16 v[56:59], v[136:139], v[144:147], v[56:59]
	v_mfma_f32_16x16x32_bf16 v[44:47], v[128:131], v[152:155], v[44:47]
	v_mfma_f32_16x16x32_bf16 v[40:43], v[136:139], v[152:155], v[40:43]
	v_mfma_f32_16x16x32_bf16 v[28:31], v[128:131], v[160:163], v[28:31]
	v_mfma_f32_16x16x32_bf16 v[24:27], v[136:139], v[160:163], v[24:27]
	v_mfma_f32_16x16x32_bf16 v[12:15], v[128:131], v[168:171], v[12:15]
	v_mfma_f32_16x16x32_bf16 v[8:11], v[136:139], v[168:171], v[8:11]
	s_waitcnt lgkmcnt(0)
	v_mfma_f32_16x16x32_bf16 v[60:63], v[132:135], v[148:151], v[60:63]
	v_mfma_f32_16x16x32_bf16 v[56:59], v[140:143], v[148:151], v[56:59]
	v_mfma_f32_16x16x32_bf16 v[44:47], v[132:135], v[156:159], v[44:47]
	v_mfma_f32_16x16x32_bf16 v[40:43], v[140:143], v[156:159], v[40:43]
	v_mfma_f32_16x16x32_bf16 v[28:31], v[132:135], v[164:167], v[28:31]
	v_mfma_f32_16x16x32_bf16 v[24:27], v[140:143], v[164:167], v[24:27]
	v_mfma_f32_16x16x32_bf16 v[12:15], v[132:135], v[172:175], v[12:15]
	v_mfma_f32_16x16x32_bf16 v[8:11], v[140:143], v[172:175], v[8:11]
	s_barrier
	s_setprio 0
	s_add_u32 s54, s24, 0x80000
	s_addc_u32 s55, s25, 0
	s_add_i32 s57, s51, s35
	s_mov_b32 m0, s57
	s_nop 0
	global_load_lds_dwordx4 v180, s[54:55]
	s_add_i32 m0, s57, 0x2000
	s_nop 0
	global_load_lds_dwordx4 v176, s[54:55]
	s_add_i32 s54, 0, 0x18000
	v_add_u32_e32 v140, s54, v205
	ds_read_b128 v[128:131], v140
	ds_read_b128 v[132:135], v140 offset:1024
	ds_read_b128 v[136:139], v140 offset:2048
	ds_read_b128 v[140:143], v140 offset:3072
	s_waitcnt vmcnt(6)
	s_setprio 1
	s_barrier
; #define PG8_STAGE(bufoff, gbase, voff) do { _Pragma("unroll") for (int _i = 0; _i < 2; ++_i) \
;     __builtin_amdgcn_global_load_lds((const unsigned*)((const char*)(gbase) + (voff)[_i]), (LAS unsigned*)(lds + (bufoff) + ldsw + _i * 8192), 16, 0, 0); } while (0)
; #define PG8_LDA(dst, b, h) do { _Pragma("unroll") for (int m = 0; m < 4; ++m) _Pragma("unroll") for (int k = 0; k < 2; ++k) dst[m][k] = *(const LAS bf16x8*)(lds + PG8_SA(b, h) + aoff + m * 2048 + k * 1024); } while (0)
; #define PG8_LDB(dst, b, h) do { _Pragma("unroll") for (int n = 0; n < 2; ++n) _Pragma("unroll") for (int k = 0; k < 2; ++k) dst[n][k] = *(const LAS bf16x8*)(lds + PG8_SB(b, h) + boff + n * 2048 + k * 1024); } while (0)
; #define PG8_MMA(ai, bj, At, Bt) do { __builtin_amdgcn_s_setprio(1); _Pragma("unroll") for (int m = 0; m < 4; ++m) _Pragma("unroll") for (int n = 0; n < 2; ++n) _Pragma("unroll") for (int k = 0; k < 2; ++k) \
;     acc[ai][bj][m][n] = __builtin_amdgcn_mfma_f32_16x16x32_bf16(Bt[n][k], At[m][k], acc[ai][bj][m][n], 0, 0, 0); __builtin_amdgcn_s_setprio(0); } while (0)
; #define PG8_WAIT_V(n) asm volatile("s_waitcnt vmcnt(" #n ")" ::: "memory")
; #define PG8_WAIT_L(n) asm volatile("s_waitcnt lgkmcnt(" #n ")" ::: "memory")
; #define PG8_BAR __builtin_amdgcn_s_barrier()
; #define PG8_SCHED __builtin_amdgcn_sched_barrier(0)
; template <class Epi, class Sched = StaticOrder>
; DI void gemm_phase(LAS unsigned char* lds, const Gemm g, const Sched& S, const Epi& E) {
;     ...
;       PG8_WAIT_V(6); PG8_BAR; PG8_MMA(1, 1, At, B1); PG8_BAR;
;       PG8_LDB(B0, 1, 0); PG8_SCHED; PG8_LDA(At, 1, 0); PG8_STAGE(PG8_SA(0, 1), a2 + hstep, voffA);
;       PG8_WAIT_L(8); PG8_BAR; PG8_WAIT_L(0); PG8_MMA(0, 0, At, B0); PG8_BAR; PG8_SCHED;
;       PG8_LDB(B1, 1, 1); PG8_STAGE(PG8_SB(1, 0), b3, voffB);
;       PG8_BAR; PG8_WAIT_L(0); PG8_MMA(0, 1, At, B1); PG8_BAR;
;       PG8_LDA(At, 1, 1); PG8_STAGE(PG8_SA(1, 0), a3, voffA);
;       PG8_BAR; PG8_WAIT_L(0); PG8_MMA(1, 0, At, B0); PG8_BAR; PG8_SCHED;
	v_mfma_f32_16x16x32_bf16 v[52:55], v[192:195], v[144:147], v[52:55]
	v_mfma_f32_16x16x32_bf16 v[48:51], v[200:203], v[144:147], v[48:51]
	v_mfma_f32_16x16x32_bf16 v[36:39], v[192:195], v[152:155], v[36:39]
	v_mfma_f32_16x16x32_bf16 v[32:35], v[200:203], v[152:155], v[32:35]
	v_mfma_f32_16x16x32_bf16 v[20:23], v[192:195], v[160:163], v[20:23]
	v_mfma_f32_16x16x32_bf16 v[16:19], v[200:203], v[160:163], v[16:19]
	v_mfma_f32_16x16x32_bf16 v[4:7], v[192:195], v[168:171], v[4:7]
	v_mfma_f32_16x16x32_bf16 v[0:3], v[200:203], v[168:171], v[0:3]
	v_mfma_f32_16x16x32_bf16 v[52:55], v[196:199], v[148:151], v[52:55]
	v_mfma_f32_16x16x32_bf16 v[48:51], v[212:215], v[148:151], v[48:51]
	v_mfma_f32_16x16x32_bf16 v[36:39], v[196:199], v[156:159], v[36:39]
	v_mfma_f32_16x16x32_bf16 v[32:35], v[212:215], v[156:159], v[32:35]
	v_mfma_f32_16x16x32_bf16 v[20:23], v[196:199], v[164:167], v[20:23]
	v_mfma_f32_16x16x32_bf16 v[16:19], v[212:215], v[164:167], v[16:19]
	v_mfma_f32_16x16x32_bf16 v[4:7], v[196:199], v[172:175], v[4:7]
	v_mfma_f32_16x16x32_bf16 v[0:3], v[212:215], v[172:175], v[0:3]
	s_barrier
	s_setprio 0
	s_add_u32 s26, s26, 0x80000
	s_addc_u32 s27, s27, 0
	s_mov_b32 m0, s39
	ds_read_b128 v[144:147], v208 offset:32768
	ds_read_b128 v[152:155], v208 offset:34816
	ds_read_b128 v[160:163], v208 offset:36864
	ds_read_b128 v[168:171], v208 offset:38912
	ds_read_b128 v[148:151], v208 offset:33792
	ds_read_b128 v[156:159], v208 offset:35840
	ds_read_b128 v[164:167], v208 offset:37888
	ds_read_b128 v[172:175], v208 offset:39936
	global_load_lds_dwordx4 v182, s[26:27]
	s_mov_b32 m0, s40
	s_nop 0
	global_load_lds_dwordx4 v178, s[26:27]
	s_waitcnt lgkmcnt(8)
	s_setprio 1
	s_barrier
	s_waitcnt lgkmcnt(4)
	v_mfma_f32_16x16x32_bf16 v[124:127], v[128:131], v[144:147], v[124:127]
	v_mfma_f32_16x16x32_bf16 v[120:123], v[136:139], v[144:147], v[120:123]
	v_mfma_f32_16x16x32_bf16 v[108:111], v[128:131], v[152:155], v[108:111]
	v_mfma_f32_16x16x32_bf16 v[104:107], v[136:139], v[152:155], v[104:107]
	v_mfma_f32_16x16x32_bf16 v[92:95], v[128:131], v[160:163], v[92:95]
	v_mfma_f32_16x16x32_bf16 v[88:91], v[136:139], v[160:163], v[88:91]
	v_mfma_f32_16x16x32_bf16 v[76:79], v[128:131], v[168:171], v[76:79]
	v_mfma_f32_16x16x32_bf16 v[72:75], v[136:139], v[168:171], v[72:75]
	s_waitcnt lgkmcnt(0)
	v_mfma_f32_16x16x32_bf16 v[124:127], v[132:135], v[148:151], v[124:127]
	v_mfma_f32_16x16x32_bf16 v[120:123], v[140:143], v[148:151], v[120:123]
	v_mfma_f32_16x16x32_bf16 v[108:111], v[132:135], v[156:159], v[108:111]
	v_mfma_f32_16x16x32_bf16 v[104:107], v[140:143], v[156:159], v[104:107]
	v_mfma_f32_16x16x32_bf16 v[92:95], v[132:135], v[164:167], v[92:95]
	v_mfma_f32_16x16x32_bf16 v[88:91], v[140:143], v[164:167], v[88:91]
	v_mfma_f32_16x16x32_bf16 v[76:79], v[132:135], v[172:175], v[76:79]
	v_mfma_f32_16x16x32_bf16 v[72:75], v[140:143], v[172:175], v[72:75]
	s_barrier
	s_setprio 0
	s_add_i32 s26, 0, 0x1c000
	s_add_i32 s27, s54, s35
	v_add_u32_e32 v212, s26, v205
	s_mov_b32 m0, s27
	ds_read_b128 v[192:195], v212
	ds_read_b128 v[196:199], v212 offset:1024
	ds_read_b128 v[200:203], v212 offset:2048
	ds_read_b128 v[212:215], v212 offset:3072
	global_load_lds_dwordx4 v180, s[98:99]
	s_add_i32 m0, s27, 0x2000
	s_nop 0
	global_load_lds_dwordx4 v176, s[98:99]
	s_setprio 1
	s_barrier
	s_waitcnt lgkmcnt(0)
	v_mfma_f32_16x16x32_bf16 v[116:119], v[192:195], v[144:147], v[116:119]
	v_mfma_f32_16x16x32_bf16 v[112:115], v[200:203], v[144:147], v[112:115]
	v_mfma_f32_16x16x32_bf16 v[100:103], v[192:195], v[152:155], v[100:103]
	v_mfma_f32_16x16x32_bf16 v[96:99], v[200:203], v[152:155], v[96:99]
	v_mfma_f32_16x16x32_bf16 v[84:87], v[192:195], v[160:163], v[84:87]
	v_mfma_f32_16x16x32_bf16 v[80:83], v[200:203], v[160:163], v[80:83]
	v_mfma_f32_16x16x32_bf16 v[68:71], v[192:195], v[168:171], v[68:71]
	v_mfma_f32_16x16x32_bf16 v[64:67], v[200:203], v[168:171], v[64:67]
	v_mfma_f32_16x16x32_bf16 v[116:119], v[196:199], v[148:151], v[116:119]
	v_mfma_f32_16x16x32_bf16 v[112:115], v[212:215], v[148:151], v[112:115]
	v_mfma_f32_16x16x32_bf16 v[100:103], v[196:199], v[156:159], v[100:103]
	v_mfma_f32_16x16x32_bf16 v[96:99], v[212:215], v[156:159], v[96:99]
	v_mfma_f32_16x16x32_bf16 v[84:87], v[196:199], v[164:167], v[84:87]
	v_mfma_f32_16x16x32_bf16 v[80:83], v[212:215], v[164:167], v[80:83]
	v_mfma_f32_16x16x32_bf16 v[68:71], v[196:199], v[172:175], v[68:71]
	v_mfma_f32_16x16x32_bf16 v[64:67], v[212:215], v[172:175], v[64:67]
	s_barrier
	s_setprio 0
	s_mov_b32 m0, s46
	ds_read_b128 v[144:147], v208 offset:49152
	ds_read_b128 v[152:155], v208 offset:51200
	ds_read_b128 v[160:163], v208 offset:53248
	ds_read_b128 v[168:171], v208 offset:55296
	ds_read_b128 v[148:151], v208 offset:50176
	ds_read_b128 v[156:159], v208 offset:52224
	ds_read_b128 v[164:167], v208 offset:54272
	ds_read_b128 v[172:175], v208 offset:56320
	global_load_lds_dwordx4 v182, s[100:101]
	s_mov_b32 m0, s47
	s_nop 0
	global_load_lds_dwordx4 v178, s[100:101]
	s_waitcnt vmcnt(10)
	s_setprio 1
	s_barrier
	s_waitcnt lgkmcnt(4)
	v_mfma_f32_16x16x32_bf16 v[60:63], v[128:131], v[144:147], v[60:63]
	v_mfma_f32_16x16x32_bf16 v[56:59], v[136:139], v[144:147], v[56:59]
	v_mfma_f32_16x16x32_bf16 v[44:47], v[128:131], v[152:155], v[44:47]
	v_mfma_f32_16x16x32_bf16 v[40:43], v[136:139], v[152:155], v[40:43]
	v_mfma_f32_16x16x32_bf16 v[28:31], v[128:131], v[160:163], v[28:31]
	v_mfma_f32_16x16x32_bf16 v[24:27], v[136:139], v[160:163], v[24:27]
	v_mfma_f32_16x16x32_bf16 v[12:15], v[128:131], v[168:171], v[12:15]
	v_mfma_f32_16x16x32_bf16 v[8:11], v[136:139], v[168:171], v[8:11]
	s_waitcnt lgkmcnt(0)
	v_mfma_f32_16x16x32_bf16 v[60:63], v[132:135], v[148:151], v[60:63]
	v_mfma_f32_16x16x32_bf16 v[56:59], v[140:143], v[148:151], v[56:59]
	v_mfma_f32_16x16x32_bf16 v[44:47], v[132:135], v[156:159], v[44:47]
	v_mfma_f32_16x16x32_bf16 v[40:43], v[140:143], v[156:159], v[40:43]
	v_mfma_f32_16x16x32_bf16 v[28:31], v[132:135], v[164:167], v[28:31]
	v_mfma_f32_16x16x32_bf16 v[24:27], v[140:143], v[164:167], v[24:27]
	v_mfma_f32_16x16x32_bf16 v[12:15], v[132:135], v[172:175], v[12:15]
	v_mfma_f32_16x16x32_bf16 v[8:11], v[140:143], v[172:175], v[8:11]
	s_barrier
; DI unsigned pack2(float lo, float hi) { f32x2 v = {lo, hi}; bf16v2 r = __builtin_convertvector(v, bf16v2); return __builtin_bit_cast(unsigned, r); }
; #define PG8_STAGE(bufoff, gbase, voff) do { _Pragma("unroll") for (int _i = 0; _i < 2; ++_i) \
;     __builtin_amdgcn_global_load_lds((const unsigned*)((const char*)(gbase) + (voff)[_i]), (LAS unsigned*)(lds + (bufoff) + ldsw + _i * 8192), 16, 0, 0); } while (0)
; #define PG8_WAIT_V(n) asm volatile("s_waitcnt vmcnt(" #n ")" ::: "memory")
; #define PG8_BAR __builtin_amdgcn_s_barrier()
;   DI void operator()(const f32x4 (&acc)[2][2][4][2], const Unit& u, int wr, int wc, int fr, int fq) const {
;     const int row0 = u.pm * BM + wr * 64 + fr, col0 = u.pn * BM + wc * 32 + 8 * fq;
; #pragma unroll
;     for (int ai = 0; ai < 2; ++ai) {
;       f32x4 bv[4][2][2];
; #pragma unroll
;       for (int m = 0; m < 4; ++m)
; #pragma unroll
;         for (int bj = 0; bj < 2; ++bj) {
;           const float* bp = base + (size_t)(row0 + ai * HALF + m * 16) * 2048 + col0 + bj * HALF;
;           bv[m][bj][0] = *(const f32x4*)bp; bv[m][bj][1] = *(const f32x4*)(bp + 4);
;         }
; #pragma unroll
;       for (int m = 0; m < 4; ++m) {
;         const int row = row0 + ai * HALF + m * 16;
;         const size_t off = (size_t)row * 2048 + col0;
;         float ss = 0.f;
; #pragma unroll
;         for (int bj = 0; bj < 2; ++bj) {
;           const f32x4 v0 = acc[ai][bj][m][0] + bv[m][bj][0], v1 = acc[ai][bj][m][1] + bv[m][bj][1];
;           *(f32x4*)(C + off + bj * HALF) = v0; *(f32x4*)(C + off + bj * HALF + 4) = v1;
;           if (xb) {
;             u32x4 w; w.x = pack2(v0[0], v0[1]); w.y = pack2(v0[2], v0[3]); w.z = pack2(v1[0], v1[1]); w.w = pack2(v1[2], v1[3]);
;             *(u32x4*)(xb + off + bj * HALF) = w;
;             ss += v0[0] * v0[0] + v0[1] * v0[1] + v0[2] * v0[2] + v0[3] * v0[3] + v1[0] * v1[0] + v1[1] * v1[1] + v1[2] * v1[2] + v1[3] * v1[3];
;           }
;         }
;         if (xb) {
;           ss += __shfl_xor(ss, 16); ss += __shfl_xor(ss, 32);
;           if (fq == 0) ssq[(size_t)row * 32 + u.pn * 4 + wc] = ss;
; template <class Epi, class Sched = StaticOrder>
; DI void gemm_phase(LAS unsigned char* lds, const Gemm g, const Sched& S, const Epi& E) {
;     ...
;       PG8_STAGE(PG8_SB(1, 1), b3 + hstep, voffB);
;       PG8_WAIT_V(6); PG8_BAR; PG8_MMA(1, 1, At, B1); PG8_BAR;
;     }
	s_setprio 0
	s_add_u32 s24, s24, 0x80080
	s_addc_u32 s25, s25, 0
	s_add_i32 s26, s26, s35
	s_mov_b32 m0, s26
	s_nop 0
	global_load_lds_dwordx4 v180, s[24:25]
	s_add_i32 m0, s26, 0x2000
	s_nop 0
	global_load_lds_dwordx4 v176, s[24:25]
	ds_read_b128 v[128:131], v207
	ds_read_b128 v[132:135], v207 offset:1024
	ds_read_b128 v[136:139], v207 offset:2048
	ds_read_b128 v[140:143], v207 offset:3072
	s_waitcnt vmcnt(6)
	s_setprio 1
	s_barrier
	v_mfma_f32_16x16x32_bf16 v[52:55], v[192:195], v[144:147], v[52:55]
	v_mfma_f32_16x16x32_bf16 v[48:51], v[200:203], v[144:147], v[48:51]
	v_mfma_f32_16x16x32_bf16 v[36:39], v[192:195], v[152:155], v[36:39]
	v_mfma_f32_16x16x32_bf16 v[32:35], v[200:203], v[152:155], v[32:35]
	v_mfma_f32_16x16x32_bf16 v[20:23], v[192:195], v[160:163], v[20:23]
	v_mfma_f32_16x16x32_bf16 v[16:19], v[200:203], v[160:163], v[16:19]
	v_mfma_f32_16x16x32_bf16 v[4:7], v[192:195], v[168:171], v[4:7]
	v_mfma_f32_16x16x32_bf16 v[0:3], v[200:203], v[168:171], v[0:3]
	v_mfma_f32_16x16x32_bf16 v[52:55], v[196:199], v[148:151], v[52:55]
	v_mfma_f32_16x16x32_bf16 v[48:51], v[212:215], v[148:151], v[48:51]
	v_mfma_f32_16x16x32_bf16 v[36:39], v[196:199], v[156:159], v[36:39]
	v_mfma_f32_16x16x32_bf16 v[32:35], v[212:215], v[156:159], v[32:35]
	v_mfma_f32_16x16x32_bf16 v[20:23], v[196:199], v[164:167], v[20:23]
	v_mfma_f32_16x16x32_bf16 v[16:19], v[212:215], v[164:167], v[16:19]
	v_mfma_f32_16x16x32_bf16 v[4:7], v[196:199], v[172:175], v[4:7]
	v_mfma_f32_16x16x32_bf16 v[0:3], v[212:215], v[172:175], v[0:3]
	s_add_i32 s53, s53, 2
	s_add_u32 s22, s22, 0x100
	s_addc_u32 s23, s23, 0
	s_add_u32 s45, s45, 0x100
	s_addc_u32 s52, s52, 0
	s_cmp_gt_u32 s53, 29
	s_barrier
	s_setprio 0
	s_cbranch_scc0 .LBB0_728
	s_waitcnt lgkmcnt(0)
	v_lshl_add_u32 v196, s12, 8, v204
	v_lshl_or_b32 v192, s42, 8, v206
	v_ashrrev_i32_e32 v193, 31, v192
	v_ashrrev_i32_e32 v197, 31, v196
	v_lshl_add_u64 v[194:195], v[192:193], 2, s[60:61]
	v_lshlrev_b64 v[128:129], 13, v[196:197]
	v_lshl_add_u64 v[128:129], v[194:195], 0, v[128:129]
	global_load_dwordx4 v[214:217], v[128:129], off
	global_load_dwordx4 v[218:221], v[128:129], off offset:16
	global_load_dwordx4 v[222:225], v[128:129], off offset:512
	global_load_dwordx4 v[226:229], v[128:129], off offset:528
	v_or_b32_e32 v202, 16, v196
	v_or_b32_e32 v200, 32, v196
	v_or_b32_e32 v198, 48, v196
	v_ashrrev_i32_e32 v203, 31, v202
	v_ashrrev_i32_e32 v201, 31, v200
	v_ashrrev_i32_e32 v199, 31, v198
	v_lshlrev_b64 v[128:129], 13, v[202:203]
	v_lshlrev_b64 v[130:131], 13, v[200:201]
	v_lshlrev_b64 v[132:133], 13, v[198:199]
	v_lshl_add_u64 v[128:129], v[194:195], 0, v[128:129]
	v_lshl_add_u64 v[130:131], v[194:195], 0, v[130:131]
	v_lshl_add_u64 v[132:133], v[194:195], 0, v[132:133]
	global_load_dwordx4 v[168:171], v[128:129], off offset:16
	global_load_dwordx4 v[172:175], v[128:129], off
	global_load_dwordx4 v[160:163], v[128:129], off offset:528
	global_load_dwordx4 v[164:167], v[128:129], off offset:512
	global_load_dwordx4 v[152:155], v[130:131], off offset:16
	global_load_dwordx4 v[156:159], v[130:131], off
	global_load_dwordx4 v[144:147], v[130:131], off offset:528
	global_load_dwordx4 v[148:151], v[130:131], off offset:512
	global_load_dwordx4 v[136:139], v[132:133], off offset:16
	global_load_dwordx4 v[140:143], v[132:133], off
	s_nop 0
	global_load_dwordx4 v[128:131], v[132:133], off offset:528
	s_nop 0
	global_load_dwordx4 v[132:135], v[132:133], off offset:512
	v_and_b32_e32 v212, 64, v211
	v_xor_b32_e32 v230, 16, v211
	v_add_u32_e32 v232, 64, v212
	v_xor_b32_e32 v231, 32, v211
	v_cmp_lt_i32_e32 vcc, v230, v232
	v_lshlrev_b64 v[212:213], 11, v[196:197]
	v_readlane_b32 s64, v243, 3
	v_cndmask_b32_e32 v233, v211, v230, vcc
	v_cmp_lt_i32_e32 vcc, v231, v232
	v_readlane_b32 s78, v243, 17
	v_readlane_b32 s79, v243, 18
	v_cndmask_b32_e32 v234, v211, v231, vcc
	v_lshl_add_u64 v[230:231], v[212:213], 0, v[192:193]
	v_lshlrev_b32_e32 v212, 2, v233
	v_lshl_add_u64 v[232:233], v[230:231], 2, s[78:79]
	v_lshl_add_u64 v[230:231], v[230:231], 1, s[2:3]
	s_lshl_b32 s22, s42, 2
	s_ashr_i32 s23, s22, 31
	v_readlane_b32 s65, v243, 4
	v_readlane_b32 s66, v243, 5
	v_readlane_b32 s67, v243, 6
	v_readlane_b32 s68, v243, 7
	v_readlane_b32 s69, v243, 8
	v_readlane_b32 s70, v243, 9
	v_readlane_b32 s71, v243, 10
	v_readlane_b32 s72, v243, 11
	v_readlane_b32 s73, v243, 12
	v_readlane_b32 s74, v243, 13
	v_readlane_b32 s75, v243, 14
	v_readlane_b32 s76, v243, 15
	v_readlane_b32 s77, v243, 16
	s_waitcnt vmcnt(0)
	v_pk_add_f32 v[126:127], v[126:127], v[216:217]
	v_pk_add_f32 v[124:125], v[124:125], v[214:215]
	v_pk_add_f32 v[116:117], v[116:117], v[222:223]
	v_pk_add_f32 v[122:123], v[122:123], v[220:221]
	v_pk_add_f32 v[120:121], v[120:121], v[218:219]
	v_pk_add_f32 v[214:215], v[112:113], v[226:227]
	global_store_dwordx4 v[232:233], v[124:127], off
	global_store_dwordx4 v[232:233], v[120:123], off offset:16
	v_cvt_pk_bf16_f32 v112, v124, v125
	v_mul_f32_e32 v125, v125, v125
	v_mul_f32_e32 v213, v117, v117
	v_pk_add_f32 v[118:119], v[118:119], v[224:225]
	v_fmac_f32_e32 v125, v124, v124
	v_fmac_f32_e32 v213, v116, v116
	v_fmac_f32_e32 v125, v126, v126
	v_fmac_f32_e32 v213, v118, v118
	v_fmac_f32_e32 v125, v127, v127
	v_fmac_f32_e32 v213, v119, v119
	v_fmac_f32_e32 v125, v120, v120
	v_fmac_f32_e32 v213, v214, v214
	v_pk_add_f32 v[216:217], v[114:115], v[228:229]
	v_fmac_f32_e32 v125, v121, v121
	v_fmac_f32_e32 v213, v215, v215
	v_fmac_f32_e32 v125, v122, v122
	v_fmac_f32_e32 v213, v216, v216
	v_fmac_f32_e32 v125, v123, v123
	v_fmac_f32_e32 v213, v217, v217
	v_cvt_pk_bf16_f32 v114, v120, v121
	v_add_f32_e32 v120, v125, v213
	ds_bpermute_b32 v121, v212, v120
	v_cvt_pk_bf16_f32 v113, v126, v127
	v_cvt_pk_bf16_f32 v115, v122, v123
	global_store_dwordx4 v[230:231], v[112:115], off
	global_store_dwordx4 v[232:233], v[116:119], off offset:512
	global_store_dwordx4 v[232:233], v[214:217], off offset:528
	v_cvt_pk_bf16_f32 v122, v116, v117
	s_waitcnt lgkmcnt(0)
	v_add_f32_e32 v112, v120, v121
	v_lshlrev_b32_e32 v120, 2, v234
	ds_bpermute_b32 v113, v120, v112
	v_cvt_pk_bf16_f32 v123, v118, v119
	v_cvt_pk_bf16_f32 v124, v214, v215
	v_cvt_pk_bf16_f32 v125, v216, v217
	global_store_dwordx4 v[230:231], v[122:125], off offset:256
	s_and_saveexec_b64 s[24:25], s[0:1]
	s_cbranch_execz .LBB0_731
	s_waitcnt lgkmcnt(0)
	v_add_f32_e32 v114, v112, v113
	v_lshlrev_b64 v[112:113], 7, v[196:197]
	v_lshl_add_u64 v[112:113], s[8:9], 0, v[112:113]
	v_lshl_add_u64 v[112:113], s[22:23], 2, v[112:113]
	s_lshl_b32 s12, s41, 2
	v_lshl_add_u64 v[112:113], v[112:113], 0, s[12:13]
	global_store_dword v[112:113], v114, off

; #define PG8_STAGE(bufoff, gbase, voff) do { _Pragma("unroll") for (int _i = 0; _i < 2; ++_i) \
;     __builtin_amdgcn_global_load_lds((const unsigned*)((const char*)(gbase) + (voff)[_i]), (LAS unsigned*)(lds + (bufoff) + ldsw + _i * 8192), 16, 0, 0); } while (0)
; #define PG8_LDA(dst, b, h) do { _Pragma("unroll") for (int m = 0; m < 4; ++m) _Pragma("unroll") for (int k = 0; k < 2; ++k) dst[m][k] = *(const LAS bf16x8*)(lds + PG8_SA(b, h) + aoff + m * 2048 + k * 1024); } while (0)
; #define PG8_LDB(dst, b, h) do { _Pragma("unroll") for (int n = 0; n < 2; ++n) _Pragma("unroll") for (int k = 0; k < 2; ++k) dst[n][k] = *(const LAS bf16x8*)(lds + PG8_SB(b, h) + boff + n * 2048 + k * 1024); } while (0)
; #define PG8_MMA(ai, bj, At, Bt) do { __builtin_amdgcn_s_setprio(1); _Pragma("unroll") for (int m = 0; m < 4; ++m) _Pragma("unroll") for (int n = 0; n < 2; ++n) _Pragma("unroll") for (int k = 0; k < 2; ++k) \
;     acc[ai][bj][m][n] = __builtin_amdgcn_mfma_f32_16x16x32_bf16(Bt[n][k], At[m][k], acc[ai][bj][m][n], 0, 0, 0); __builtin_amdgcn_s_setprio(0); } while (0)
; #define PG8_WAIT_V(n) asm volatile("s_waitcnt vmcnt(" #n ")" ::: "memory")
; #define PG8_WAIT_L(n) asm volatile("s_waitcnt lgkmcnt(" #n ")" ::: "memory")
; template <class Epi, class Sched = StaticOrder>
; DI void gemm_phase(LAS unsigned char* lds, const Gemm g, const Sched& S, const Epi& E) {
;     ...
;     for (int t = 0; t < nt; t += 2) {
;       const bool last = (t == nt - 2);
;       const char* a1 = cA + (size_t)(t + 1) * kstep;
;       const char* a2 = last ? nA : cA + (size_t)(t + 2) * kstep; const char* b2 = last ? nB : cB + (size_t)(t + 2) * kstep;
;       const char* a3 = a2 + kstep; const char* b3 = b2 + kstep;
;       PG8_LDB(B0, 0, 0); PG8_SCHED; PG8_LDA(At, 0, 0); PG8_STAGE(PG8_SA(1, 1), a1 + hstep, voffA);
;       PG8_WAIT_L(8); PG8_BAR; PG8_WAIT_L(0); PG8_MMA(0, 0, At, B0); PG8_BAR; PG8_SCHED;
;       PG8_LDB(B1, 0, 1); PG8_STAGE(PG8_SB(0, 0), b2, voffB);
;       PG8_BAR; PG8_WAIT_L(0); PG8_MMA(0, 1, At, B1); PG8_BAR;
;       PG8_LDA(At, 0, 1); PG8_STAGE(PG8_SA(0, 0), a2, voffA);
;       PG8_BAR; PG8_WAIT_L(0); PG8_MMA(1, 0, At, B0); PG8_BAR; PG8_SCHED;
;       PG8_STAGE(PG8_SB(0, 1), b2 + hstep, voffB);
;       PG8_WAIT_V(6); PG8_BAR; PG8_MMA(1, 1, At, B1); PG8_BAR;
;       PG8_LDB(B0, 1, 0); PG8_SCHED; PG8_LDA(At, 1, 0); PG8_STAGE(PG8_SA(0, 1), a2 + hstep, voffA);
.LBB0_811:
	s_add_u32 s46, s14, 0xfff80080
	s_addc_u32 s47, s15, -1
	s_cmp_eq_u32 s52, 28
	s_cselect_b32 s49, s37, s47
	s_cselect_b32 s48, s42, s46
	s_cselect_b32 s47, s35, s45
	s_cselect_b32 s46, s43, s44
	s_add_i32 m0, s62, 0xc000
	ds_read_b128 v[80:83], v202
	ds_read_b128 v[92:95], v202 offset:2048
	ds_read_b128 v[180:183], v202 offset:4096
	ds_read_b128 v[188:191], v202 offset:6144
	ds_read_b128 v[84:87], v202 offset:1024
	ds_read_b128 v[96:99], v202 offset:3072
	ds_read_b128 v[184:187], v202 offset:5120
	ds_read_b128 v[192:195], v202 offset:7168
	global_load_lds_dwordx4 v170, s[14:15]
	s_add_i32 m0, s62, 0xe000
	s_nop 0
	global_load_lds_dwordx4 v172, s[14:15]
	s_waitcnt lgkmcnt(8)
	s_setprio 1
	s_barrier
	s_waitcnt lgkmcnt(4)
	v_mfma_f32_16x16x32_bf16 v[156:159], v[64:67], v[80:83], v[156:159]
	v_mfma_f32_16x16x32_bf16 v[144:147], v[72:75], v[80:83], v[144:147]
	v_mfma_f32_16x16x32_bf16 v[140:143], v[64:67], v[92:95], v[140:143]
	v_mfma_f32_16x16x32_bf16 v[132:135], v[72:75], v[92:95], v[132:135]
	v_mfma_f32_16x16x32_bf16 v[124:127], v[64:67], v[180:183], v[124:127]
	v_mfma_f32_16x16x32_bf16 v[116:119], v[72:75], v[180:183], v[116:119]
	v_mfma_f32_16x16x32_bf16 v[112:115], v[64:67], v[188:191], v[112:115]
	v_mfma_f32_16x16x32_bf16 v[108:111], v[72:75], v[188:191], v[108:111]
	s_waitcnt lgkmcnt(0)
	v_mfma_f32_16x16x32_bf16 v[156:159], v[68:71], v[84:87], v[156:159]
	v_mfma_f32_16x16x32_bf16 v[144:147], v[76:79], v[84:87], v[144:147]
	v_mfma_f32_16x16x32_bf16 v[140:143], v[68:71], v[96:99], v[140:143]
	v_mfma_f32_16x16x32_bf16 v[132:135], v[76:79], v[96:99], v[132:135]
	v_mfma_f32_16x16x32_bf16 v[124:127], v[68:71], v[184:187], v[124:127]
	v_mfma_f32_16x16x32_bf16 v[116:119], v[76:79], v[184:187], v[116:119]
	v_mfma_f32_16x16x32_bf16 v[112:115], v[68:71], v[192:195], v[112:115]
	v_mfma_f32_16x16x32_bf16 v[108:111], v[76:79], v[192:195], v[108:111]
	s_barrier
	s_setprio 0
	s_add_i32 s53, s72, s60
	s_add_u32 s98, s46, 0x80
	s_addc_u32 s99, s47, 0
	s_add_u32 s100, s48, 0x80
	s_addc_u32 s101, s49, 0
	s_mov_b32 m0, s53
	ds_read_b128 v[206:209], v203
	ds_read_b128 v[212:215], v203 offset:1024
	ds_read_b128 v[216:219], v203 offset:2048
	ds_read_b128 v[220:223], v203 offset:3072
	global_load_lds_dwordx4 v164, s[46:47]
	s_add_i32 m0, s53, 0x2000
	s_nop 0
	global_load_lds_dwordx4 v160, s[46:47]
	s_setprio 1
	s_barrier
	s_waitcnt lgkmcnt(0)
	v_mfma_f32_16x16x32_bf16 v[152:155], v[206:209], v[80:83], v[152:155]
	v_mfma_f32_16x16x32_bf16 v[80:83], v[216:219], v[80:83], v[148:151]
	v_mfma_f32_16x16x32_bf16 v[152:155], v[212:215], v[84:87], v[152:155]
	v_mfma_f32_16x16x32_bf16 v[80:83], v[220:223], v[84:87], v[80:83]
	v_mfma_f32_16x16x32_bf16 v[84:87], v[206:209], v[92:95], v[136:139]
	v_mfma_f32_16x16x32_bf16 v[92:95], v[216:219], v[92:95], v[128:131]
	v_mfma_f32_16x16x32_bf16 v[104:107], v[216:219], v[180:183], v[104:107]
	v_mfma_f32_16x16x32_bf16 v[100:103], v[206:209], v[188:191], v[100:103]
	v_mfma_f32_16x16x32_bf16 v[88:91], v[216:219], v[188:191], v[88:91]
	v_mfma_f32_16x16x32_bf16 v[84:87], v[212:215], v[96:99], v[84:87]
	v_mfma_f32_16x16x32_bf16 v[92:95], v[220:223], v[96:99], v[92:95]
	v_mfma_f32_16x16x32_bf16 v[96:99], v[206:209], v[180:183], v[120:123]
	v_mfma_f32_16x16x32_bf16 v[104:107], v[220:223], v[184:187], v[104:107]
	v_mfma_f32_16x16x32_bf16 v[100:103], v[212:215], v[192:195], v[100:103]
	v_mfma_f32_16x16x32_bf16 v[88:91], v[220:223], v[192:195], v[88:91]
	v_mfma_f32_16x16x32_bf16 v[96:99], v[212:215], v[184:187], v[96:99]
	s_barrier
	s_setprio 0
	s_mov_b32 m0, s62
	ds_read_b128 v[120:123], v202 offset:16384
	ds_read_b128 v[136:139], v202 offset:18432
	ds_read_b128 v[180:183], v202 offset:20480
	ds_read_b128 v[188:191], v202 offset:22528
	ds_read_b128 v[128:131], v202 offset:17408
	ds_read_b128 v[148:151], v202 offset:19456
	ds_read_b128 v[184:187], v202 offset:21504
	ds_read_b128 v[192:195], v202 offset:23552
	global_load_lds_dwordx4 v166, s[48:49]
	s_mov_b32 m0, s63
	s_nop 0
	global_load_lds_dwordx4 v162, s[48:49]
	s_waitcnt vmcnt(10)
	s_setprio 1
	s_barrier
	s_waitcnt lgkmcnt(4)
	v_mfma_f32_16x16x32_bf16 v[60:63], v[64:67], v[120:123], v[60:63]
	v_mfma_f32_16x16x32_bf16 v[48:51], v[72:75], v[120:123], v[48:51]
	v_mfma_f32_16x16x32_bf16 v[44:47], v[64:67], v[136:139], v[44:47]
	v_mfma_f32_16x16x32_bf16 v[36:39], v[72:75], v[136:139], v[36:39]
	v_mfma_f32_16x16x32_bf16 v[28:31], v[64:67], v[180:183], v[28:31]
	v_mfma_f32_16x16x32_bf16 v[20:23], v[72:75], v[180:183], v[20:23]
	v_mfma_f32_16x16x32_bf16 v[16:19], v[64:67], v[188:191], v[16:19]
	v_mfma_f32_16x16x32_bf16 v[12:15], v[72:75], v[188:191], v[12:15]
	s_waitcnt lgkmcnt(0)
	v_mfma_f32_16x16x32_bf16 v[60:63], v[68:71], v[128:131], v[60:63]
	v_mfma_f32_16x16x32_bf16 v[48:51], v[76:79], v[128:131], v[48:51]
	v_mfma_f32_16x16x32_bf16 v[44:47], v[68:71], v[148:151], v[44:47]
	v_mfma_f32_16x16x32_bf16 v[36:39], v[76:79], v[148:151], v[36:39]
	v_mfma_f32_16x16x32_bf16 v[28:31], v[68:71], v[184:187], v[28:31]
	v_mfma_f32_16x16x32_bf16 v[20:23], v[76:79], v[184:187], v[20:23]
	v_mfma_f32_16x16x32_bf16 v[16:19], v[68:71], v[192:195], v[16:19]
	v_mfma_f32_16x16x32_bf16 v[12:15], v[76:79], v[192:195], v[12:15]
	s_barrier
	s_setprio 0
	s_add_u32 s54, s46, 0x80000
	s_addc_u32 s55, s47, 0
	s_add_i32 s53, s73, s60
	s_mov_b32 m0, s53
	s_nop 0
	global_load_lds_dwordx4 v164, s[54:55]
	s_add_i32 m0, s53, 0x2000
	s_nop 0
	global_load_lds_dwordx4 v160, s[54:55]
	s_add_i32 s53, 0, 0x18000
	v_add_u32_e32 v76, s53, v198
	ds_read_b128 v[64:67], v76
	ds_read_b128 v[68:71], v76 offset:1024
	ds_read_b128 v[72:75], v76 offset:2048
	ds_read_b128 v[76:79], v76 offset:3072
	s_waitcnt vmcnt(6)
	s_setprio 1
	s_barrier
; #define PG8_STAGE(bufoff, gbase, voff) do { _Pragma("unroll") for (int _i = 0; _i < 2; ++_i) \
;     __builtin_amdgcn_global_load_lds((const unsigned*)((const char*)(gbase) + (voff)[_i]), (LAS unsigned*)(lds + (bufoff) + ldsw + _i * 8192), 16, 0, 0); } while (0)
; #define PG8_LDA(dst, b, h) do { _Pragma("unroll") for (int m = 0; m < 4; ++m) _Pragma("unroll") for (int k = 0; k < 2; ++k) dst[m][k] = *(const LAS bf16x8*)(lds + PG8_SA(b, h) + aoff + m * 2048 + k * 1024); } while (0)
; #define PG8_LDB(dst, b, h) do { _Pragma("unroll") for (int n = 0; n < 2; ++n) _Pragma("unroll") for (int k = 0; k < 2; ++k) dst[n][k] = *(const LAS bf16x8*)(lds + PG8_SB(b, h) + boff + n * 2048 + k * 1024); } while (0)
; #define PG8_MMA(ai, bj, At, Bt) do { __builtin_amdgcn_s_setprio(1); _Pragma("unroll") for (int m = 0; m < 4; ++m) _Pragma("unroll") for (int n = 0; n < 2; ++n) _Pragma("unroll") for (int k = 0; k < 2; ++k) \
;     acc[ai][bj][m][n] = __builtin_amdgcn_mfma_f32_16x16x32_bf16(Bt[n][k], At[m][k], acc[ai][bj][m][n], 0, 0, 0); __builtin_amdgcn_s_setprio(0); } while (0)
; #define PG8_WAIT_V(n) asm volatile("s_waitcnt vmcnt(" #n ")" ::: "memory")
; #define PG8_WAIT_L(n) asm volatile("s_waitcnt lgkmcnt(" #n ")" ::: "memory")
; #define PG8_BAR __builtin_amdgcn_s_barrier()
; #define PG8_SCHED __builtin_amdgcn_sched_barrier(0)
; template <class Epi, class Sched = StaticOrder>
; DI void gemm_phase(LAS unsigned char* lds, const Gemm g, const Sched& S, const Epi& E) {
;     ...
;       PG8_WAIT_V(6); PG8_BAR; PG8_MMA(1, 1, At, B1); PG8_BAR;
;       PG8_LDB(B0, 1, 0); PG8_SCHED; PG8_LDA(At, 1, 0); PG8_STAGE(PG8_SA(0, 1), a2 + hstep, voffA);
;       PG8_WAIT_L(8); PG8_BAR; PG8_WAIT_L(0); PG8_MMA(0, 0, At, B0); PG8_BAR; PG8_SCHED;
;       PG8_LDB(B1, 1, 1); PG8_STAGE(PG8_SB(1, 0), b3, voffB);
;       PG8_BAR; PG8_WAIT_L(0); PG8_MMA(0, 1, At, B1); PG8_BAR;
;       PG8_LDA(At, 1, 1); PG8_STAGE(PG8_SA(1, 0), a3, voffA);
;       PG8_BAR; PG8_WAIT_L(0); PG8_MMA(1, 0, At, B0); PG8_BAR; PG8_SCHED;
	v_mfma_f32_16x16x32_bf16 v[56:59], v[206:209], v[120:123], v[56:59]
	v_mfma_f32_16x16x32_bf16 v[52:55], v[216:219], v[120:123], v[52:55]
	v_mfma_f32_16x16x32_bf16 v[40:43], v[206:209], v[136:139], v[40:43]
	v_mfma_f32_16x16x32_bf16 v[32:35], v[216:219], v[136:139], v[32:35]
	v_mfma_f32_16x16x32_bf16 v[24:27], v[206:209], v[180:183], v[24:27]
	v_mfma_f32_16x16x32_bf16 v[8:11], v[216:219], v[180:183], v[8:11]
	v_mfma_f32_16x16x32_bf16 v[4:7], v[206:209], v[188:191], v[4:7]
	v_mfma_f32_16x16x32_bf16 v[0:3], v[216:219], v[188:191], v[0:3]
	v_mfma_f32_16x16x32_bf16 v[56:59], v[212:215], v[128:131], v[56:59]
	v_mfma_f32_16x16x32_bf16 v[52:55], v[220:223], v[128:131], v[52:55]
	v_mfma_f32_16x16x32_bf16 v[40:43], v[212:215], v[148:151], v[40:43]
	v_mfma_f32_16x16x32_bf16 v[32:35], v[220:223], v[148:151], v[32:35]
	v_mfma_f32_16x16x32_bf16 v[24:27], v[212:215], v[184:187], v[24:27]
	v_mfma_f32_16x16x32_bf16 v[8:11], v[220:223], v[184:187], v[8:11]
	v_mfma_f32_16x16x32_bf16 v[4:7], v[212:215], v[192:195], v[4:7]
	v_mfma_f32_16x16x32_bf16 v[0:3], v[220:223], v[192:195], v[0:3]
	s_barrier
	s_setprio 0
	s_add_u32 s48, s48, 0x80000
	s_addc_u32 s49, s49, 0
	s_mov_b32 m0, s64
	ds_read_b128 v[120:123], v202 offset:32768
	ds_read_b128 v[128:131], v202 offset:33792
	ds_read_b128 v[180:183], v202 offset:34816
	ds_read_b128 v[188:191], v202 offset:36864
	ds_read_b128 v[184:187], v202 offset:35840
	ds_read_b128 v[192:195], v202 offset:37888
	ds_read_b128 v[206:209], v202 offset:38912
	ds_read_b128 v[212:215], v202 offset:39936
	global_load_lds_dwordx4 v166, s[48:49]
	s_mov_b32 m0, s65
	s_nop 0
	global_load_lds_dwordx4 v162, s[48:49]
	s_waitcnt lgkmcnt(8)
	s_setprio 1
	s_barrier
	s_waitcnt lgkmcnt(4)
	v_mfma_f32_16x16x32_bf16 v[136:139], v[64:67], v[120:123], v[156:159]
	v_mfma_f32_16x16x32_bf16 v[156:159], v[68:71], v[128:131], v[136:139]
	v_mfma_f32_16x16x32_bf16 v[136:139], v[72:75], v[120:123], v[144:147]
	v_mfma_f32_16x16x32_bf16 v[144:147], v[76:79], v[128:131], v[136:139]
	v_mfma_f32_16x16x32_bf16 v[136:139], v[64:67], v[180:183], v[140:143]
	v_mfma_f32_16x16x32_bf16 v[132:135], v[72:75], v[180:183], v[132:135]
	v_mfma_f32_16x16x32_bf16 v[124:127], v[64:67], v[188:191], v[124:127]
	v_mfma_f32_16x16x32_bf16 v[116:119], v[72:75], v[188:191], v[116:119]
	s_waitcnt lgkmcnt(0)
	v_mfma_f32_16x16x32_bf16 v[112:115], v[64:67], v[206:209], v[112:115]
	v_mfma_f32_16x16x32_bf16 v[108:111], v[72:75], v[206:209], v[108:111]
	v_mfma_f32_16x16x32_bf16 v[140:143], v[68:71], v[184:187], v[136:139]
	v_mfma_f32_16x16x32_bf16 v[132:135], v[76:79], v[184:187], v[132:135]
	v_mfma_f32_16x16x32_bf16 v[124:127], v[68:71], v[192:195], v[124:127]
	v_mfma_f32_16x16x32_bf16 v[116:119], v[76:79], v[192:195], v[116:119]
	v_mfma_f32_16x16x32_bf16 v[112:115], v[68:71], v[212:215], v[112:115]
	v_mfma_f32_16x16x32_bf16 v[108:111], v[76:79], v[212:215], v[108:111]
	s_barrier
	s_setprio 0
	s_add_i32 s48, 0, 0x1c000
	v_add_u32_e32 v136, s48, v198
	s_add_i32 s49, s53, s60
	ds_read_b128 v[216:219], v136
	ds_read_b128 v[220:223], v136 offset:1024
	ds_read_b128 v[224:227], v136 offset:2048
	ds_read_b128 v[228:231], v136 offset:3072
	s_mov_b32 m0, s49
	s_nop 0
	global_load_lds_dwordx4 v164, s[98:99]
	s_add_i32 m0, s49, 0x2000
	s_nop 0
	global_load_lds_dwordx4 v160, s[98:99]
	s_setprio 1
	s_barrier
	s_waitcnt lgkmcnt(0)
	v_mfma_f32_16x16x32_bf16 v[80:83], v[224:227], v[120:123], v[80:83]
	v_mfma_f32_16x16x32_bf16 v[136:139], v[216:219], v[120:123], v[152:155]
	v_mfma_f32_16x16x32_bf16 v[148:151], v[228:231], v[128:131], v[80:83]
	v_mfma_f32_16x16x32_bf16 v[80:83], v[216:219], v[180:183], v[84:87]
	v_mfma_f32_16x16x32_bf16 v[152:155], v[220:223], v[128:131], v[136:139]
	v_mfma_f32_16x16x32_bf16 v[136:139], v[220:223], v[184:187], v[80:83]
	v_mfma_f32_16x16x32_bf16 v[80:83], v[224:227], v[180:183], v[92:95]
	v_mfma_f32_16x16x32_bf16 v[128:131], v[228:231], v[184:187], v[80:83]
	v_mfma_f32_16x16x32_bf16 v[80:83], v[216:219], v[188:191], v[96:99]
	v_mfma_f32_16x16x32_bf16 v[120:123], v[220:223], v[192:195], v[80:83]
	v_mfma_f32_16x16x32_bf16 v[80:83], v[224:227], v[188:191], v[104:107]
	v_mfma_f32_16x16x32_bf16 v[104:107], v[228:231], v[192:195], v[80:83]
	v_mfma_f32_16x16x32_bf16 v[80:83], v[216:219], v[206:209], v[100:103]
	v_mfma_f32_16x16x32_bf16 v[100:103], v[220:223], v[212:215], v[80:83]
	v_mfma_f32_16x16x32_bf16 v[80:83], v[224:227], v[206:209], v[88:91]
	v_mfma_f32_16x16x32_bf16 v[88:91], v[228:231], v[212:215], v[80:83]
	s_barrier
	s_setprio 0
	s_mov_b32 m0, s67
	s_nop 2
	ds_read_b128 v[80:83], v202 offset:49152
	ds_read_b128 v[92:95], v202 offset:51200
	ds_read_b128 v[180:183], v202 offset:53248
	ds_read_b128 v[188:191], v202 offset:55296
	ds_read_b128 v[84:87], v202 offset:50176
	ds_read_b128 v[96:99], v202 offset:52224
	ds_read_b128 v[184:187], v202 offset:54272
	ds_read_b128 v[192:195], v202 offset:56320
	global_load_lds_dwordx4 v166, s[100:101]
	s_mov_b32 m0, s68
	s_nop 0
	global_load_lds_dwordx4 v162, s[100:101]
	s_waitcnt vmcnt(10)
	s_setprio 1
	s_barrier
	s_waitcnt lgkmcnt(4)
	v_mfma_f32_16x16x32_bf16 v[60:63], v[64:67], v[80:83], v[60:63]
	v_mfma_f32_16x16x32_bf16 v[48:51], v[72:75], v[80:83], v[48:51]
	v_mfma_f32_16x16x32_bf16 v[44:47], v[64:67], v[92:95], v[44:47]
	v_mfma_f32_16x16x32_bf16 v[36:39], v[72:75], v[92:95], v[36:39]
	v_mfma_f32_16x16x32_bf16 v[28:31], v[64:67], v[180:183], v[28:31]
	v_mfma_f32_16x16x32_bf16 v[20:23], v[72:75], v[180:183], v[20:23]
	v_mfma_f32_16x16x32_bf16 v[16:19], v[64:67], v[188:191], v[16:19]
	v_mfma_f32_16x16x32_bf16 v[12:15], v[72:75], v[188:191], v[12:15]
	s_waitcnt lgkmcnt(0)
	v_mfma_f32_16x16x32_bf16 v[60:63], v[68:71], v[84:87], v[60:63]
	v_mfma_f32_16x16x32_bf16 v[48:51], v[76:79], v[84:87], v[48:51]
	v_mfma_f32_16x16x32_bf16 v[44:47], v[68:71], v[96:99], v[44:47]
	v_mfma_f32_16x16x32_bf16 v[36:39], v[76:79], v[96:99], v[36:39]
	v_mfma_f32_16x16x32_bf16 v[28:31], v[68:71], v[184:187], v[28:31]
	v_mfma_f32_16x16x32_bf16 v[20:23], v[76:79], v[184:187], v[20:23]
	v_mfma_f32_16x16x32_bf16 v[16:19], v[68:71], v[192:195], v[16:19]
	v_mfma_f32_16x16x32_bf16 v[12:15], v[76:79], v[192:195], v[12:15]
	s_barrier
; #define PG8_STAGE(bufoff, gbase, voff) do { _Pragma("unroll") for (int _i = 0; _i < 2; ++_i) \
;     __builtin_amdgcn_global_load_lds((const unsigned*)((const char*)(gbase) + (voff)[_i]), (LAS unsigned*)(lds + (bufoff) + ldsw + _i * 8192), 16, 0, 0); } while (0)
; #define PG8_MMA(ai, bj, At, Bt) do { __builtin_amdgcn_s_setprio(1); _Pragma("unroll") for (int m = 0; m < 4; ++m) _Pragma("unroll") for (int n = 0; n < 2; ++n) _Pragma("unroll") for (int k = 0; k < 2; ++k) \
;     acc[ai][bj][m][n] = __builtin_amdgcn_mfma_f32_16x16x32_bf16(Bt[n][k], At[m][k], acc[ai][bj][m][n], 0, 0, 0); __builtin_amdgcn_s_setprio(0); } while (0)
; #define PG8_WAIT_V(n) asm volatile("s_waitcnt vmcnt(" #n ")" ::: "memory")
; #define PG8_BAR __builtin_amdgcn_s_barrier()
;   DI void operator()(const f32x4 (&acc)[2][2][4][2], const Unit& u, int wr, int wc, int fr, int fq) const {
;     const int col = u.pn * 128 + wc * 32 + 8 * fq;
;     float w0[8], w1[8], w2[8], bb[8];
; #pragma unroll
;     for (int e = 0; e < 8; ++e) { w0[e] = cw[col + e]; w1[e] = cw[5632 + col + e]; w2[e] = cw[2 * 5632 + col + e]; bb[e] = cb[col + e]; }
; #pragma unroll
;     for (int ai = 0; ai < 2; ++ai) {
;       const int row0 = u.pm * BM + ai * HALF + wr * 64, span = row0 >> 6;
;       float rsv[4];
; #pragma unroll
;       for (int m = 0; m < 4; ++m) rsv[m] = row_rstd(ssq, row0 + 16 * m + fr, fq);
; template <class Epi, class Sched = StaticOrder>
; DI void gemm_phase(LAS unsigned char* lds, const Gemm g, const Sched& S, const Epi& E) {
;     ...
;       PG8_STAGE(PG8_SB(1, 1), b3 + hstep, voffB);
;       PG8_WAIT_V(6); PG8_BAR; PG8_MMA(1, 1, At, B1); PG8_BAR;
;     }
	s_setprio 0
	s_add_u32 s46, s46, 0x80080
	s_addc_u32 s47, s47, 0
	s_add_i32 s48, s48, s60
	s_mov_b32 m0, s48
	s_nop 0
	global_load_lds_dwordx4 v164, s[46:47]
	s_add_i32 m0, s48, 0x2000
	s_nop 0
	global_load_lds_dwordx4 v160, s[46:47]
	ds_read_b128 v[64:67], v201
	ds_read_b128 v[68:71], v201 offset:1024
	ds_read_b128 v[72:75], v201 offset:2048
	ds_read_b128 v[76:79], v201 offset:3072
	s_waitcnt vmcnt(6)
	s_setprio 1
	s_barrier
	v_mfma_f32_16x16x32_bf16 v[56:59], v[216:219], v[80:83], v[56:59]
	v_mfma_f32_16x16x32_bf16 v[52:55], v[224:227], v[80:83], v[52:55]
	v_mfma_f32_16x16x32_bf16 v[40:43], v[216:219], v[92:95], v[40:43]
	v_mfma_f32_16x16x32_bf16 v[32:35], v[224:227], v[92:95], v[32:35]
	v_mfma_f32_16x16x32_bf16 v[24:27], v[216:219], v[180:183], v[24:27]
	v_mfma_f32_16x16x32_bf16 v[8:11], v[224:227], v[180:183], v[8:11]
	v_mfma_f32_16x16x32_bf16 v[4:7], v[216:219], v[188:191], v[4:7]
	v_mfma_f32_16x16x32_bf16 v[0:3], v[224:227], v[188:191], v[0:3]
	v_mfma_f32_16x16x32_bf16 v[56:59], v[220:223], v[84:87], v[56:59]
	v_mfma_f32_16x16x32_bf16 v[52:55], v[228:231], v[84:87], v[52:55]
	v_mfma_f32_16x16x32_bf16 v[40:43], v[220:223], v[96:99], v[40:43]
	v_mfma_f32_16x16x32_bf16 v[32:35], v[228:231], v[96:99], v[32:35]
	v_mfma_f32_16x16x32_bf16 v[24:27], v[220:223], v[184:187], v[24:27]
	v_mfma_f32_16x16x32_bf16 v[8:11], v[228:231], v[184:187], v[8:11]
	v_mfma_f32_16x16x32_bf16 v[4:7], v[220:223], v[192:195], v[4:7]
	v_mfma_f32_16x16x32_bf16 v[0:3], v[228:231], v[192:195], v[0:3]
	s_add_i32 s52, s52, 2
	s_add_u32 s14, s14, 0x100
	s_addc_u32 s15, s15, 0
	s_add_u32 s44, s44, 0x100
	s_addc_u32 s45, s45, 0
	s_cmp_gt_u32 s52, 29
	s_barrier
	s_setprio 0
	s_cbranch_scc0 .LBB0_811
	s_waitcnt lgkmcnt(0)
	s_lshl_b32 s35, s12, 8
	s_add_i32 s35, s35, s66
	v_or_b32_e32 v190, s35, v179
	v_ashrrev_i32_e32 v191, 31, v190
	v_lshlrev_b64 v[64:65], 7, v[190:191]
	v_or_b32_e32 v188, 16, v190
	v_lshl_add_u64 v[64:65], v[168:169], 0, v[64:65]
	v_ashrrev_i32_e32 v189, 31, v188
	global_load_dwordx4 v[192:195], v[64:65], off
	global_load_dwordx4 v[206:209], v[64:65], off offset:16
	v_lshlrev_b64 v[64:65], 7, v[188:189]
	v_lshl_add_u64 v[64:65], v[168:169], 0, v[64:65]
	global_load_dwordx4 v[212:215], v[64:65], off
	global_load_dwordx4 v[216:219], v[64:65], off offset:16
	v_or_b32_e32 v186, 32, v190
	v_ashrrev_i32_e32 v187, 31, v186
	v_lshlrev_b64 v[64:65], 7, v[186:187]
	v_or_b32_e32 v184, 48, v190
	v_lshl_add_u64 v[64:65], v[168:169], 0, v[64:65]
	v_ashrrev_i32_e32 v185, 31, v184
	global_load_dwordx4 v[220:223], v[64:65], off
	global_load_dwordx4 v[224:227], v[64:65], off offset:16
	v_lshlrev_b64 v[64:65], 7, v[184:185]
	v_lshl_add_u64 v[64:65], v[168:169], 0, v[64:65]
	global_load_dwordx4 v[228:231], v[64:65], off
	global_load_dwordx4 v[232:235], v[64:65], off offset:16
	v_lshl_or_b32 v180, s13, 7, v200
	v_and_b32_e32 v65, 64, v204
	v_xor_b32_e32 v64, 16, v204
	v_ashrrev_i32_e32 v181, 31, v180
	v_add_u32_e32 v65, 64, v65
	v_readlane_b32 s44, v243, 3
	v_xor_b32_e32 v66, 32, v204
	v_lshlrev_b64 v[182:183], 2, v[180:181]
	v_cmp_lt_i32_e32 vcc, v64, v65
	v_readlane_b32 s52, v243, 11
	v_readlane_b32 s53, v243, 12
	v_cndmask_b32_e32 v64, v204, v64, vcc
	v_cmp_lt_i32_e32 vcc, v66, v65
	v_lshl_add_u64 v[92:93], s[52:53], 0, v[182:183]
	v_readlane_b32 s54, v243, 13
	v_cndmask_b32_e32 v65, v204, v66, vcc
	v_add_co_u32_e32 v94, vcc, 0x5000, v92
	v_readlane_b32 s55, v243, 14
	s_nop 0
	v_addc_co_u32_e32 v95, vcc, 0, v93, vcc
	v_add_co_u32_e32 v96, vcc, 0xb000, v92
	v_lshl_add_u64 v[72:73], s[54:55], 0, v[182:183]
	v_lshl_add_u64 v[74:75], v[92:93], 0, s[26:27]
	v_lshl_add_u64 v[76:77], v[92:93], 0, s[28:29]
	v_addc_co_u32_e32 v97, vcc, 0, v93, vcc
	v_lshlrev_b32_e32 v187, 2, v64
	v_lshlrev_b32_e32 v185, 2, v65
	global_load_dwordx4 v[64:67], v[92:93], off offset:16
	global_load_dwordx4 v[80:83], v[92:93], off
	global_load_dwordx4 v[68:71], v[72:73], off offset:16
	global_load_dwordx4 v[84:87], v[72:73], off
	s_nop 0
	global_load_dwordx4 v[72:75], v[74:75], off offset:16
	s_nop 0
	global_load_dwordx4 v[76:79], v[76:77], off offset:16
	s_nop 0
	global_load_dwordx4 v[92:95], v[94:95], off offset:2048
	s_nop 0
	global_load_dwordx4 v[96:99], v[96:97], off
	v_mov_b32_e32 v211, 0
	v_mov_b32_e32 v205, 0
	v_readlane_b32 s45, v243, 4
	v_readlane_b32 s46, v243, 5
	v_readlane_b32 s47, v243, 6
	v_readlane_b32 s48, v243, 7
	v_readlane_b32 s49, v243, 8
	v_readlane_b32 s50, v243, 9
	v_readlane_b32 s51, v243, 10
	v_readlane_b32 s56, v243, 15
	v_readlane_b32 s57, v243, 16
	v_readlane_b32 s58, v243, 17
	v_readlane_b32 s59, v243, 18
	s_waitcnt vmcnt(0)
	v_mov_b32_e32 v196, v192
	v_mov_b32_e32 v197, v206
	v_mov_b32_e32 v206, v193
	v_mov_b32_e32 v192, v194
	v_mov_b32_e32 v193, v208
	v_mov_b32_e32 v208, v195
	v_pk_add_f32 v[194:195], v[196:197], v[206:207]
	v_pk_add_f32 v[192:193], v[192:193], v[208:209]
	v_mov_b32_e32 v196, v212
	v_mov_b32_e32 v197, v216
	v_mov_b32_e32 v216, v213
	v_mov_b32_e32 v206, v214
	v_mov_b32_e32 v207, v218
	v_mov_b32_e32 v218, v215
	v_pk_add_f32 v[192:193], v[194:195], v[192:193]
	v_pk_add_f32 v[194:195], v[196:197], v[216:217]
	v_pk_add_f32 v[196:197], v[206:207], v[218:219]
	v_mov_b32_e32 v208, v220
	v_pk_add_f32 v[194:195], v[194:195], v[196:197]
	v_mov_b32_e32 v197, v192
	v_mov_b32_e32 v196, v194
	v_mov_b32_e32 v192, v195
	v_pk_add_f32 v[192:193], v[196:197], v[192:193]
	ds_bpermute_b32 v195, v187, v193
	ds_bpermute_b32 v194, v187, v192
	v_mov_b32_e32 v209, v224
	v_mov_b32_e32 v224, v221
	v_mov_b32_e32 v212, v222
	v_mov_b32_e32 v213, v226
	s_waitcnt lgkmcnt(0)
; DI unsigned pack2(float lo, float hi) { f32x2 v = {lo, hi}; bf16v2 r = __builtin_convertvector(v, bf16v2); return __builtin_bit_cast(unsigned, r); }
; DI float silu_f(float x) { return x * sigmoid_f(x); }
; DI float dpp_ror1(float v) { return __int_as_float(__builtin_amdgcn_update_dpp(0, __float_as_int(v), 0x121, 0xf, 0xf, false)); }
; DI float dpp_ror2(float v) { return __int_as_float(__builtin_amdgcn_update_dpp(0, __float_as_int(v), 0x122, 0xf, 0xf, false)); }
;   DI void operator()(const f32x4 (&acc)[2][2][4][2], const Unit& u, int wr, int wc, int fr, int fq) const {
;     ...
;       for (int m = 0; m < 4; ++m) rsv[m] = row_rstd(ssq, row0 + 16 * m + fr, fq);
;       float p1[8], p2[8];
; #pragma unroll
;       for (int e = 0; e < 8; ++e) { p1[e] = 0.f; p2[e] = 0.f; }
; #pragma unroll
;       for (int m = 0; m < 4; ++m) {
;         float g[8], uu[8], a[8];
;         const float rs = rsv[m];
; #pragma unroll
;         for (int e = 0; e < 4; ++e) { g[e] = acc[ai][0][m][0][e] * rs; g[4 + e] = acc[ai][0][m][1][e] * rs; uu[e] = acc[ai][1][m][0][e] * rs; uu[4 + e] = acc[ai][1][m][1][e] * rs; }
; #pragma unroll
;         for (int e = 0; e < 8; ++e) {
;           const float x1 = dpp_ror1(g[e]), x2 = dpp_ror2(g[e]);
;           const float pr1 = (fr == 0) ? p1[e] : x1, pr2 = (fr < 2) ? p2[e] : x2;
;           a[e] = w2[e] * g[e] + w1[e] * pr1 + w0[e] * pr2 + bb[e];
;           p1[e] = x1; p2[e] = x2;
;         }
;         if (m == 0 && fr < 2) {
;           float* ha = headA + (size_t)(span * 2 + fr) * 5632 + col; float* hu = headU + (size_t)(span * 2 + fr) * 5632 + col;
;           *(f32x4*)ha = (f32x4){a[0], a[1], a[2], a[3]}; *(f32x4*)(ha + 4) = (f32x4){a[4], a[5], a[6], a[7]};
;           *(f32x4*)hu = (f32x4){uu[0], uu[1], uu[2], uu[3]}; *(f32x4*)(hu + 4) = (f32x4){uu[4], uu[5], uu[6], uu[7]};
;         } else {
;           u32x4 w;
;           w.x = pack2(silu_f(a[0]) * uu[0], silu_f(a[1]) * uu[1]);
;           w.y = pack2(silu_f(a[2]) * uu[2], silu_f(a[3]) * uu[3]);
;           w.z = pack2(silu_f(a[4]) * uu[4], silu_f(a[5]) * uu[5]);
;           w.w = pack2(silu_f(a[6]) * uu[6], silu_f(a[7]) * uu[7]);
;           *(u32x4*)(H + (size_t)(row0 + 16 * m + fr) * 5632 + col) = w;
	v_pk_add_f32 v[192:193], v[192:193], v[194:195]
	ds_bpermute_b32 v195, v185, v193
	ds_bpermute_b32 v194, v185, v192
	v_mov_b32_e32 v226, v223
	v_mov_b32_e32 v196, v228
	v_mov_b32_e32 v197, v232
	v_mov_b32_e32 v232, v229
	s_waitcnt lgkmcnt(0)
	v_pk_add_f32 v[192:193], v[192:193], v[194:195]
	v_mov_b32_e32 v206, v230
	v_pk_fma_f32 v[192:193], v[192:193], s[30:31], v[178:179] op_sel_hi:[1,0,0]
	v_mov_b32_e32 v207, v234
	v_mul_f32_e32 v189, 0x4b800000, v193
	v_cmp_gt_f32_e64 s[12:13], s74, v193
	v_mov_b32_e32 v234, v231
	v_pk_add_f32 v[208:209], v[208:209], v[224:225]
	v_cndmask_b32_e64 v189, v193, v189, s[12:13]
	v_rsq_f32_e32 v189, v189
	v_pk_add_f32 v[212:213], v[212:213], v[226:227]
	v_pk_add_f32 v[196:197], v[196:197], v[232:233]
	v_pk_add_f32 v[194:195], v[206:207], v[234:235]
	v_mul_f32_e32 v191, 0x45800000, v189
	v_cndmask_b32_e64 v220, v189, v191, s[12:13]
	v_pk_add_f32 v[208:209], v[208:209], v[212:213]
	v_pk_add_f32 v[194:195], v[196:197], v[194:195]
	v_pk_mul_f32 v[156:157], v[156:157], v[220:221] op_sel_hi:[1,0]
	v_mov_b32_e32 v216, 0
	v_mov_b32_e32 v218, 0
	v_mov_b32_e32 v196, v194
	v_mov_b32_e32 v197, v208
	v_mov_b32_e32 v208, v195
	v_mov_b32_dpp v216, v156 row_ror:1 row_mask:0xf bank_mask:0xf
	v_mov_b32_dpp v218, v157 row_ror:1 row_mask:0xf bank_mask:0xf
	v_pk_add_f32 v[194:195], v[196:197], v[208:209]
	v_cndmask_b32_e64 v207, v218, 0, s[0:1]
	v_cndmask_b32_e64 v206, v216, 0, s[0:1]
	v_pk_mul_f32 v[158:159], v[158:159], v[220:221] op_sel_hi:[1,0]
	v_mov_b32_e32 v212, 0
	v_mov_b32_e32 v214, 0
	ds_bpermute_b32 v197, v187, v195
	ds_bpermute_b32 v196, v187, v194
	v_mov_b32_e32 v215, 0
	v_mov_b32_e32 v217, 0
	v_pk_mul_f32 v[206:207], v[92:93], v[206:207]
	v_mov_b32_dpp v212, v158 row_ror:1 row_mask:0xf bank_mask:0xf
	v_mov_b32_dpp v214, v159 row_ror:1 row_mask:0xf bank_mask:0xf
	v_mov_b32_dpp v215, v156 row_ror:2 row_mask:0xf bank_mask:0xf
	v_mov_b32_dpp v217, v157 row_ror:2 row_mask:0xf bank_mask:0xf
	v_pk_fma_f32 v[156:157], v[96:97], v[156:157], v[206:207]
	v_mov_b32_e32 v213, 0
	v_cndmask_b32_e64 v207, v214, 0, s[0:1]
	v_cndmask_b32_e64 v206, v212, 0, s[0:1]
	v_cndmask_b32_e64 v209, v217, 0, s[4:5]
	v_cndmask_b32_e64 v208, v215, 0, s[4:5]
	v_mov_b32_dpp v211, v158 row_ror:2 row_mask:0xf bank_mask:0xf
	v_mov_b32_dpp v213, v159 row_ror:2 row_mask:0xf bank_mask:0xf
	v_pk_mul_f32 v[206:207], v[94:95], v[206:207]
	v_pk_fma_f32 v[156:157], v[80:81], v[208:209], v[156:157]
	v_cndmask_b32_e64 v209, v213, 0, s[4:5]
	v_cndmask_b32_e64 v208, v211, 0, s[4:5]
	v_pk_fma_f32 v[158:159], v[98:99], v[158:159], v[206:207]
	v_pk_mul_f32 v[144:145], v[144:145], v[220:221] op_sel_hi:[1,0]
	v_pk_fma_f32 v[158:159], v[82:83], v[208:209], v[158:159]
	v_mov_b32_e32 v207, 0
	v_mov_b32_e32 v209, 0
	v_pk_mul_f32 v[146:147], v[146:147], v[220:221] op_sel_hi:[1,0]
	v_mov_b32_e32 v191, 0
	s_waitcnt lgkmcnt(0)
	v_pk_add_f32 v[194:195], v[194:195], v[196:197]
	v_mov_b32_dpp v207, v144 row_ror:1 row_mask:0xf bank_mask:0xf
	v_mov_b32_dpp v209, v145 row_ror:1 row_mask:0xf bank_mask:0xf
	v_mov_b32_dpp v191, v146 row_ror:1 row_mask:0xf bank_mask:0xf
	v_mov_b32_dpp v205, v147 row_ror:1 row_mask:0xf bank_mask:0xf
	ds_bpermute_b32 v197, v185, v195
	ds_bpermute_b32 v196, v185, v194
	v_pk_mul_f32 v[152:153], v[152:153], v[220:221] op_sel_hi:[1,0]
	v_pk_mul_f32 v[148:149], v[148:149], v[220:221] op_sel_hi:[1,0]
	v_pk_mul_f32 v[154:155], v[154:155], v[220:221] op_sel_hi:[1,0]
	v_pk_mul_f32 v[150:151], v[150:151], v[220:221] op_sel_hi:[1,0]
	v_mov_b32_e32 v206, 0
	v_mov_b32_e32 v208, 0
	v_cndmask_b32_e64 v223, v209, 0, s[0:1]
	v_cndmask_b32_e64 v222, v207, 0, s[0:1]
	v_mov_b32_e32 v189, 0
	v_mov_b32_e32 v193, 0
	v_cndmask_b32_e64 v221, v205, 0, s[0:1]
	v_cndmask_b32_e64 v220, v191, 0, s[0:1]
	v_mov_b32_dpp v206, v144 row_ror:2 row_mask:0xf bank_mask:0xf
	v_mov_b32_dpp v208, v145 row_ror:2 row_mask:0xf bank_mask:0xf
	v_pk_mul_f32 v[222:223], v[72:73], v[222:223]
	v_mov_b32_dpp v189, v146 row_ror:2 row_mask:0xf bank_mask:0xf
	v_mov_b32_dpp v193, v147 row_ror:2 row_mask:0xf bank_mask:0xf
	v_pk_mul_f32 v[220:221], v[74:75], v[220:221]
	v_cndmask_b32_e64 v225, v208, 0, s[4:5]
	v_cndmask_b32_e64 v224, v206, 0, s[4:5]
	v_pk_fma_f32 v[144:145], v[76:77], v[144:145], v[222:223]
	v_cndmask_b32_e64 v223, v193, 0, s[4:5]
	v_cndmask_b32_e64 v222, v189, 0, s[4:5]
	v_pk_fma_f32 v[146:147], v[78:79], v[146:147], v[220:221]
	v_pk_fma_f32 v[144:145], v[64:65], v[224:225], v[144:145]
	v_pk_fma_f32 v[146:147], v[66:67], v[222:223], v[146:147]
	v_cmp_gt_f32_e32 vcc, s74, v192
	v_pk_add_f32 v[156:157], v[84:85], v[156:157]
	v_pk_add_f32 v[158:159], v[86:87], v[158:159]
	v_pk_add_f32 v[144:145], v[68:69], v[144:145]
	v_pk_add_f32 v[146:147], v[70:71], v[146:147]
	s_and_saveexec_b64 s[12:13], s[10:11]
	s_xor_b64 s[12:13], exec, s[12:13]
	s_cbranch_execz .LBB0_814
	v_mul_f32_e32 v219, 0xbfb8aa3b, v156
	v_exp_f32_e32 v219, v219
	v_mul_f32_e32 v220, 0xbfb8aa3b, v157
	v_exp_f32_e32 v220, v220
	v_mul_f32_e32 v222, 0xbfb8aa3b, v159
	v_add_f32_e32 v219, 1.0, v219
	v_exp_f32_e32 v223, v222
	v_add_f32_e32 v221, 1.0, v220
	v_rcp_f32_e32 v220, v219
	v_mul_f32_e32 v219, 0xbfb8aa3b, v158
	v_exp_f32_e32 v219, v219
	v_rcp_f32_e32 v221, v221
	v_add_f32_e32 v219, 1.0, v219
	v_rcp_f32_e32 v222, v219
	v_add_f32_e32 v219, 1.0, v223
	v_rcp_f32_e32 v223, v219
	v_pk_mul_f32 v[156:157], v[156:157], v[220:221]
	s_nop 0
	v_pk_mul_f32 v[152:153], v[152:153], v[156:157]
	v_pk_mul_f32 v[156:157], v[158:159], v[222:223]
	v_cvt_pk_bf16_f32 v152, v152, v153
	v_mul_f32_e32 v153, 0xbfb8aa3b, v144
	v_pk_mul_f32 v[154:155], v[154:155], v[156:157]
	v_exp_f32_e32 v156, v153
	v_mul_f32_e32 v153, 0xbfb8aa3b, v145
	v_exp_f32_e32 v157, v153
	v_cvt_pk_bf16_f32 v153, v154, v155
	v_add_f32_e32 v154, 1.0, v156
	v_mul_f32_e32 v156, 0xbfb8aa3b, v146
	v_add_f32_e32 v155, 1.0, v157
	v_mul_f32_e32 v157, 0xbfb8aa3b, v147
	v_exp_f32_e32 v156, v156
	v_exp_f32_e32 v157, v157
	v_rcp_f32_e32 v154, v154
	v_rcp_f32_e32 v155, v155
	v_add_f32_e32 v156, 1.0, v156
	v_add_f32_e32 v157, 1.0, v157
	v_rcp_f32_e32 v156, v156
	v_rcp_f32_e32 v157, v157
	v_pk_mul_f32 v[144:145], v[144:145], v[154:155]
	s_nop 0
	v_pk_mul_f32 v[144:145], v[148:149], v[144:145]
	s_nop 0
	v_cvt_pk_bf16_f32 v154, v144, v145
	v_pk_mul_f32 v[144:145], v[146:147], v[156:157]
	s_nop 0
	v_pk_mul_f32 v[144:145], v[150:151], v[144:145]
	s_nop 0
	v_cvt_pk_bf16_f32 v155, v144, v145
	v_mov_b64_e32 v[144:145], s[16:17]
	v_mad_i64_i32 v[144:145], s[14:15], v190, s75, v[144:145]
	v_lshl_add_u64 v[144:145], v[180:181], 1, v[144:145]
	global_store_dwordx4 v[144:145], v[152:155], off

; #define PG8_STAGE(bufoff, gbase, voff) do { _Pragma("unroll") for (int _i = 0; _i < 2; ++_i) \
;     __builtin_amdgcn_global_load_lds((const unsigned*)((const char*)(gbase) + (voff)[_i]), (LAS unsigned*)(lds + (bufoff) + ldsw + _i * 8192), 16, 0, 0); } while (0)
; #define PG8_LDA(dst, b, h) do { _Pragma("unroll") for (int m = 0; m < 4; ++m) _Pragma("unroll") for (int k = 0; k < 2; ++k) dst[m][k] = *(const LAS bf16x8*)(lds + PG8_SA(b, h) + aoff + m * 2048 + k * 1024); } while (0)
; #define PG8_LDB(dst, b, h) do { _Pragma("unroll") for (int n = 0; n < 2; ++n) _Pragma("unroll") for (int k = 0; k < 2; ++k) dst[n][k] = *(const LAS bf16x8*)(lds + PG8_SB(b, h) + boff + n * 2048 + k * 1024); } while (0)
; #define PG8_MMA(ai, bj, At, Bt) do { __builtin_amdgcn_s_setprio(1); _Pragma("unroll") for (int m = 0; m < 4; ++m) _Pragma("unroll") for (int n = 0; n < 2; ++n) _Pragma("unroll") for (int k = 0; k < 2; ++k) \
;     acc[ai][bj][m][n] = __builtin_amdgcn_mfma_f32_16x16x32_bf16(Bt[n][k], At[m][k], acc[ai][bj][m][n], 0, 0, 0); __builtin_amdgcn_s_setprio(0); } while (0)
; #define PG8_WAIT_V(n) asm volatile("s_waitcnt vmcnt(" #n ")" ::: "memory")
; #define PG8_WAIT_L(n) asm volatile("s_waitcnt lgkmcnt(" #n ")" ::: "memory")
; template <class Epi, class Sched = StaticOrder>
; DI void gemm_phase(LAS unsigned char* lds, const Gemm g, const Sched& S, const Epi& E) {
;     ...
;     for (int t = 0; t < nt; t += 2) {
;       const bool last = (t == nt - 2);
;       const char* a1 = cA + (size_t)(t + 1) * kstep;
;       const char* a2 = last ? nA : cA + (size_t)(t + 2) * kstep; const char* b2 = last ? nB : cB + (size_t)(t + 2) * kstep;
;       const char* a3 = a2 + kstep; const char* b3 = b2 + kstep;
;       PG8_LDB(B0, 0, 0); PG8_SCHED; PG8_LDA(At, 0, 0); PG8_STAGE(PG8_SA(1, 1), a1 + hstep, voffA);
;       PG8_WAIT_L(8); PG8_BAR; PG8_WAIT_L(0); PG8_MMA(0, 0, At, B0); PG8_BAR; PG8_SCHED;
;       PG8_LDB(B1, 0, 1); PG8_STAGE(PG8_SB(0, 0), b2, voffB);
;       PG8_BAR; PG8_WAIT_L(0); PG8_MMA(0, 1, At, B1); PG8_BAR;
;       PG8_LDA(At, 0, 1); PG8_STAGE(PG8_SA(0, 0), a2, voffA);
;       PG8_BAR; PG8_WAIT_L(0); PG8_MMA(1, 0, At, B0); PG8_BAR; PG8_SCHED;
;       PG8_STAGE(PG8_SB(0, 1), b2 + hstep, voffB);
;       PG8_WAIT_V(6); PG8_BAR; PG8_MMA(1, 1, At, B1); PG8_BAR;
;       PG8_LDB(B0, 1, 0); PG8_SCHED; PG8_LDA(At, 1, 0); PG8_STAGE(PG8_SA(0, 1), a2 + hstep, voffA);
.LBB0_961:
	s_add_u32 s20, s18, 0xffea0080
	s_addc_u32 s21, s19, -1
	s_cmpk_eq_i32 s44, 0x54
	s_cselect_b32 s23, s5, s21
	s_cselect_b32 s22, s4, s20
	s_cselect_b32 s21, s7, s43
	s_cselect_b32 s20, s6, s42
	s_add_i32 m0, s31, 0xc000
	ds_read_b128 v[144:147], v215
	ds_read_b128 v[152:155], v215 offset:2048
	ds_read_b128 v[160:163], v215 offset:4096
	ds_read_b128 v[168:171], v215 offset:6144
	ds_read_b128 v[148:151], v215 offset:1024
	ds_read_b128 v[156:159], v215 offset:3072
	ds_read_b128 v[164:167], v215 offset:5120
	ds_read_b128 v[172:175], v215 offset:7168
	global_load_lds_dwordx4 v184, s[18:19]
	s_add_i32 m0, s31, 0xe000
	s_nop 0
	global_load_lds_dwordx4 v186, s[18:19]
	s_waitcnt lgkmcnt(8)
	s_setprio 1
	s_barrier
	s_waitcnt lgkmcnt(4)
	v_mfma_f32_16x16x32_bf16 v[124:127], v[128:131], v[144:147], v[124:127]
	v_mfma_f32_16x16x32_bf16 v[120:123], v[136:139], v[144:147], v[120:123]
	v_mfma_f32_16x16x32_bf16 v[108:111], v[128:131], v[152:155], v[108:111]
	v_mfma_f32_16x16x32_bf16 v[104:107], v[136:139], v[152:155], v[104:107]
	v_mfma_f32_16x16x32_bf16 v[92:95], v[128:131], v[160:163], v[92:95]
	v_mfma_f32_16x16x32_bf16 v[88:91], v[136:139], v[160:163], v[88:91]
	v_mfma_f32_16x16x32_bf16 v[76:79], v[128:131], v[168:171], v[76:79]
	v_mfma_f32_16x16x32_bf16 v[72:75], v[136:139], v[168:171], v[72:75]
	s_waitcnt lgkmcnt(0)
	v_mfma_f32_16x16x32_bf16 v[124:127], v[132:135], v[148:151], v[124:127]
	v_mfma_f32_16x16x32_bf16 v[120:123], v[140:143], v[148:151], v[120:123]
	v_mfma_f32_16x16x32_bf16 v[108:111], v[132:135], v[156:159], v[108:111]
	v_mfma_f32_16x16x32_bf16 v[104:107], v[140:143], v[156:159], v[104:107]
	v_mfma_f32_16x16x32_bf16 v[92:95], v[132:135], v[164:167], v[92:95]
	v_mfma_f32_16x16x32_bf16 v[88:91], v[140:143], v[164:167], v[88:91]
	v_mfma_f32_16x16x32_bf16 v[76:79], v[132:135], v[172:175], v[76:79]
	v_mfma_f32_16x16x32_bf16 v[72:75], v[140:143], v[172:175], v[72:75]
	s_barrier
	s_setprio 0
	s_add_i32 s45, s46, s30
	s_add_u32 s98, s20, 0x80
	s_addc_u32 s99, s21, 0
	s_add_u32 s100, s22, 0x80
	s_addc_u32 s101, s23, 0
	s_mov_b32 m0, s45
	ds_read_b128 v[192:195], v216
	ds_read_b128 v[196:199], v216 offset:1024
	ds_read_b128 v[200:203], v216 offset:2048
	ds_read_b128 v[204:207], v216 offset:3072
	global_load_lds_dwordx4 v178, s[20:21]
	s_add_i32 m0, s45, 0x2000
	s_nop 0
	global_load_lds_dwordx4 v182, s[20:21]
	s_setprio 1
	s_barrier
	s_waitcnt lgkmcnt(0)
	v_mfma_f32_16x16x32_bf16 v[116:119], v[192:195], v[144:147], v[116:119]
	v_mfma_f32_16x16x32_bf16 v[112:115], v[200:203], v[144:147], v[112:115]
	v_mfma_f32_16x16x32_bf16 v[100:103], v[192:195], v[152:155], v[100:103]
	v_mfma_f32_16x16x32_bf16 v[96:99], v[200:203], v[152:155], v[96:99]
	v_mfma_f32_16x16x32_bf16 v[84:87], v[192:195], v[160:163], v[84:87]
	v_mfma_f32_16x16x32_bf16 v[80:83], v[200:203], v[160:163], v[80:83]
	v_mfma_f32_16x16x32_bf16 v[68:71], v[192:195], v[168:171], v[68:71]
	v_mfma_f32_16x16x32_bf16 v[64:67], v[200:203], v[168:171], v[64:67]
	v_mfma_f32_16x16x32_bf16 v[116:119], v[196:199], v[148:151], v[116:119]
	v_mfma_f32_16x16x32_bf16 v[112:115], v[204:207], v[148:151], v[112:115]
	v_mfma_f32_16x16x32_bf16 v[100:103], v[196:199], v[156:159], v[100:103]
	v_mfma_f32_16x16x32_bf16 v[96:99], v[204:207], v[156:159], v[96:99]
	v_mfma_f32_16x16x32_bf16 v[84:87], v[196:199], v[164:167], v[84:87]
	v_mfma_f32_16x16x32_bf16 v[80:83], v[204:207], v[164:167], v[80:83]
	v_mfma_f32_16x16x32_bf16 v[68:71], v[196:199], v[172:175], v[68:71]
	v_mfma_f32_16x16x32_bf16 v[64:67], v[204:207], v[172:175], v[64:67]
	s_barrier
	s_setprio 0
	s_mov_b32 m0, s31
	ds_read_b128 v[144:147], v215 offset:16384
	ds_read_b128 v[152:155], v215 offset:18432
	ds_read_b128 v[160:163], v215 offset:20480
	ds_read_b128 v[168:171], v215 offset:22528
	ds_read_b128 v[148:151], v215 offset:17408
	ds_read_b128 v[156:159], v215 offset:19456
	ds_read_b128 v[164:167], v215 offset:21504
	ds_read_b128 v[172:175], v215 offset:23552
	global_load_lds_dwordx4 v176, s[22:23]
	s_mov_b32 m0, s33
	s_nop 0
	global_load_lds_dwordx4 v180, s[22:23]
	s_waitcnt vmcnt(10)
	s_setprio 1
	s_barrier
	s_waitcnt lgkmcnt(4)
	v_mfma_f32_16x16x32_bf16 v[60:63], v[128:131], v[144:147], v[60:63]
	v_mfma_f32_16x16x32_bf16 v[56:59], v[136:139], v[144:147], v[56:59]
	v_mfma_f32_16x16x32_bf16 v[44:47], v[128:131], v[152:155], v[44:47]
	v_mfma_f32_16x16x32_bf16 v[40:43], v[136:139], v[152:155], v[40:43]
	v_mfma_f32_16x16x32_bf16 v[28:31], v[128:131], v[160:163], v[28:31]
	v_mfma_f32_16x16x32_bf16 v[24:27], v[136:139], v[160:163], v[24:27]
	v_mfma_f32_16x16x32_bf16 v[12:15], v[128:131], v[168:171], v[12:15]
	v_mfma_f32_16x16x32_bf16 v[8:11], v[136:139], v[168:171], v[8:11]
	s_waitcnt lgkmcnt(0)
	v_mfma_f32_16x16x32_bf16 v[60:63], v[132:135], v[148:151], v[60:63]
	v_mfma_f32_16x16x32_bf16 v[56:59], v[140:143], v[148:151], v[56:59]
	v_mfma_f32_16x16x32_bf16 v[44:47], v[132:135], v[156:159], v[44:47]
	v_mfma_f32_16x16x32_bf16 v[40:43], v[140:143], v[156:159], v[40:43]
	v_mfma_f32_16x16x32_bf16 v[28:31], v[132:135], v[164:167], v[28:31]
	v_mfma_f32_16x16x32_bf16 v[24:27], v[140:143], v[164:167], v[24:27]
	v_mfma_f32_16x16x32_bf16 v[12:15], v[132:135], v[172:175], v[12:15]
	v_mfma_f32_16x16x32_bf16 v[8:11], v[140:143], v[172:175], v[8:11]
	s_barrier
	s_setprio 0
	s_add_u32 s52, s20, 0x160000
	s_addc_u32 s53, s21, 0
	s_add_i32 s45, s47, s30
	s_mov_b32 m0, s45
	s_nop 0
	global_load_lds_dwordx4 v178, s[52:53]
	s_add_i32 m0, s45, 0x2000
	s_nop 0
	global_load_lds_dwordx4 v182, s[52:53]
	s_add_i32 s45, 0, 0x18000
	v_add_u32_e32 v140, s45, v212
	ds_read_b128 v[128:131], v140
	ds_read_b128 v[132:135], v140 offset:1024
	ds_read_b128 v[136:139], v140 offset:2048
	ds_read_b128 v[140:143], v140 offset:3072
	s_waitcnt vmcnt(6)
	s_setprio 1
	s_barrier
; #define PG8_STAGE(bufoff, gbase, voff) do { _Pragma("unroll") for (int _i = 0; _i < 2; ++_i) \
;     __builtin_amdgcn_global_load_lds((const unsigned*)((const char*)(gbase) + (voff)[_i]), (LAS unsigned*)(lds + (bufoff) + ldsw + _i * 8192), 16, 0, 0); } while (0)
; #define PG8_LDA(dst, b, h) do { _Pragma("unroll") for (int m = 0; m < 4; ++m) _Pragma("unroll") for (int k = 0; k < 2; ++k) dst[m][k] = *(const LAS bf16x8*)(lds + PG8_SA(b, h) + aoff + m * 2048 + k * 1024); } while (0)
; #define PG8_LDB(dst, b, h) do { _Pragma("unroll") for (int n = 0; n < 2; ++n) _Pragma("unroll") for (int k = 0; k < 2; ++k) dst[n][k] = *(const LAS bf16x8*)(lds + PG8_SB(b, h) + boff + n * 2048 + k * 1024); } while (0)
; #define PG8_MMA(ai, bj, At, Bt) do { __builtin_amdgcn_s_setprio(1); _Pragma("unroll") for (int m = 0; m < 4; ++m) _Pragma("unroll") for (int n = 0; n < 2; ++n) _Pragma("unroll") for (int k = 0; k < 2; ++k) \
;     acc[ai][bj][m][n] = __builtin_amdgcn_mfma_f32_16x16x32_bf16(Bt[n][k], At[m][k], acc[ai][bj][m][n], 0, 0, 0); __builtin_amdgcn_s_setprio(0); } while (0)
; #define PG8_WAIT_V(n) asm volatile("s_waitcnt vmcnt(" #n ")" ::: "memory")
; #define PG8_WAIT_L(n) asm volatile("s_waitcnt lgkmcnt(" #n ")" ::: "memory")
; #define PG8_BAR __builtin_amdgcn_s_barrier()
; #define PG8_SCHED __builtin_amdgcn_sched_barrier(0)
; template <class Epi, class Sched = StaticOrder>
; DI void gemm_phase(LAS unsigned char* lds, const Gemm g, const Sched& S, const Epi& E) {
;     ...
;       PG8_WAIT_V(6); PG8_BAR; PG8_MMA(1, 1, At, B1); PG8_BAR;
;       PG8_LDB(B0, 1, 0); PG8_SCHED; PG8_LDA(At, 1, 0); PG8_STAGE(PG8_SA(0, 1), a2 + hstep, voffA);
;       PG8_WAIT_L(8); PG8_BAR; PG8_WAIT_L(0); PG8_MMA(0, 0, At, B0); PG8_BAR; PG8_SCHED;
;       PG8_LDB(B1, 1, 1); PG8_STAGE(PG8_SB(1, 0), b3, voffB);
;       PG8_BAR; PG8_WAIT_L(0); PG8_MMA(0, 1, At, B1); PG8_BAR;
;       PG8_LDA(At, 1, 1); PG8_STAGE(PG8_SA(1, 0), a3, voffA);
;       PG8_BAR; PG8_WAIT_L(0); PG8_MMA(1, 0, At, B0); PG8_BAR; PG8_SCHED;
	v_mfma_f32_16x16x32_bf16 v[52:55], v[192:195], v[144:147], v[52:55]
	v_mfma_f32_16x16x32_bf16 v[48:51], v[200:203], v[144:147], v[48:51]
	v_mfma_f32_16x16x32_bf16 v[36:39], v[192:195], v[152:155], v[36:39]
	v_mfma_f32_16x16x32_bf16 v[32:35], v[200:203], v[152:155], v[32:35]
	v_mfma_f32_16x16x32_bf16 v[20:23], v[192:195], v[160:163], v[20:23]
	v_mfma_f32_16x16x32_bf16 v[16:19], v[200:203], v[160:163], v[16:19]
	v_mfma_f32_16x16x32_bf16 v[4:7], v[192:195], v[168:171], v[4:7]
	v_mfma_f32_16x16x32_bf16 v[0:3], v[200:203], v[168:171], v[0:3]
	v_mfma_f32_16x16x32_bf16 v[52:55], v[196:199], v[148:151], v[52:55]
	v_mfma_f32_16x16x32_bf16 v[48:51], v[204:207], v[148:151], v[48:51]
	v_mfma_f32_16x16x32_bf16 v[36:39], v[196:199], v[156:159], v[36:39]
	v_mfma_f32_16x16x32_bf16 v[32:35], v[204:207], v[156:159], v[32:35]
	v_mfma_f32_16x16x32_bf16 v[20:23], v[196:199], v[164:167], v[20:23]
	v_mfma_f32_16x16x32_bf16 v[16:19], v[204:207], v[164:167], v[16:19]
	v_mfma_f32_16x16x32_bf16 v[4:7], v[196:199], v[172:175], v[4:7]
	v_mfma_f32_16x16x32_bf16 v[0:3], v[204:207], v[172:175], v[0:3]
	s_barrier
	s_setprio 0
	s_add_u32 s22, s22, 0x160000
	s_addc_u32 s23, s23, 0
	s_mov_b32 m0, s34
	ds_read_b128 v[144:147], v215 offset:32768
	ds_read_b128 v[152:155], v215 offset:34816
	ds_read_b128 v[160:163], v215 offset:36864
	ds_read_b128 v[168:171], v215 offset:38912
	ds_read_b128 v[148:151], v215 offset:33792
	ds_read_b128 v[156:159], v215 offset:35840
	ds_read_b128 v[164:167], v215 offset:37888
	ds_read_b128 v[172:175], v215 offset:39936
	global_load_lds_dwordx4 v176, s[22:23]
	s_mov_b32 m0, s35
	s_nop 0
	global_load_lds_dwordx4 v180, s[22:23]
	s_waitcnt lgkmcnt(8)
	s_setprio 1
	s_barrier
	s_waitcnt lgkmcnt(4)
	v_mfma_f32_16x16x32_bf16 v[124:127], v[128:131], v[144:147], v[124:127]
	v_mfma_f32_16x16x32_bf16 v[120:123], v[136:139], v[144:147], v[120:123]
	v_mfma_f32_16x16x32_bf16 v[108:111], v[128:131], v[152:155], v[108:111]
	v_mfma_f32_16x16x32_bf16 v[104:107], v[136:139], v[152:155], v[104:107]
	v_mfma_f32_16x16x32_bf16 v[92:95], v[128:131], v[160:163], v[92:95]
	v_mfma_f32_16x16x32_bf16 v[88:91], v[136:139], v[160:163], v[88:91]
	v_mfma_f32_16x16x32_bf16 v[76:79], v[128:131], v[168:171], v[76:79]
	v_mfma_f32_16x16x32_bf16 v[72:75], v[136:139], v[168:171], v[72:75]
	s_waitcnt lgkmcnt(0)
	v_mfma_f32_16x16x32_bf16 v[124:127], v[132:135], v[148:151], v[124:127]
	v_mfma_f32_16x16x32_bf16 v[120:123], v[140:143], v[148:151], v[120:123]
	v_mfma_f32_16x16x32_bf16 v[108:111], v[132:135], v[156:159], v[108:111]
	v_mfma_f32_16x16x32_bf16 v[104:107], v[140:143], v[156:159], v[104:107]
	v_mfma_f32_16x16x32_bf16 v[92:95], v[132:135], v[164:167], v[92:95]
	v_mfma_f32_16x16x32_bf16 v[88:91], v[140:143], v[164:167], v[88:91]
	v_mfma_f32_16x16x32_bf16 v[76:79], v[132:135], v[172:175], v[76:79]
	v_mfma_f32_16x16x32_bf16 v[72:75], v[140:143], v[172:175], v[72:75]
	s_barrier
	s_setprio 0
	s_add_i32 s22, 0, 0x1c000
	s_add_i32 s23, s45, s30
	v_add_u32_e32 v204, s22, v212
	s_mov_b32 m0, s23
	ds_read_b128 v[192:195], v204
	ds_read_b128 v[196:199], v204 offset:1024
	ds_read_b128 v[200:203], v204 offset:2048
	ds_read_b128 v[204:207], v204 offset:3072
	global_load_lds_dwordx4 v178, s[98:99]
	s_add_i32 m0, s23, 0x2000
	s_nop 0
	global_load_lds_dwordx4 v182, s[98:99]
	s_setprio 1
	s_barrier
	s_waitcnt lgkmcnt(0)
	v_mfma_f32_16x16x32_bf16 v[116:119], v[192:195], v[144:147], v[116:119]
	v_mfma_f32_16x16x32_bf16 v[112:115], v[200:203], v[144:147], v[112:115]
	v_mfma_f32_16x16x32_bf16 v[100:103], v[192:195], v[152:155], v[100:103]
	v_mfma_f32_16x16x32_bf16 v[96:99], v[200:203], v[152:155], v[96:99]
	v_mfma_f32_16x16x32_bf16 v[84:87], v[192:195], v[160:163], v[84:87]
	v_mfma_f32_16x16x32_bf16 v[80:83], v[200:203], v[160:163], v[80:83]
	v_mfma_f32_16x16x32_bf16 v[68:71], v[192:195], v[168:171], v[68:71]
	v_mfma_f32_16x16x32_bf16 v[64:67], v[200:203], v[168:171], v[64:67]
	v_mfma_f32_16x16x32_bf16 v[116:119], v[196:199], v[148:151], v[116:119]
	v_mfma_f32_16x16x32_bf16 v[112:115], v[204:207], v[148:151], v[112:115]
	v_mfma_f32_16x16x32_bf16 v[100:103], v[196:199], v[156:159], v[100:103]
	v_mfma_f32_16x16x32_bf16 v[96:99], v[204:207], v[156:159], v[96:99]
	v_mfma_f32_16x16x32_bf16 v[84:87], v[196:199], v[164:167], v[84:87]
	v_mfma_f32_16x16x32_bf16 v[80:83], v[204:207], v[164:167], v[80:83]
	v_mfma_f32_16x16x32_bf16 v[68:71], v[196:199], v[172:175], v[68:71]
	v_mfma_f32_16x16x32_bf16 v[64:67], v[204:207], v[172:175], v[64:67]
	s_barrier
	s_setprio 0
	s_mov_b32 m0, s37
	ds_read_b128 v[144:147], v215 offset:49152
	ds_read_b128 v[152:155], v215 offset:51200
	ds_read_b128 v[160:163], v215 offset:53248
	ds_read_b128 v[168:171], v215 offset:55296
	ds_read_b128 v[148:151], v215 offset:50176
	ds_read_b128 v[156:159], v215 offset:52224
	ds_read_b128 v[164:167], v215 offset:54272
	ds_read_b128 v[172:175], v215 offset:56320
	global_load_lds_dwordx4 v176, s[100:101]
	s_mov_b32 m0, s38
	s_nop 0
	global_load_lds_dwordx4 v180, s[100:101]
	s_waitcnt vmcnt(10)
	s_setprio 1
	s_barrier
	s_waitcnt lgkmcnt(4)
	v_mfma_f32_16x16x32_bf16 v[60:63], v[128:131], v[144:147], v[60:63]
	v_mfma_f32_16x16x32_bf16 v[56:59], v[136:139], v[144:147], v[56:59]
	v_mfma_f32_16x16x32_bf16 v[44:47], v[128:131], v[152:155], v[44:47]
	v_mfma_f32_16x16x32_bf16 v[40:43], v[136:139], v[152:155], v[40:43]
	v_mfma_f32_16x16x32_bf16 v[28:31], v[128:131], v[160:163], v[28:31]
	v_mfma_f32_16x16x32_bf16 v[24:27], v[136:139], v[160:163], v[24:27]
	v_mfma_f32_16x16x32_bf16 v[12:15], v[128:131], v[168:171], v[12:15]
	v_mfma_f32_16x16x32_bf16 v[8:11], v[136:139], v[168:171], v[8:11]
	s_waitcnt lgkmcnt(0)
	v_mfma_f32_16x16x32_bf16 v[60:63], v[132:135], v[148:151], v[60:63]
	v_mfma_f32_16x16x32_bf16 v[56:59], v[140:143], v[148:151], v[56:59]
	v_mfma_f32_16x16x32_bf16 v[44:47], v[132:135], v[156:159], v[44:47]
	v_mfma_f32_16x16x32_bf16 v[40:43], v[140:143], v[156:159], v[40:43]
	v_mfma_f32_16x16x32_bf16 v[28:31], v[132:135], v[164:167], v[28:31]
	v_mfma_f32_16x16x32_bf16 v[24:27], v[140:143], v[164:167], v[24:27]
	v_mfma_f32_16x16x32_bf16 v[12:15], v[132:135], v[172:175], v[12:15]
	v_mfma_f32_16x16x32_bf16 v[8:11], v[140:143], v[172:175], v[8:11]
	s_barrier
; DI unsigned pack2(float lo, float hi) { f32x2 v = {lo, hi}; bf16v2 r = __builtin_convertvector(v, bf16v2); return __builtin_bit_cast(unsigned, r); }
; #define PG8_STAGE(bufoff, gbase, voff) do { _Pragma("unroll") for (int _i = 0; _i < 2; ++_i) \
;     __builtin_amdgcn_global_load_lds((const unsigned*)((const char*)(gbase) + (voff)[_i]), (LAS unsigned*)(lds + (bufoff) + ldsw + _i * 8192), 16, 0, 0); } while (0)
; #define PG8_WAIT_V(n) asm volatile("s_waitcnt vmcnt(" #n ")" ::: "memory")
; #define PG8_BAR __builtin_amdgcn_s_barrier()
;   DI void operator()(const f32x4 (&acc)[2][2][4][2], const Unit& u, int wr, int wc, int fr, int fq) const {
;     const int row0 = u.pm * BM + wr * 64 + fr, col0 = u.pn * BM + wc * 32 + 8 * fq;
; #pragma unroll
;     for (int ai = 0; ai < 2; ++ai) {
;       f32x4 bv[4][2][2];
; #pragma unroll
;       for (int m = 0; m < 4; ++m)
; #pragma unroll
;         for (int bj = 0; bj < 2; ++bj) {
;           const float* bp = base + (size_t)(row0 + ai * HALF + m * 16) * 2048 + col0 + bj * HALF;
;           bv[m][bj][0] = *(const f32x4*)bp; bv[m][bj][1] = *(const f32x4*)(bp + 4);
;         }
; #pragma unroll
;       for (int m = 0; m < 4; ++m) {
;         const int row = row0 + ai * HALF + m * 16;
;         const size_t off = (size_t)row * 2048 + col0;
;         float ss = 0.f;
; #pragma unroll
;         for (int bj = 0; bj < 2; ++bj) {
;           const f32x4 v0 = acc[ai][bj][m][0] + bv[m][bj][0], v1 = acc[ai][bj][m][1] + bv[m][bj][1];
;           *(f32x4*)(C + off + bj * HALF) = v0; *(f32x4*)(C + off + bj * HALF + 4) = v1;
;           if (xb) {
;             u32x4 w; w.x = pack2(v0[0], v0[1]); w.y = pack2(v0[2], v0[3]); w.z = pack2(v1[0], v1[1]); w.w = pack2(v1[2], v1[3]);
;             *(u32x4*)(xb + off + bj * HALF) = w;
;             ss += v0[0] * v0[0] + v0[1] * v0[1] + v0[2] * v0[2] + v0[3] * v0[3] + v1[0] * v1[0] + v1[1] * v1[1] + v1[2] * v1[2] + v1[3] * v1[3];
;           }
;         }
;         if (xb) {
;           ss += __shfl_xor(ss, 16); ss += __shfl_xor(ss, 32);
;           if (fq == 0) ssq[(size_t)row * 32 + u.pn * 4 + wc] = ss;
; template <class Epi, class Sched = StaticOrder>
; DI void gemm_phase(LAS unsigned char* lds, const Gemm g, const Sched& S, const Epi& E) {
;     ...
;       PG8_STAGE(PG8_SB(1, 1), b3 + hstep, voffB);
;       PG8_WAIT_V(6); PG8_BAR; PG8_MMA(1, 1, At, B1); PG8_BAR;
;     }
	s_setprio 0
	s_add_u32 s20, s20, 0x160080
	s_addc_u32 s21, s21, 0
	s_add_i32 s22, s22, s30
	s_mov_b32 m0, s22
	s_nop 0
	global_load_lds_dwordx4 v178, s[20:21]
	s_add_i32 m0, s22, 0x2000
	s_nop 0
	global_load_lds_dwordx4 v182, s[20:21]
	ds_read_b128 v[128:131], v214
	ds_read_b128 v[132:135], v214 offset:1024
	ds_read_b128 v[136:139], v214 offset:2048
	ds_read_b128 v[140:143], v214 offset:3072
	s_waitcnt vmcnt(6)
	s_setprio 1
	s_barrier
	v_mfma_f32_16x16x32_bf16 v[52:55], v[192:195], v[144:147], v[52:55]
	v_mfma_f32_16x16x32_bf16 v[48:51], v[200:203], v[144:147], v[48:51]
	v_mfma_f32_16x16x32_bf16 v[36:39], v[192:195], v[152:155], v[36:39]
	v_mfma_f32_16x16x32_bf16 v[32:35], v[200:203], v[152:155], v[32:35]
	v_mfma_f32_16x16x32_bf16 v[20:23], v[192:195], v[160:163], v[20:23]
	v_mfma_f32_16x16x32_bf16 v[16:19], v[200:203], v[160:163], v[16:19]
	v_mfma_f32_16x16x32_bf16 v[4:7], v[192:195], v[168:171], v[4:7]
	v_mfma_f32_16x16x32_bf16 v[0:3], v[200:203], v[168:171], v[0:3]
	v_mfma_f32_16x16x32_bf16 v[52:55], v[196:199], v[148:151], v[52:55]
	v_mfma_f32_16x16x32_bf16 v[48:51], v[204:207], v[148:151], v[48:51]
	v_mfma_f32_16x16x32_bf16 v[36:39], v[196:199], v[156:159], v[36:39]
	v_mfma_f32_16x16x32_bf16 v[32:35], v[204:207], v[156:159], v[32:35]
	v_mfma_f32_16x16x32_bf16 v[20:23], v[196:199], v[164:167], v[20:23]
	v_mfma_f32_16x16x32_bf16 v[16:19], v[204:207], v[164:167], v[16:19]
	v_mfma_f32_16x16x32_bf16 v[4:7], v[196:199], v[172:175], v[4:7]
	v_mfma_f32_16x16x32_bf16 v[0:3], v[204:207], v[172:175], v[0:3]
	s_add_i32 s44, s44, 2
	s_add_u32 s18, s18, 0x100
	s_addc_u32 s19, s19, 0
	s_add_u32 s42, s42, 0x100
	s_addc_u32 s43, s43, 0
	s_cmpk_gt_u32 s44, 0x55
	s_barrier
	s_setprio 0
	s_cbranch_scc0 .LBB0_961
	s_waitcnt lgkmcnt(0)
	v_lshl_add_u32 v194, s51, 8, v211
	v_lshl_or_b32 v192, s2, 8, v213
	v_readlane_b32 s52, v243, 3
	v_ashrrev_i32_e32 v193, 31, v192
	v_readlane_b32 s66, v243, 17
	v_readlane_b32 s67, v243, 18
	v_ashrrev_i32_e32 v195, 31, v194
	v_lshlrev_b64 v[128:129], 13, v[194:195]
	v_lshl_add_u64 v[196:197], v[192:193], 2, s[66:67]
	v_lshl_add_u64 v[236:237], v[196:197], 0, v[128:129]
	global_load_dwordx4 v[220:223], v[236:237], off
	global_load_dwordx4 v[224:227], v[236:237], off offset:16
	global_load_dwordx4 v[228:231], v[236:237], off offset:512
	global_load_dwordx4 v[232:235], v[236:237], off offset:528
	v_or_b32_e32 v206, 16, v194
	v_or_b32_e32 v202, 32, v194
	v_or_b32_e32 v198, 48, v194
	v_ashrrev_i32_e32 v207, 31, v206
	v_ashrrev_i32_e32 v203, 31, v202
	v_ashrrev_i32_e32 v199, 31, v198
	v_lshlrev_b64 v[128:129], 13, v[206:207]
	v_lshlrev_b64 v[130:131], 13, v[202:203]
	v_lshlrev_b64 v[132:133], 13, v[198:199]
	v_lshl_add_u64 v[208:209], v[196:197], 0, v[128:129]
	v_lshl_add_u64 v[204:205], v[196:197], 0, v[130:131]
	v_lshl_add_u64 v[200:201], v[196:197], 0, v[132:133]
	global_load_dwordx4 v[168:171], v[208:209], off offset:16
	global_load_dwordx4 v[172:175], v[208:209], off
	global_load_dwordx4 v[160:163], v[208:209], off offset:528
	global_load_dwordx4 v[164:167], v[208:209], off offset:512
	global_load_dwordx4 v[152:155], v[204:205], off offset:16
	global_load_dwordx4 v[156:159], v[204:205], off
	global_load_dwordx4 v[144:147], v[204:205], off offset:528
	global_load_dwordx4 v[148:151], v[204:205], off offset:512
	global_load_dwordx4 v[136:139], v[200:201], off offset:16
	global_load_dwordx4 v[140:143], v[200:201], off
	global_load_dwordx4 v[128:131], v[200:201], off offset:528
	global_load_dwordx4 v[132:135], v[200:201], off offset:512
	v_and_b32_e32 v218, 64, v217
	v_xor_b32_e32 v238, 16, v217
	v_add_u32_e32 v240, 64, v218
	v_xor_b32_e32 v239, 32, v217
	v_cmp_lt_i32_e32 vcc, v238, v240
	v_lshlrev_b64 v[218:219], 11, v[194:195]
	s_lshl_b32 s18, s2, 2
	v_cndmask_b32_e32 v241, v217, v238, vcc
	v_cmp_lt_i32_e32 vcc, v239, v240
	s_ashr_i32 s19, s18, 31
	v_readlane_b32 s53, v243, 4
	v_cndmask_b32_e32 v240, v217, v239, vcc
	v_lshl_add_u64 v[238:239], v[218:219], 0, v[192:193]
	v_lshlrev_b32_e32 v218, 2, v241
	v_lshl_add_u64 v[238:239], v[238:239], 1, s[12:13]
	v_readlane_b32 s54, v243, 5
	v_readlane_b32 s55, v243, 6
	v_readlane_b32 s56, v243, 7
	v_readlane_b32 s57, v243, 8
	v_readlane_b32 s58, v243, 9
	v_readlane_b32 s59, v243, 10
	v_readlane_b32 s60, v243, 11
	v_readlane_b32 s61, v243, 12
	v_readlane_b32 s62, v243, 13
	v_readlane_b32 s63, v243, 14
	v_readlane_b32 s64, v243, 15
	v_readlane_b32 s65, v243, 16
	s_waitcnt vmcnt(0)
	v_pk_add_f32 v[126:127], v[126:127], v[222:223]
	v_pk_add_f32 v[124:125], v[124:125], v[220:221]
	v_pk_add_f32 v[116:117], v[116:117], v[228:229]
	v_pk_add_f32 v[122:123], v[122:123], v[226:227]
	v_pk_add_f32 v[120:121], v[120:121], v[224:225]
	v_pk_add_f32 v[220:221], v[112:113], v[232:233]
	global_store_dwordx4 v[236:237], v[124:127], off
	global_store_dwordx4 v[236:237], v[120:123], off offset:16
	v_cvt_pk_bf16_f32 v112, v124, v125
	v_mul_f32_e32 v125, v125, v125
	v_mul_f32_e32 v219, v117, v117
	v_pk_add_f32 v[118:119], v[118:119], v[230:231]
	v_fmac_f32_e32 v125, v124, v124
	v_fmac_f32_e32 v219, v116, v116
	v_fmac_f32_e32 v125, v126, v126
	v_fmac_f32_e32 v219, v118, v118
	v_fmac_f32_e32 v125, v127, v127
	v_fmac_f32_e32 v219, v119, v119
	v_fmac_f32_e32 v125, v120, v120
	v_fmac_f32_e32 v219, v220, v220
	v_pk_add_f32 v[222:223], v[114:115], v[234:235]
	v_fmac_f32_e32 v125, v121, v121
	v_fmac_f32_e32 v219, v221, v221
	v_fmac_f32_e32 v125, v122, v122
	v_fmac_f32_e32 v219, v222, v222
	v_fmac_f32_e32 v125, v123, v123
	v_fmac_f32_e32 v219, v223, v223
	v_cvt_pk_bf16_f32 v114, v120, v121
	v_add_f32_e32 v121, v125, v219
	v_cvt_pk_bf16_f32 v115, v122, v123
	ds_bpermute_b32 v122, v218, v121
	v_cvt_pk_bf16_f32 v113, v126, v127
	global_store_dwordx4 v[238:239], v[112:115], off
	global_store_dwordx4 v[236:237], v[116:119], off offset:512
	global_store_dwordx4 v[236:237], v[220:223], off offset:528
	v_lshlrev_b32_e32 v126, 2, v240
	v_cvt_pk_bf16_f32 v120, v116, v117
	s_waitcnt lgkmcnt(0)
	v_add_f32_e32 v112, v121, v122
	ds_bpermute_b32 v113, v126, v112
	v_cvt_pk_bf16_f32 v121, v118, v119
	v_cvt_pk_bf16_f32 v122, v220, v221
	v_cvt_pk_bf16_f32 v123, v222, v223
	global_store_dwordx4 v[238:239], v[120:123], off offset:256
	s_and_saveexec_b64 s[20:21], s[0:1]
	s_cbranch_execz .LBB0_964
	s_waitcnt lgkmcnt(0)
	v_add_f32_e32 v114, v112, v113
	v_lshlrev_b64 v[112:113], 7, v[194:195]
	v_lshl_add_u64 v[112:113], s[14:15], 0, v[112:113]
	v_lshl_add_u64 v[112:113], s[18:19], 2, v[112:113]
	s_lshl_b32 s2, s36, 2
	v_lshl_add_u64 v[112:113], v[112:113], 0, s[2:3]
	global_store_dword v[112:113], v114, off

; #define PG8_STAGE(bufoff, gbase, voff) do { _Pragma("unroll") for (int _i = 0; _i < 2; ++_i) \
;     __builtin_amdgcn_global_load_lds((const unsigned*)((const char*)(gbase) + (voff)[_i]), (LAS unsigned*)(lds + (bufoff) + ldsw + _i * 8192), 16, 0, 0); } while (0)
; #define PG8_LDA(dst, b, h) do { _Pragma("unroll") for (int m = 0; m < 4; ++m) _Pragma("unroll") for (int k = 0; k < 2; ++k) dst[m][k] = *(const LAS bf16x8*)(lds + PG8_SA(b, h) + aoff + m * 2048 + k * 1024); } while (0)
; #define PG8_LDB(dst, b, h) do { _Pragma("unroll") for (int n = 0; n < 2; ++n) _Pragma("unroll") for (int k = 0; k < 2; ++k) dst[n][k] = *(const LAS bf16x8*)(lds + PG8_SB(b, h) + boff + n * 2048 + k * 1024); } while (0)
; #define PG8_MMA(ai, bj, At, Bt) do { __builtin_amdgcn_s_setprio(1); _Pragma("unroll") for (int m = 0; m < 4; ++m) _Pragma("unroll") for (int n = 0; n < 2; ++n) _Pragma("unroll") for (int k = 0; k < 2; ++k) \
;     acc[ai][bj][m][n] = __builtin_amdgcn_mfma_f32_16x16x32_bf16(Bt[n][k], At[m][k], acc[ai][bj][m][n], 0, 0, 0); __builtin_amdgcn_s_setprio(0); } while (0)
; #define PG8_WAIT_V(n) asm volatile("s_waitcnt vmcnt(" #n ")" ::: "memory")
; #define PG8_WAIT_L(n) asm volatile("s_waitcnt lgkmcnt(" #n ")" ::: "memory")
; template <class Epi, class Sched = StaticOrder>
; DI void gemm_phase(LAS unsigned char* lds, const Gemm g, const Sched& S, const Epi& E) {
;     ...
;     for (int t = 0; t < nt; t += 2) {
;       const bool last = (t == nt - 2);
;       const char* a1 = cA + (size_t)(t + 1) * kstep;
;       const char* a2 = last ? nA : cA + (size_t)(t + 2) * kstep; const char* b2 = last ? nB : cB + (size_t)(t + 2) * kstep;
;       const char* a3 = a2 + kstep; const char* b3 = b2 + kstep;
;       PG8_LDB(B0, 0, 0); PG8_SCHED; PG8_LDA(At, 0, 0); PG8_STAGE(PG8_SA(1, 1), a1 + hstep, voffA);
;       PG8_WAIT_L(8); PG8_BAR; PG8_WAIT_L(0); PG8_MMA(0, 0, At, B0); PG8_BAR; PG8_SCHED;
;       PG8_LDB(B1, 0, 1); PG8_STAGE(PG8_SB(0, 0), b2, voffB);
;       PG8_BAR; PG8_WAIT_L(0); PG8_MMA(0, 1, At, B1); PG8_BAR;
;       PG8_LDA(At, 0, 1); PG8_STAGE(PG8_SA(0, 0), a2, voffA);
;       PG8_BAR; PG8_WAIT_L(0); PG8_MMA(1, 0, At, B0); PG8_BAR; PG8_SCHED;
;       PG8_STAGE(PG8_SB(0, 1), b2 + hstep, voffB);
;       PG8_WAIT_V(6); PG8_BAR; PG8_MMA(1, 1, At, B1); PG8_BAR;
;       PG8_LDB(B0, 1, 0); PG8_SCHED; PG8_LDA(At, 1, 0); PG8_STAGE(PG8_SA(0, 1), a2 + hstep, voffA);
.LBB0_1052:
	s_add_u32 s12, s10, 0xfff80080
	s_addc_u32 s13, s11, -1
	s_cmp_eq_u32 s52, 28
	s_cselect_b32 s65, s41, s13
	s_cselect_b32 s64, s42, s12
	s_cselect_b32 s13, s43, s49
	s_cselect_b32 s12, s44, s45
	s_add_i32 m0, s61, 0xc000
	ds_read_b128 v[144:147], v204
	ds_read_b128 v[152:155], v204 offset:2048
	ds_read_b128 v[178:181], v204 offset:4096
	ds_read_b128 v[186:189], v204 offset:6144
	ds_read_b128 v[148:151], v204 offset:1024
	ds_read_b128 v[156:159], v204 offset:3072
	ds_read_b128 v[182:185], v204 offset:5120
	ds_read_b128 v[190:193], v204 offset:7168
	global_load_lds_dwordx4 v172, s[10:11]
	s_add_i32 m0, s61, 0xe000
	s_nop 0
	global_load_lds_dwordx4 v174, s[10:11]
	s_waitcnt lgkmcnt(8)
	s_setprio 1
	s_barrier
	s_waitcnt lgkmcnt(4)
	v_mfma_f32_16x16x32_bf16 v[124:127], v[128:131], v[144:147], v[124:127]
	v_mfma_f32_16x16x32_bf16 v[120:123], v[136:139], v[144:147], v[120:123]
	v_mfma_f32_16x16x32_bf16 v[116:119], v[128:131], v[152:155], v[116:119]
	v_mfma_f32_16x16x32_bf16 v[104:107], v[136:139], v[152:155], v[104:107]
	v_mfma_f32_16x16x32_bf16 v[92:95], v[128:131], v[178:181], v[92:95]
	v_mfma_f32_16x16x32_bf16 v[88:91], v[136:139], v[178:181], v[88:91]
	v_mfma_f32_16x16x32_bf16 v[84:87], v[128:131], v[186:189], v[84:87]
	v_mfma_f32_16x16x32_bf16 v[72:75], v[136:139], v[186:189], v[72:75]
	s_waitcnt lgkmcnt(0)
	v_mfma_f32_16x16x32_bf16 v[124:127], v[132:135], v[148:151], v[124:127]
	v_mfma_f32_16x16x32_bf16 v[120:123], v[140:143], v[148:151], v[120:123]
	v_mfma_f32_16x16x32_bf16 v[116:119], v[132:135], v[156:159], v[116:119]
	v_mfma_f32_16x16x32_bf16 v[104:107], v[140:143], v[156:159], v[104:107]
	v_mfma_f32_16x16x32_bf16 v[92:95], v[132:135], v[182:185], v[92:95]
	v_mfma_f32_16x16x32_bf16 v[88:91], v[140:143], v[182:185], v[88:91]
	v_mfma_f32_16x16x32_bf16 v[84:87], v[132:135], v[190:193], v[84:87]
	v_mfma_f32_16x16x32_bf16 v[72:75], v[140:143], v[190:193], v[72:75]
	s_barrier
	s_setprio 0
	s_add_i32 s53, s80, s70
	s_add_u32 s98, s12, 0x80
	s_addc_u32 s99, s13, 0
	s_add_u32 s100, s64, 0x80
	s_addc_u32 s101, s65, 0
	s_mov_b32 m0, s53
	ds_read_b128 v[194:197], v205
	ds_read_b128 v[212:215], v205 offset:1024
	ds_read_b128 v[216:219], v205 offset:2048
	ds_read_b128 v[220:223], v205 offset:3072
	global_load_lds_dwordx4 v162, s[12:13]
	s_add_i32 m0, s53, 0x2000
	s_nop 0
	global_load_lds_dwordx4 v166, s[12:13]
	s_setprio 1
	s_barrier
	s_waitcnt lgkmcnt(0)
	v_mfma_f32_16x16x32_bf16 v[112:115], v[194:197], v[144:147], v[112:115]
	v_mfma_f32_16x16x32_bf16 v[108:111], v[216:219], v[144:147], v[108:111]
	v_mfma_f32_16x16x32_bf16 v[100:103], v[194:197], v[152:155], v[100:103]
	v_mfma_f32_16x16x32_bf16 v[96:99], v[216:219], v[152:155], v[96:99]
	v_mfma_f32_16x16x32_bf16 v[80:83], v[194:197], v[178:181], v[80:83]
	v_mfma_f32_16x16x32_bf16 v[76:79], v[216:219], v[178:181], v[76:79]
	v_mfma_f32_16x16x32_bf16 v[68:71], v[194:197], v[186:189], v[68:71]
	v_mfma_f32_16x16x32_bf16 v[64:67], v[216:219], v[186:189], v[64:67]
	v_mfma_f32_16x16x32_bf16 v[112:115], v[212:215], v[148:151], v[112:115]
	v_mfma_f32_16x16x32_bf16 v[108:111], v[220:223], v[148:151], v[108:111]
	v_mfma_f32_16x16x32_bf16 v[100:103], v[212:215], v[156:159], v[100:103]
	v_mfma_f32_16x16x32_bf16 v[96:99], v[220:223], v[156:159], v[96:99]
	v_mfma_f32_16x16x32_bf16 v[80:83], v[212:215], v[182:185], v[80:83]
	v_mfma_f32_16x16x32_bf16 v[76:79], v[220:223], v[182:185], v[76:79]
	v_mfma_f32_16x16x32_bf16 v[68:71], v[212:215], v[190:193], v[68:71]
	v_mfma_f32_16x16x32_bf16 v[64:67], v[220:223], v[190:193], v[64:67]
	s_barrier
	s_setprio 0
	s_mov_b32 m0, s61
	ds_read_b128 v[144:147], v204 offset:16384
	ds_read_b128 v[152:155], v204 offset:18432
	ds_read_b128 v[178:181], v204 offset:20480
	ds_read_b128 v[186:189], v204 offset:22528
	ds_read_b128 v[148:151], v204 offset:17408
	ds_read_b128 v[156:159], v204 offset:19456
	ds_read_b128 v[182:185], v204 offset:21504
	ds_read_b128 v[190:193], v204 offset:23552
	global_load_lds_dwordx4 v160, s[64:65]
	s_mov_b32 m0, s63
	s_nop 0
	global_load_lds_dwordx4 v164, s[64:65]
	s_waitcnt vmcnt(10)
	s_setprio 1
	s_barrier
	s_waitcnt lgkmcnt(4)
	v_mfma_f32_16x16x32_bf16 v[60:63], v[128:131], v[144:147], v[60:63]
	v_mfma_f32_16x16x32_bf16 v[56:59], v[136:139], v[144:147], v[56:59]
	v_mfma_f32_16x16x32_bf16 v[48:51], v[128:131], v[152:155], v[48:51]
	v_mfma_f32_16x16x32_bf16 v[40:43], v[136:139], v[152:155], v[40:43]
	v_mfma_f32_16x16x32_bf16 v[28:31], v[128:131], v[178:181], v[28:31]
	v_mfma_f32_16x16x32_bf16 v[24:27], v[136:139], v[178:181], v[24:27]
	v_mfma_f32_16x16x32_bf16 v[12:15], v[128:131], v[186:189], v[12:15]
	v_mfma_f32_16x16x32_bf16 v[8:11], v[136:139], v[186:189], v[8:11]
	s_waitcnt lgkmcnt(0)
	v_mfma_f32_16x16x32_bf16 v[60:63], v[132:135], v[148:151], v[60:63]
	v_mfma_f32_16x16x32_bf16 v[56:59], v[140:143], v[148:151], v[56:59]
	v_mfma_f32_16x16x32_bf16 v[48:51], v[132:135], v[156:159], v[48:51]
	v_mfma_f32_16x16x32_bf16 v[40:43], v[140:143], v[156:159], v[40:43]
	v_mfma_f32_16x16x32_bf16 v[28:31], v[132:135], v[182:185], v[28:31]
	v_mfma_f32_16x16x32_bf16 v[24:27], v[140:143], v[182:185], v[24:27]
	v_mfma_f32_16x16x32_bf16 v[12:15], v[132:135], v[190:193], v[12:15]
	v_mfma_f32_16x16x32_bf16 v[8:11], v[140:143], v[190:193], v[8:11]
	s_barrier
	s_setprio 0
	s_add_u32 s54, s12, 0x80000
	s_addc_u32 s55, s13, 0
	s_add_i32 s53, s81, s70
	s_mov_b32 m0, s53
	s_nop 0
	global_load_lds_dwordx4 v162, s[54:55]
	s_add_i32 m0, s53, 0x2000
	s_nop 0
	global_load_lds_dwordx4 v166, s[54:55]
	s_add_i32 s53, 0, 0x18000
	v_add_u32_e32 v140, s53, v199
	ds_read_b128 v[128:131], v140
	ds_read_b128 v[132:135], v140 offset:1024
	ds_read_b128 v[136:139], v140 offset:2048
	ds_read_b128 v[140:143], v140 offset:3072
	s_waitcnt vmcnt(6)
	s_setprio 1
	s_barrier
; #define PG8_STAGE(bufoff, gbase, voff) do { _Pragma("unroll") for (int _i = 0; _i < 2; ++_i) \
;     __builtin_amdgcn_global_load_lds((const unsigned*)((const char*)(gbase) + (voff)[_i]), (LAS unsigned*)(lds + (bufoff) + ldsw + _i * 8192), 16, 0, 0); } while (0)
; #define PG8_LDA(dst, b, h) do { _Pragma("unroll") for (int m = 0; m < 4; ++m) _Pragma("unroll") for (int k = 0; k < 2; ++k) dst[m][k] = *(const LAS bf16x8*)(lds + PG8_SA(b, h) + aoff + m * 2048 + k * 1024); } while (0)
; #define PG8_LDB(dst, b, h) do { _Pragma("unroll") for (int n = 0; n < 2; ++n) _Pragma("unroll") for (int k = 0; k < 2; ++k) dst[n][k] = *(const LAS bf16x8*)(lds + PG8_SB(b, h) + boff + n * 2048 + k * 1024); } while (0)
; #define PG8_MMA(ai, bj, At, Bt) do { __builtin_amdgcn_s_setprio(1); _Pragma("unroll") for (int m = 0; m < 4; ++m) _Pragma("unroll") for (int n = 0; n < 2; ++n) _Pragma("unroll") for (int k = 0; k < 2; ++k) \
;     acc[ai][bj][m][n] = __builtin_amdgcn_mfma_f32_16x16x32_bf16(Bt[n][k], At[m][k], acc[ai][bj][m][n], 0, 0, 0); __builtin_amdgcn_s_setprio(0); } while (0)
; #define PG8_WAIT_V(n) asm volatile("s_waitcnt vmcnt(" #n ")" ::: "memory")
; #define PG8_WAIT_L(n) asm volatile("s_waitcnt lgkmcnt(" #n ")" ::: "memory")
; #define PG8_BAR __builtin_amdgcn_s_barrier()
; #define PG8_SCHED __builtin_amdgcn_sched_barrier(0)
; template <class Epi, class Sched = StaticOrder>
; DI void gemm_phase(LAS unsigned char* lds, const Gemm g, const Sched& S, const Epi& E) {
;     ...
;       PG8_WAIT_V(6); PG8_BAR; PG8_MMA(1, 1, At, B1); PG8_BAR;
;       PG8_LDB(B0, 1, 0); PG8_SCHED; PG8_LDA(At, 1, 0); PG8_STAGE(PG8_SA(0, 1), a2 + hstep, voffA);
;       PG8_WAIT_L(8); PG8_BAR; PG8_WAIT_L(0); PG8_MMA(0, 0, At, B0); PG8_BAR; PG8_SCHED;
;       PG8_LDB(B1, 1, 1); PG8_STAGE(PG8_SB(1, 0), b3, voffB);
;       PG8_BAR; PG8_WAIT_L(0); PG8_MMA(0, 1, At, B1); PG8_BAR;
;       PG8_LDA(At, 1, 1); PG8_STAGE(PG8_SA(1, 0), a3, voffA);
;       PG8_BAR; PG8_WAIT_L(0); PG8_MMA(1, 0, At, B0); PG8_BAR; PG8_SCHED;
	v_mfma_f32_16x16x32_bf16 v[52:55], v[194:197], v[144:147], v[52:55]
	v_mfma_f32_16x16x32_bf16 v[44:47], v[216:219], v[144:147], v[44:47]
	v_mfma_f32_16x16x32_bf16 v[36:39], v[194:197], v[152:155], v[36:39]
	v_mfma_f32_16x16x32_bf16 v[32:35], v[216:219], v[152:155], v[32:35]
	v_mfma_f32_16x16x32_bf16 v[20:23], v[194:197], v[178:181], v[20:23]
	v_mfma_f32_16x16x32_bf16 v[16:19], v[216:219], v[178:181], v[16:19]
	v_mfma_f32_16x16x32_bf16 v[4:7], v[194:197], v[186:189], v[4:7]
	v_mfma_f32_16x16x32_bf16 v[0:3], v[216:219], v[186:189], v[0:3]
	v_mfma_f32_16x16x32_bf16 v[52:55], v[212:215], v[148:151], v[52:55]
	v_mfma_f32_16x16x32_bf16 v[44:47], v[220:223], v[148:151], v[44:47]
	v_mfma_f32_16x16x32_bf16 v[36:39], v[212:215], v[156:159], v[36:39]
	v_mfma_f32_16x16x32_bf16 v[32:35], v[220:223], v[156:159], v[32:35]
	v_mfma_f32_16x16x32_bf16 v[20:23], v[212:215], v[182:185], v[20:23]
	v_mfma_f32_16x16x32_bf16 v[16:19], v[220:223], v[182:185], v[16:19]
	v_mfma_f32_16x16x32_bf16 v[4:7], v[212:215], v[190:193], v[4:7]
	v_mfma_f32_16x16x32_bf16 v[0:3], v[220:223], v[190:193], v[0:3]
	s_barrier
	s_setprio 0
	s_add_u32 s54, s64, 0x80000
	s_addc_u32 s55, s65, 0
	s_mov_b32 m0, s71
	ds_read_b128 v[144:147], v204 offset:32768
	ds_read_b128 v[152:155], v204 offset:34816
	ds_read_b128 v[178:181], v204 offset:36864
	ds_read_b128 v[186:189], v204 offset:38912
	ds_read_b128 v[148:151], v204 offset:33792
	ds_read_b128 v[156:159], v204 offset:35840
	ds_read_b128 v[182:185], v204 offset:37888
	ds_read_b128 v[190:193], v204 offset:39936
	global_load_lds_dwordx4 v160, s[54:55]
	s_mov_b32 m0, s72
	s_nop 0
	global_load_lds_dwordx4 v164, s[54:55]
	s_waitcnt lgkmcnt(8)
	s_setprio 1
	s_barrier
	s_waitcnt lgkmcnt(4)
	v_mfma_f32_16x16x32_bf16 v[124:127], v[128:131], v[144:147], v[124:127]
	v_mfma_f32_16x16x32_bf16 v[120:123], v[136:139], v[144:147], v[120:123]
	v_mfma_f32_16x16x32_bf16 v[116:119], v[128:131], v[152:155], v[116:119]
	v_mfma_f32_16x16x32_bf16 v[104:107], v[136:139], v[152:155], v[104:107]
	v_mfma_f32_16x16x32_bf16 v[92:95], v[128:131], v[178:181], v[92:95]
	v_mfma_f32_16x16x32_bf16 v[88:91], v[136:139], v[178:181], v[88:91]
	v_mfma_f32_16x16x32_bf16 v[84:87], v[128:131], v[186:189], v[84:87]
	v_mfma_f32_16x16x32_bf16 v[72:75], v[136:139], v[186:189], v[72:75]
	s_waitcnt lgkmcnt(0)
	v_mfma_f32_16x16x32_bf16 v[124:127], v[132:135], v[148:151], v[124:127]
	v_mfma_f32_16x16x32_bf16 v[120:123], v[140:143], v[148:151], v[120:123]
	v_mfma_f32_16x16x32_bf16 v[116:119], v[132:135], v[156:159], v[116:119]
	v_mfma_f32_16x16x32_bf16 v[104:107], v[140:143], v[156:159], v[104:107]
	v_mfma_f32_16x16x32_bf16 v[92:95], v[132:135], v[182:185], v[92:95]
	v_mfma_f32_16x16x32_bf16 v[88:91], v[140:143], v[182:185], v[88:91]
	v_mfma_f32_16x16x32_bf16 v[84:87], v[132:135], v[190:193], v[84:87]
	v_mfma_f32_16x16x32_bf16 v[72:75], v[140:143], v[190:193], v[72:75]
	s_barrier
	s_setprio 0
	s_add_i32 s54, 0, 0x1c000
	s_add_i32 s53, s53, s70
	v_add_u32_e32 v168, s54, v199
	s_mov_b32 m0, s53
	ds_read_b128 v[194:197], v168
	ds_read_b128 v[212:215], v168 offset:1024
	ds_read_b128 v[216:219], v168 offset:2048
	ds_read_b128 v[220:223], v168 offset:3072
	global_load_lds_dwordx4 v162, s[98:99]
	s_add_i32 m0, s53, 0x2000
	s_nop 0
	global_load_lds_dwordx4 v166, s[98:99]
	s_setprio 1
	s_barrier
	s_waitcnt lgkmcnt(0)
	v_mfma_f32_16x16x32_bf16 v[112:115], v[194:197], v[144:147], v[112:115]
	v_mfma_f32_16x16x32_bf16 v[108:111], v[216:219], v[144:147], v[108:111]
	v_mfma_f32_16x16x32_bf16 v[100:103], v[194:197], v[152:155], v[100:103]
	v_mfma_f32_16x16x32_bf16 v[96:99], v[216:219], v[152:155], v[96:99]
	v_mfma_f32_16x16x32_bf16 v[80:83], v[194:197], v[178:181], v[80:83]
	v_mfma_f32_16x16x32_bf16 v[76:79], v[216:219], v[178:181], v[76:79]
	v_mfma_f32_16x16x32_bf16 v[68:71], v[194:197], v[186:189], v[68:71]
	v_mfma_f32_16x16x32_bf16 v[64:67], v[216:219], v[186:189], v[64:67]
	v_mfma_f32_16x16x32_bf16 v[112:115], v[212:215], v[148:151], v[112:115]
	v_mfma_f32_16x16x32_bf16 v[108:111], v[220:223], v[148:151], v[108:111]
	v_mfma_f32_16x16x32_bf16 v[100:103], v[212:215], v[156:159], v[100:103]
	v_mfma_f32_16x16x32_bf16 v[96:99], v[220:223], v[156:159], v[96:99]
	v_mfma_f32_16x16x32_bf16 v[80:83], v[212:215], v[182:185], v[80:83]
	v_mfma_f32_16x16x32_bf16 v[76:79], v[220:223], v[182:185], v[76:79]
	v_mfma_f32_16x16x32_bf16 v[68:71], v[212:215], v[190:193], v[68:71]
	v_mfma_f32_16x16x32_bf16 v[64:67], v[220:223], v[190:193], v[64:67]
	s_barrier
	s_setprio 0
	s_mov_b32 m0, s76
	ds_read_b128 v[144:147], v204 offset:49152
	ds_read_b128 v[152:155], v204 offset:51200
	ds_read_b128 v[178:181], v204 offset:53248
	ds_read_b128 v[186:189], v204 offset:55296
	ds_read_b128 v[148:151], v204 offset:50176
	ds_read_b128 v[156:159], v204 offset:52224
	ds_read_b128 v[182:185], v204 offset:54272
	ds_read_b128 v[190:193], v204 offset:56320
	global_load_lds_dwordx4 v160, s[100:101]
	s_mov_b32 m0, s77
	s_nop 0
	global_load_lds_dwordx4 v164, s[100:101]
	s_waitcnt vmcnt(10)
	s_setprio 1
	s_barrier
	s_waitcnt lgkmcnt(4)
	v_mfma_f32_16x16x32_bf16 v[60:63], v[128:131], v[144:147], v[60:63]
	v_mfma_f32_16x16x32_bf16 v[56:59], v[136:139], v[144:147], v[56:59]
	v_mfma_f32_16x16x32_bf16 v[48:51], v[128:131], v[152:155], v[48:51]
	v_mfma_f32_16x16x32_bf16 v[40:43], v[136:139], v[152:155], v[40:43]
	v_mfma_f32_16x16x32_bf16 v[28:31], v[128:131], v[178:181], v[28:31]
	v_mfma_f32_16x16x32_bf16 v[24:27], v[136:139], v[178:181], v[24:27]
	v_mfma_f32_16x16x32_bf16 v[12:15], v[128:131], v[186:189], v[12:15]
	v_mfma_f32_16x16x32_bf16 v[8:11], v[136:139], v[186:189], v[8:11]
	s_waitcnt lgkmcnt(0)
	v_mfma_f32_16x16x32_bf16 v[60:63], v[132:135], v[148:151], v[60:63]
	v_mfma_f32_16x16x32_bf16 v[56:59], v[140:143], v[148:151], v[56:59]
	v_mfma_f32_16x16x32_bf16 v[48:51], v[132:135], v[156:159], v[48:51]
	v_mfma_f32_16x16x32_bf16 v[40:43], v[140:143], v[156:159], v[40:43]
	v_mfma_f32_16x16x32_bf16 v[28:31], v[132:135], v[182:185], v[28:31]
	v_mfma_f32_16x16x32_bf16 v[24:27], v[140:143], v[182:185], v[24:27]
	v_mfma_f32_16x16x32_bf16 v[12:15], v[132:135], v[190:193], v[12:15]
	v_mfma_f32_16x16x32_bf16 v[8:11], v[140:143], v[190:193], v[8:11]
	s_barrier
; #define PG8_STAGE(bufoff, gbase, voff) do { _Pragma("unroll") for (int _i = 0; _i < 2; ++_i) \
;     __builtin_amdgcn_global_load_lds((const unsigned*)((const char*)(gbase) + (voff)[_i]), (LAS unsigned*)(lds + (bufoff) + ldsw + _i * 8192), 16, 0, 0); } while (0)
; #define PG8_MMA(ai, bj, At, Bt) do { __builtin_amdgcn_s_setprio(1); _Pragma("unroll") for (int m = 0; m < 4; ++m) _Pragma("unroll") for (int n = 0; n < 2; ++n) _Pragma("unroll") for (int k = 0; k < 2; ++k) \
;     acc[ai][bj][m][n] = __builtin_amdgcn_mfma_f32_16x16x32_bf16(Bt[n][k], At[m][k], acc[ai][bj][m][n], 0, 0, 0); __builtin_amdgcn_s_setprio(0); } while (0)
; #define PG8_WAIT_V(n) asm volatile("s_waitcnt vmcnt(" #n ")" ::: "memory")
; #define PG8_BAR __builtin_amdgcn_s_barrier()
;   DI void operator()(const f32x4 (&acc)[2][2][4][2], const Unit& u, int wr, int wc, int fr, int fq) const {
;     if (u.pn >= 16) {
;     ...
;     const int col = u.pn * 128 + wc * 32 + 8 * fq;
;     float w0[8], w1[8], w2[8];
; #pragma unroll
;     for (int e = 0; e < 8; ++e) { w0[e] = cw[col + e]; w1[e] = cw[2048 + col + e]; w2[e] = cw[4096 + col + e]; }
; #pragma unroll
;     for (int ai = 0; ai < 2; ++ai) {
;       const int row0 = u.pm * BM + ai * HALF + wr * 64, span = row0 >> 6;
;       float rsv[4];
; #pragma unroll
;       for (int m = 0; m < 4; ++m) rsv[m] = row_rstd(ssq, row0 + 16 * m + fr, fq);
; template <class Epi, class Sched = StaticOrder>
; DI void gemm_phase(LAS unsigned char* lds, const Gemm g, const Sched& S, const Epi& E) {
;     ...
;       PG8_STAGE(PG8_SB(1, 1), b3 + hstep, voffB);
;       PG8_WAIT_V(6); PG8_BAR; PG8_MMA(1, 1, At, B1); PG8_BAR;
;     }
	s_setprio 0
	s_add_u32 s12, s12, 0x80080
	s_addc_u32 s13, s13, 0
	s_add_i32 s53, s54, s70
	s_mov_b32 m0, s53
	s_nop 0
	global_load_lds_dwordx4 v162, s[12:13]
	s_add_i32 m0, s53, 0x2000
	s_nop 0
	global_load_lds_dwordx4 v166, s[12:13]
	ds_read_b128 v[128:131], v203
	ds_read_b128 v[132:135], v203 offset:1024
	ds_read_b128 v[136:139], v203 offset:2048
	ds_read_b128 v[140:143], v203 offset:3072
	s_waitcnt vmcnt(6)
	s_setprio 1
	s_barrier
	v_mfma_f32_16x16x32_bf16 v[52:55], v[194:197], v[144:147], v[52:55]
	v_mfma_f32_16x16x32_bf16 v[44:47], v[216:219], v[144:147], v[44:47]
	v_mfma_f32_16x16x32_bf16 v[36:39], v[194:197], v[152:155], v[36:39]
	v_mfma_f32_16x16x32_bf16 v[32:35], v[216:219], v[152:155], v[32:35]
	v_mfma_f32_16x16x32_bf16 v[20:23], v[194:197], v[178:181], v[20:23]
	v_mfma_f32_16x16x32_bf16 v[16:19], v[216:219], v[178:181], v[16:19]
	v_mfma_f32_16x16x32_bf16 v[4:7], v[194:197], v[186:189], v[4:7]
	v_mfma_f32_16x16x32_bf16 v[0:3], v[216:219], v[186:189], v[0:3]
	v_mfma_f32_16x16x32_bf16 v[52:55], v[212:215], v[148:151], v[52:55]
	v_mfma_f32_16x16x32_bf16 v[44:47], v[220:223], v[148:151], v[44:47]
	v_mfma_f32_16x16x32_bf16 v[36:39], v[212:215], v[156:159], v[36:39]
	v_mfma_f32_16x16x32_bf16 v[32:35], v[220:223], v[156:159], v[32:35]
	v_mfma_f32_16x16x32_bf16 v[20:23], v[212:215], v[182:185], v[20:23]
	v_mfma_f32_16x16x32_bf16 v[16:19], v[220:223], v[182:185], v[16:19]
	v_mfma_f32_16x16x32_bf16 v[4:7], v[212:215], v[190:193], v[4:7]
	v_mfma_f32_16x16x32_bf16 v[0:3], v[220:223], v[190:193], v[0:3]
	s_add_i32 s52, s52, 2
	s_add_u32 s10, s10, 0x100
	s_addc_u32 s11, s11, 0
	s_add_u32 s45, s45, 0x100
	s_addc_u32 s49, s49, 0
	s_cmp_gt_u32 s52, 29
	s_barrier
	s_setprio 0
	s_cbranch_scc0 .LBB0_1052
	s_waitcnt lgkmcnt(0)
	s_cmp_lt_i32 s62, 16
	s_mov_b64 s[10:11], -1
	s_cbranch_scc0 .LBB0_1067
	s_lshl_b32 s41, s60, 8
	s_add_i32 s41, s41, s75
	v_or_b32_e32 v186, s41, v177
	v_ashrrev_i32_e32 v187, 31, v186
	v_lshlrev_b64 v[128:129], 7, v[186:187]
	v_or_b32_e32 v180, 16, v186
	v_lshl_add_u64 v[128:129], v[170:171], 0, v[128:129]
	v_ashrrev_i32_e32 v181, 31, v180
	global_load_dwordx4 v[152:155], v[128:129], off
	global_load_dwordx4 v[156:159], v[128:129], off offset:16
	v_lshlrev_b64 v[128:129], 7, v[180:181]
	v_lshl_add_u64 v[128:129], v[170:171], 0, v[128:129]
	global_load_dwordx4 v[188:191], v[128:129], off
	global_load_dwordx4 v[192:195], v[128:129], off offset:16
	v_or_b32_e32 v184, 32, v186
	v_ashrrev_i32_e32 v185, 31, v184
	v_lshlrev_b64 v[128:129], 7, v[184:185]
	v_or_b32_e32 v182, 48, v186
	v_lshl_add_u64 v[128:129], v[170:171], 0, v[128:129]
	v_ashrrev_i32_e32 v183, 31, v182
	global_load_dwordx4 v[212:215], v[128:129], off
	global_load_dwordx4 v[216:219], v[128:129], off offset:16
	v_lshlrev_b64 v[128:129], 7, v[182:183]
	v_lshl_add_u64 v[128:129], v[170:171], 0, v[128:129]
	global_load_dwordx4 v[220:223], v[128:129], off
	global_load_dwordx4 v[224:227], v[128:129], off offset:16
	v_and_b32_e32 v129, 64, v206
	v_lshl_or_b32 v178, s62, 7, v200
	v_xor_b32_e32 v128, 16, v206
	v_add_u32_e32 v129, 64, v129
	v_readlane_b32 s44, v243, 3
	v_xor_b32_e32 v130, 32, v206
	v_ashrrev_i32_e32 v179, 31, v178
	v_readlane_b32 s45, v243, 4
	v_cmp_lt_i32_e32 vcc, v128, v129
	s_movk_i32 s10, 0x2000
	v_lshl_add_u64 v[144:145], v[178:179], 2, s[44:45]
	v_cndmask_b32_e32 v134, v206, v128, vcc
	v_cmp_lt_i32_e32 vcc, v130, v129
	v_lshl_add_u64 v[132:133], v[144:145], 0, s[26:27]
	v_lshl_add_u64 v[136:137], v[144:145], 0, s[28:29]
	v_cndmask_b32_e32 v135, v206, v130, vcc
	v_add_co_u32_e32 v146, vcc, s10, v144
	global_load_dwordx4 v[128:131], v[144:145], off offset:16
	global_load_dwordx4 v[140:143], v[144:145], off
	v_addc_co_u32_e32 v147, vcc, 0, v145, vcc
	v_add_co_u32_e32 v148, vcc, s74, v144
	v_lshlrev_b32_e32 v196, 2, v134
	s_nop 0
	v_addc_co_u32_e32 v149, vcc, 0, v145, vcc
	v_lshlrev_b32_e32 v207, 2, v135
	global_load_dwordx4 v[132:135], v[132:133], off offset:16
	s_nop 0
	global_load_dwordx4 v[136:139], v[136:137], off offset:16
	s_nop 0
	global_load_dwordx4 v[144:147], v[146:147], off
	s_nop 0
	global_load_dwordx4 v[148:151], v[148:149], off
	v_mov_b32_e32 v197, 0
	v_mov_b32_e32 v211, 0
	v_readlane_b32 s46, v243, 5
	v_readlane_b32 s47, v243, 6
	v_readlane_b32 s48, v243, 7
	v_readlane_b32 s49, v243, 8
	v_readlane_b32 s50, v243, 9
	v_readlane_b32 s51, v243, 10
	v_readlane_b32 s52, v243, 11
	v_readlane_b32 s53, v243, 12
	v_readlane_b32 s54, v243, 13
	v_readlane_b32 s55, v243, 14
	v_readlane_b32 s56, v243, 15
	v_readlane_b32 s57, v243, 16
	v_readlane_b32 s58, v243, 17
	v_readlane_b32 s59, v243, 18
	s_waitcnt vmcnt(0)
	v_mov_b32_e32 v208, v152
	v_mov_b32_e32 v209, v156
	v_mov_b32_e32 v156, v153
	v_mov_b32_e32 v152, v154
	v_mov_b32_e32 v153, v158
	v_mov_b32_e32 v158, v155
	v_pk_add_f32 v[154:155], v[208:209], v[156:157]
	v_pk_add_f32 v[152:153], v[152:153], v[158:159]
	v_mov_b32_e32 v156, v188
	v_mov_b32_e32 v157, v192
	v_mov_b32_e32 v192, v189
	v_mov_b32_e32 v158, v190
	v_mov_b32_e32 v159, v194
	v_mov_b32_e32 v194, v191
	v_pk_add_f32 v[152:153], v[154:155], v[152:153]
	v_pk_add_f32 v[154:155], v[156:157], v[192:193]
	v_pk_add_f32 v[156:157], v[158:159], v[194:195]
	v_mov_b32_e32 v188, v212
	v_pk_add_f32 v[154:155], v[154:155], v[156:157]
	v_mov_b32_e32 v157, v152
	v_mov_b32_e32 v156, v154
	v_mov_b32_e32 v152, v155
	v_pk_add_f32 v[152:153], v[156:157], v[152:153]
	ds_bpermute_b32 v155, v196, v153
	ds_bpermute_b32 v154, v196, v152
	v_mov_b32_e32 v189, v216
	v_mov_b32_e32 v216, v213
	v_mov_b32_e32 v190, v214
	v_mov_b32_e32 v191, v218
	s_waitcnt lgkmcnt(0)
; DI unsigned pack2(float lo, float hi) { f32x2 v = {lo, hi}; bf16v2 r = __builtin_convertvector(v, bf16v2); return __builtin_bit_cast(unsigned, r); }
; DI float dpp_ror1(float v) { return __int_as_float(__builtin_amdgcn_update_dpp(0, __float_as_int(v), 0x121, 0xf, 0xf, false)); }
; DI float dpp_ror2(float v) { return __int_as_float(__builtin_amdgcn_update_dpp(0, __float_as_int(v), 0x122, 0xf, 0xf, false)); }
;   DI void operator()(const f32x4 (&acc)[2][2][4][2], const Unit& u, int wr, int wc, int fr, int fq) const {
;     ...
;       for (int m = 0; m < 4; ++m) rsv[m] = row_rstd(ssq, row0 + 16 * m + fr, fq);
;       float p1[8], p2[8];
; #pragma unroll
;       for (int e = 0; e < 8; ++e) { p1[e] = 0.f; p2[e] = 0.f; }
; #pragma unroll
;       for (int m = 0; m < 4; ++m) {
;         float g[8], a[8];
;         const float rs1 = rsv[m], rs2 = rs1 * rs1;
; #pragma unroll
;         for (int e = 0; e < 4; ++e) { g[e] = acc[ai][0][m][0][e] * acc[ai][1][m][0][e] * rs2; g[4 + e] = acc[ai][0][m][1][e] * acc[ai][1][m][1][e] * rs2; }
; #pragma unroll
;         for (int e = 0; e < 8; ++e) {
;           const float x1 = dpp_ror1(g[e]), x2 = dpp_ror2(g[e]);
;           const float pr1 = (fr == 0) ? p1[e] : x1, pr2 = (fr < 2) ? p2[e] : x2;
;           a[e] = w2[e] * g[e] + w1[e] * pr1 + w0[e] * pr2;
;           p1[e] = x1; p2[e] = x2;
;         }
;         if (m == 0 && fr < 2) {
;           float* hc = headC + (size_t)(span * 2 + fr) * 2048 + col;
;           *(f32x4*)hc = (f32x4){a[0], a[1], a[2], a[3]}; *(f32x4*)(hc + 4) = (f32x4){a[4], a[5], a[6], a[7]};
;         } else {
;           u32x4 w; w.x = pack2(a[0] * rs1, a[1] * rs1); w.y = pack2(a[2] * rs1, a[3] * rs1); w.z = pack2(a[4] * rs1, a[5] * rs1); w.w = pack2(a[6] * rs1, a[7] * rs1);
;           *(u32x4*)(C + (size_t)(row0 + 16 * m + fr) * 2048 + col) = w;
	v_pk_add_f32 v[152:153], v[152:153], v[154:155]
	ds_bpermute_b32 v155, v207, v153
	ds_bpermute_b32 v154, v207, v152
	v_mov_b32_e32 v218, v215
	v_mov_b32_e32 v208, v220
	v_mov_b32_e32 v209, v224
	v_mov_b32_e32 v224, v221
	v_mov_b32_e32 v212, v222
	v_mov_b32_e32 v213, v226
	v_mov_b32_e32 v226, v223
	v_pk_add_f32 v[156:157], v[188:189], v[216:217]
	v_pk_add_f32 v[158:159], v[190:191], v[218:219]
	v_pk_add_f32 v[188:189], v[208:209], v[224:225]
	v_pk_add_f32 v[190:191], v[212:213], v[226:227]
	s_waitcnt lgkmcnt(0)
	v_pk_add_f32 v[152:153], v[152:153], v[154:155]
	v_pk_add_f32 v[156:157], v[156:157], v[158:159]
	v_pk_add_f32 v[158:159], v[188:189], v[190:191]
	v_pk_fma_f32 v[188:189], v[152:153], s[30:31], v[176:177] op_sel_hi:[1,0,0]
	v_mov_b32_e32 v153, v156
	v_mul_f32_e32 v152, 0x4b800000, v189
	v_cmp_gt_f32_e64 s[10:11], s84, v189
	v_mov_b32_e32 v156, v159
	v_mov_b32_e32 v194, v123
	v_cndmask_b32_e64 v152, v189, v152, s[10:11]
	v_rsq_f32_e32 v168, v152
	v_mov_b32_e32 v152, v158
	v_pk_add_f32 v[152:153], v[152:153], v[156:157]
	ds_bpermute_b32 v155, v196, v153
	ds_bpermute_b32 v154, v196, v152
	v_mul_f32_e32 v156, 0x45800000, v168
	v_cndmask_b32_e64 v195, v168, v156, s[10:11]
	v_mov_b32_e32 v217, 0
	v_mul_f32_e32 v156, v125, v113
	s_waitcnt lgkmcnt(0)
	v_pk_add_f32 v[190:191], v[152:153], v[154:155]
	v_mov_b32_e32 v152, v111
	v_mov_b32_e32 v153, v195
	v_mul_f32_e32 v154, v124, v112
	v_pk_mul_f32 v[152:153], v[194:195], v[152:153]
	v_mul_f32_e32 v155, v120, v108
	v_mul_f32_e32 v154, v154, v153
	v_pk_mul_f32 v[222:223], v[152:153], v[152:153] op_sel:[0,1] op_sel_hi:[1,0]
	v_mov_b32_e32 v213, 0
	v_mov_b32_dpp v217, v154 row_ror:1 row_mask:0xf bank_mask:0xf
	v_cndmask_b32_e64 v152, v217, 0, s[0:1]
	v_mul_f32_e32 v157, v121, v109
	v_mul_f32_e32 v158, v126, v114
	v_mul_f32_e32 v159, v122, v110
	v_mul_f32_e32 v168, v127, v115
	v_mul_f32_e32 v194, v155, v153
	v_mul_f32_e32 v155, v156, v153
	v_mov_b32_dpp v213, v154 row_ror:2 row_mask:0xf bank_mask:0xf
	v_mov_b32_e32 v221, 0
	v_mul_f32_e32 v152, v144, v152
	v_mul_f32_e32 v208, v157, v153
	v_mul_f32_e32 v156, v158, v153
	v_mul_f32_e32 v159, v159, v153
	v_mul_f32_e32 v157, v168, v153
	v_mov_b32_dpp v221, v155 row_ror:1 row_mask:0xf bank_mask:0xf
	v_cndmask_b32_e64 v153, v213, 0, s[8:9]
	v_fmac_f32_e32 v152, v148, v154
	v_mov_b32_e32 v219, 0
	v_fmac_f32_e32 v152, v140, v153
	v_cndmask_b32_e64 v153, v221, 0, s[0:1]
	v_mov_b32_dpp v219, v155 row_ror:2 row_mask:0xf bank_mask:0xf
	v_mul_f32_e32 v153, v145, v153
	v_mov_b32_e32 v216, 0
	v_cndmask_b32_e64 v154, v219, 0, s[8:9]
	v_fmac_f32_e32 v153, v149, v155
	v_mov_b32_dpp v216, v156 row_ror:1 row_mask:0xf bank_mask:0xf
	v_fmac_f32_e32 v153, v141, v154
	v_mov_b32_e32 v212, 0
	v_cndmask_b32_e64 v154, v216, 0, s[0:1]
	v_mov_b32_e32 v220, 0
	v_mov_b32_dpp v212, v156 row_ror:2 row_mask:0xf bank_mask:0xf
	v_mul_f32_e32 v154, v146, v154
	v_mov_b32_dpp v220, v157 row_ror:1 row_mask:0xf bank_mask:0xf
	v_cndmask_b32_e64 v155, v212, 0, s[8:9]
	v_fmac_f32_e32 v154, v150, v156
	v_mov_b32_e32 v218, 0
	v_fmac_f32_e32 v154, v142, v155
	v_cndmask_b32_e64 v155, v220, 0, s[0:1]
	v_mov_b32_dpp v218, v157 row_ror:2 row_mask:0xf bank_mask:0xf
	v_mul_f32_e32 v155, v147, v155
	v_cndmask_b32_e64 v156, v218, 0, s[8:9]
	v_fmac_f32_e32 v155, v151, v157
	v_mov_b32_dpp v197, v194 row_ror:1 row_mask:0xf bank_mask:0xf
	v_fmac_f32_e32 v155, v143, v156
	v_mov_b32_e32 v189, 0
	v_cndmask_b32_e64 v156, v197, 0, s[0:1]
	v_mov_b32_e32 v214, 0
	v_mov_b32_dpp v189, v194 row_ror:2 row_mask:0xf bank_mask:0xf
	v_mul_f32_e32 v156, v132, v156
	v_mov_b32_dpp v214, v208 row_ror:1 row_mask:0xf bank_mask:0xf
	v_cndmask_b32_e64 v157, v189, 0, s[8:9]
	v_fmac_f32_e32 v156, v136, v194
	v_fmac_f32_e32 v156, v128, v157
	v_cndmask_b32_e64 v157, v214, 0, s[0:1]
	v_mov_b32_e32 v209, 0
	v_mul_f32_e32 v157, v133, v157
	v_fmac_f32_e32 v157, v137, v208
	v_mov_b32_dpp v209, v208 row_ror:2 row_mask:0xf bank_mask:0xf
	v_mov_b32_e32 v208, 0
	v_cndmask_b32_e64 v158, v209, 0, s[8:9]
	v_fmac_f32_e32 v157, v129, v158
	v_mov_b32_dpp v208, v159 row_ror:1 row_mask:0xf bank_mask:0xf
	v_mov_b32_e32 v194, 0
	v_cndmask_b32_e64 v158, v208, 0, s[0:1]
	ds_bpermute_b32 v193, v207, v191
	ds_bpermute_b32 v192, v207, v190
	v_mov_b32_dpp v194, v159 row_ror:2 row_mask:0xf bank_mask:0xf
	v_mov_b32_e32 v215, 0
	v_mul_f32_e32 v158, v134, v158
	v_cndmask_b32_e64 v168, v194, 0, s[8:9]
	v_mov_b32_dpp v215, v222 row_ror:1 row_mask:0xf bank_mask:0xf
	v_fmac_f32_e32 v158, v138, v159
	v_mov_b32_dpp v211, v222 row_ror:2 row_mask:0xf bank_mask:0xf
	v_fmac_f32_e32 v158, v130, v168
	v_cndmask_b32_e64 v168, v215, 0, s[0:1]
	v_mul_f32_e32 v159, v139, v222
	v_cndmask_b32_e64 v223, v211, 0, s[8:9]
	v_fmac_f32_e32 v159, v135, v168
	v_cmp_gt_f32_e32 vcc, s84, v188
	v_fmac_f32_e32 v159, v131, v223
	s_and_saveexec_b64 s[10:11], s[4:5]
	s_xor_b64 s[10:11], exec, s[10:11]
	s_cbranch_execz .LBB0_1056
	v_mul_f32_e32 v152, v195, v152
	v_mul_f32_e32 v153, v195, v153
	v_cvt_pk_bf16_f32 v152, v152, v153
	v_mul_f32_e32 v153, v195, v154
	v_mul_f32_e32 v154, v195, v155
	v_cvt_pk_bf16_f32 v153, v153, v154
	v_mul_f32_e32 v154, v195, v156
	v_mul_f32_e32 v155, v195, v157
	v_cvt_pk_bf16_f32 v154, v154, v155
	v_mul_f32_e32 v155, v195, v158
	v_mul_f32_e32 v156, v195, v159
	v_cvt_pk_bf16_f32 v155, v155, v156
	v_lshlrev_b64 v[156:157], 12, v[186:187]
	v_lshl_add_u64 v[156:157], s[18:19], 0, v[156:157]
	v_lshl_add_u64 v[156:157], v[178:179], 1, v[156:157]
	global_store_dwordx4 v[156:157], v[152:155], off

; #define PG8_STAGE(bufoff, gbase, voff) do { _Pragma("unroll") for (int _i = 0; _i < 2; ++_i) \
;     __builtin_amdgcn_global_load_lds((const unsigned*)((const char*)(gbase) + (voff)[_i]), (LAS unsigned*)(lds + (bufoff) + ldsw + _i * 8192), 16, 0, 0); } while (0)
; #define PG8_LDA(dst, b, h) do { _Pragma("unroll") for (int m = 0; m < 4; ++m) _Pragma("unroll") for (int k = 0; k < 2; ++k) dst[m][k] = *(const LAS bf16x8*)(lds + PG8_SA(b, h) + aoff + m * 2048 + k * 1024); } while (0)
; #define PG8_LDB(dst, b, h) do { _Pragma("unroll") for (int n = 0; n < 2; ++n) _Pragma("unroll") for (int k = 0; k < 2; ++k) dst[n][k] = *(const LAS bf16x8*)(lds + PG8_SB(b, h) + boff + n * 2048 + k * 1024); } while (0)
; #define PG8_MMA(ai, bj, At, Bt) do { __builtin_amdgcn_s_setprio(1); _Pragma("unroll") for (int m = 0; m < 4; ++m) _Pragma("unroll") for (int n = 0; n < 2; ++n) _Pragma("unroll") for (int k = 0; k < 2; ++k) \
;     acc[ai][bj][m][n] = __builtin_amdgcn_mfma_f32_16x16x32_bf16(Bt[n][k], At[m][k], acc[ai][bj][m][n], 0, 0, 0); __builtin_amdgcn_s_setprio(0); } while (0)
; #define PG8_WAIT_V(n) asm volatile("s_waitcnt vmcnt(" #n ")" ::: "memory")
; #define PG8_WAIT_L(n) asm volatile("s_waitcnt lgkmcnt(" #n ")" ::: "memory")
; template <class Epi, class Sched = StaticOrder>
; DI void gemm_phase(LAS unsigned char* lds, const Gemm g, const Sched& S, const Epi& E) {
;     ...
;     for (int t = 0; t < nt; t += 2) {
;       const bool last = (t == nt - 2);
;       const char* a1 = cA + (size_t)(t + 1) * kstep;
;       const char* a2 = last ? nA : cA + (size_t)(t + 2) * kstep; const char* b2 = last ? nB : cB + (size_t)(t + 2) * kstep;
;       const char* a3 = a2 + kstep; const char* b3 = b2 + kstep;
;       PG8_LDB(B0, 0, 0); PG8_SCHED; PG8_LDA(At, 0, 0); PG8_STAGE(PG8_SA(1, 1), a1 + hstep, voffA);
;       PG8_WAIT_L(8); PG8_BAR; PG8_WAIT_L(0); PG8_MMA(0, 0, At, B0); PG8_BAR; PG8_SCHED;
;       PG8_LDB(B1, 0, 1); PG8_STAGE(PG8_SB(0, 0), b2, voffB);
;       PG8_BAR; PG8_WAIT_L(0); PG8_MMA(0, 1, At, B1); PG8_BAR;
;       PG8_LDA(At, 0, 1); PG8_STAGE(PG8_SA(0, 0), a2, voffA);
;       PG8_BAR; PG8_WAIT_L(0); PG8_MMA(1, 0, At, B0); PG8_BAR; PG8_SCHED;
;       PG8_STAGE(PG8_SB(0, 1), b2 + hstep, voffB);
;       PG8_WAIT_V(6); PG8_BAR; PG8_MMA(1, 1, At, B1); PG8_BAR;
;       PG8_LDB(B0, 1, 0); PG8_SCHED; PG8_LDA(At, 1, 0); PG8_STAGE(PG8_SA(0, 1), a2 + hstep, voffA);
.LBB0_1194:
	s_add_u32 s24, s22, 0xfff80080
	s_addc_u32 s25, s23, -1
	s_cmp_eq_u32 s54, 28
	s_cselect_b32 s27, s17, s25
	s_cselect_b32 s26, s43, s24
	s_cselect_b32 s25, s15, s53
	s_cselect_b32 s24, s51, s52
	s_add_i32 m0, s37, 0xc000
	ds_read_b128 v[144:147], v215
	ds_read_b128 v[152:155], v215 offset:2048
	ds_read_b128 v[160:163], v215 offset:4096
	ds_read_b128 v[168:171], v215 offset:6144
	ds_read_b128 v[148:151], v215 offset:1024
	ds_read_b128 v[156:159], v215 offset:3072
	ds_read_b128 v[164:167], v215 offset:5120
	ds_read_b128 v[172:175], v215 offset:7168
	global_load_lds_dwordx4 v184, s[22:23]
	s_add_i32 m0, s37, 0xe000
	s_nop 0
	global_load_lds_dwordx4 v186, s[22:23]
	s_waitcnt lgkmcnt(8)
	s_setprio 1
	s_barrier
	s_waitcnt lgkmcnt(4)
	v_mfma_f32_16x16x32_bf16 v[124:127], v[128:131], v[144:147], v[124:127]
	v_mfma_f32_16x16x32_bf16 v[120:123], v[136:139], v[144:147], v[120:123]
	v_mfma_f32_16x16x32_bf16 v[108:111], v[128:131], v[152:155], v[108:111]
	v_mfma_f32_16x16x32_bf16 v[104:107], v[136:139], v[152:155], v[104:107]
	v_mfma_f32_16x16x32_bf16 v[92:95], v[128:131], v[160:163], v[92:95]
	v_mfma_f32_16x16x32_bf16 v[88:91], v[136:139], v[160:163], v[88:91]
	v_mfma_f32_16x16x32_bf16 v[76:79], v[128:131], v[168:171], v[76:79]
	v_mfma_f32_16x16x32_bf16 v[72:75], v[136:139], v[168:171], v[72:75]
	s_waitcnt lgkmcnt(0)
	v_mfma_f32_16x16x32_bf16 v[124:127], v[132:135], v[148:151], v[124:127]
	v_mfma_f32_16x16x32_bf16 v[120:123], v[140:143], v[148:151], v[120:123]
	v_mfma_f32_16x16x32_bf16 v[108:111], v[132:135], v[156:159], v[108:111]
	v_mfma_f32_16x16x32_bf16 v[104:107], v[140:143], v[156:159], v[104:107]
	v_mfma_f32_16x16x32_bf16 v[92:95], v[132:135], v[164:167], v[92:95]
	v_mfma_f32_16x16x32_bf16 v[88:91], v[140:143], v[164:167], v[88:91]
	v_mfma_f32_16x16x32_bf16 v[76:79], v[132:135], v[172:175], v[76:79]
	v_mfma_f32_16x16x32_bf16 v[72:75], v[140:143], v[172:175], v[72:75]
	s_barrier
	s_setprio 0
	s_add_i32 s55, s48, s35
	s_add_u32 s98, s24, 0x80
	s_addc_u32 s99, s25, 0
	s_add_u32 s100, s26, 0x80
	s_addc_u32 s101, s27, 0
	s_mov_b32 m0, s55
	ds_read_b128 v[192:195], v216
	ds_read_b128 v[196:199], v216 offset:1024
	ds_read_b128 v[200:203], v216 offset:2048
	ds_read_b128 v[204:207], v216 offset:3072
	global_load_lds_dwordx4 v180, s[24:25]
	s_add_i32 m0, s55, 0x2000
	s_nop 0
	global_load_lds_dwordx4 v176, s[24:25]
	s_setprio 1
	s_barrier
	s_waitcnt lgkmcnt(0)
	v_mfma_f32_16x16x32_bf16 v[116:119], v[192:195], v[144:147], v[116:119]
	v_mfma_f32_16x16x32_bf16 v[112:115], v[200:203], v[144:147], v[112:115]
	v_mfma_f32_16x16x32_bf16 v[100:103], v[192:195], v[152:155], v[100:103]
	v_mfma_f32_16x16x32_bf16 v[96:99], v[200:203], v[152:155], v[96:99]
	v_mfma_f32_16x16x32_bf16 v[84:87], v[192:195], v[160:163], v[84:87]
	v_mfma_f32_16x16x32_bf16 v[80:83], v[200:203], v[160:163], v[80:83]
	v_mfma_f32_16x16x32_bf16 v[68:71], v[192:195], v[168:171], v[68:71]
	v_mfma_f32_16x16x32_bf16 v[64:67], v[200:203], v[168:171], v[64:67]
	v_mfma_f32_16x16x32_bf16 v[116:119], v[196:199], v[148:151], v[116:119]
	v_mfma_f32_16x16x32_bf16 v[112:115], v[204:207], v[148:151], v[112:115]
	v_mfma_f32_16x16x32_bf16 v[100:103], v[196:199], v[156:159], v[100:103]
	v_mfma_f32_16x16x32_bf16 v[96:99], v[204:207], v[156:159], v[96:99]
	v_mfma_f32_16x16x32_bf16 v[84:87], v[196:199], v[164:167], v[84:87]
	v_mfma_f32_16x16x32_bf16 v[80:83], v[204:207], v[164:167], v[80:83]
	v_mfma_f32_16x16x32_bf16 v[68:71], v[196:199], v[172:175], v[68:71]
	v_mfma_f32_16x16x32_bf16 v[64:67], v[204:207], v[172:175], v[64:67]
	s_barrier
	s_setprio 0
	s_mov_b32 m0, s37
	ds_read_b128 v[144:147], v215 offset:16384
	ds_read_b128 v[152:155], v215 offset:18432
	ds_read_b128 v[160:163], v215 offset:20480
	ds_read_b128 v[168:171], v215 offset:22528
	ds_read_b128 v[148:151], v215 offset:17408
	ds_read_b128 v[156:159], v215 offset:19456
	ds_read_b128 v[164:167], v215 offset:21504
	ds_read_b128 v[172:175], v215 offset:23552
	global_load_lds_dwordx4 v182, s[26:27]
	s_mov_b32 m0, s38
	s_nop 0
	global_load_lds_dwordx4 v178, s[26:27]
	s_waitcnt vmcnt(10)
	s_setprio 1
	s_barrier
	s_waitcnt lgkmcnt(4)
	v_mfma_f32_16x16x32_bf16 v[60:63], v[128:131], v[144:147], v[60:63]
	v_mfma_f32_16x16x32_bf16 v[56:59], v[136:139], v[144:147], v[56:59]
	v_mfma_f32_16x16x32_bf16 v[44:47], v[128:131], v[152:155], v[44:47]
	v_mfma_f32_16x16x32_bf16 v[40:43], v[136:139], v[152:155], v[40:43]
	v_mfma_f32_16x16x32_bf16 v[28:31], v[128:131], v[160:163], v[28:31]
	v_mfma_f32_16x16x32_bf16 v[24:27], v[136:139], v[160:163], v[24:27]
	v_mfma_f32_16x16x32_bf16 v[12:15], v[128:131], v[168:171], v[12:15]
	v_mfma_f32_16x16x32_bf16 v[8:11], v[136:139], v[168:171], v[8:11]
	s_waitcnt lgkmcnt(0)
	v_mfma_f32_16x16x32_bf16 v[60:63], v[132:135], v[148:151], v[60:63]
	v_mfma_f32_16x16x32_bf16 v[56:59], v[140:143], v[148:151], v[56:59]
	v_mfma_f32_16x16x32_bf16 v[44:47], v[132:135], v[156:159], v[44:47]
	v_mfma_f32_16x16x32_bf16 v[40:43], v[140:143], v[156:159], v[40:43]
	v_mfma_f32_16x16x32_bf16 v[28:31], v[132:135], v[164:167], v[28:31]
	v_mfma_f32_16x16x32_bf16 v[24:27], v[140:143], v[164:167], v[24:27]
	v_mfma_f32_16x16x32_bf16 v[12:15], v[132:135], v[172:175], v[12:15]
	v_mfma_f32_16x16x32_bf16 v[8:11], v[140:143], v[172:175], v[8:11]
	s_barrier
	s_setprio 0
	s_add_u32 s56, s24, 0x80000
	s_addc_u32 s57, s25, 0
	s_add_i32 s55, s49, s35
	s_mov_b32 m0, s55
	s_nop 0
	global_load_lds_dwordx4 v180, s[56:57]
	s_add_i32 m0, s55, 0x2000
	s_nop 0
	global_load_lds_dwordx4 v176, s[56:57]
	s_add_i32 s55, 0, 0x18000
	v_add_u32_e32 v140, s55, v212
	ds_read_b128 v[128:131], v140
	ds_read_b128 v[132:135], v140 offset:1024
	ds_read_b128 v[136:139], v140 offset:2048
	ds_read_b128 v[140:143], v140 offset:3072
	s_waitcnt vmcnt(6)
	s_setprio 1
	s_barrier
; #define PG8_STAGE(bufoff, gbase, voff) do { _Pragma("unroll") for (int _i = 0; _i < 2; ++_i) \
;     __builtin_amdgcn_global_load_lds((const unsigned*)((const char*)(gbase) + (voff)[_i]), (LAS unsigned*)(lds + (bufoff) + ldsw + _i * 8192), 16, 0, 0); } while (0)
; #define PG8_LDA(dst, b, h) do { _Pragma("unroll") for (int m = 0; m < 4; ++m) _Pragma("unroll") for (int k = 0; k < 2; ++k) dst[m][k] = *(const LAS bf16x8*)(lds + PG8_SA(b, h) + aoff + m * 2048 + k * 1024); } while (0)
; #define PG8_LDB(dst, b, h) do { _Pragma("unroll") for (int n = 0; n < 2; ++n) _Pragma("unroll") for (int k = 0; k < 2; ++k) dst[n][k] = *(const LAS bf16x8*)(lds + PG8_SB(b, h) + boff + n * 2048 + k * 1024); } while (0)
; #define PG8_MMA(ai, bj, At, Bt) do { __builtin_amdgcn_s_setprio(1); _Pragma("unroll") for (int m = 0; m < 4; ++m) _Pragma("unroll") for (int n = 0; n < 2; ++n) _Pragma("unroll") for (int k = 0; k < 2; ++k) \
;     acc[ai][bj][m][n] = __builtin_amdgcn_mfma_f32_16x16x32_bf16(Bt[n][k], At[m][k], acc[ai][bj][m][n], 0, 0, 0); __builtin_amdgcn_s_setprio(0); } while (0)
; #define PG8_WAIT_V(n) asm volatile("s_waitcnt vmcnt(" #n ")" ::: "memory")
; #define PG8_WAIT_L(n) asm volatile("s_waitcnt lgkmcnt(" #n ")" ::: "memory")
; #define PG8_BAR __builtin_amdgcn_s_barrier()
; #define PG8_SCHED __builtin_amdgcn_sched_barrier(0)
; template <class Epi, class Sched = StaticOrder>
; DI void gemm_phase(LAS unsigned char* lds, const Gemm g, const Sched& S, const Epi& E) {
;     ...
;       PG8_WAIT_V(6); PG8_BAR; PG8_MMA(1, 1, At, B1); PG8_BAR;
;       PG8_LDB(B0, 1, 0); PG8_SCHED; PG8_LDA(At, 1, 0); PG8_STAGE(PG8_SA(0, 1), a2 + hstep, voffA);
;       PG8_WAIT_L(8); PG8_BAR; PG8_WAIT_L(0); PG8_MMA(0, 0, At, B0); PG8_BAR; PG8_SCHED;
;       PG8_LDB(B1, 1, 1); PG8_STAGE(PG8_SB(1, 0), b3, voffB);
;       PG8_BAR; PG8_WAIT_L(0); PG8_MMA(0, 1, At, B1); PG8_BAR;
;       PG8_LDA(At, 1, 1); PG8_STAGE(PG8_SA(1, 0), a3, voffA);
;       PG8_BAR; PG8_WAIT_L(0); PG8_MMA(1, 0, At, B0); PG8_BAR; PG8_SCHED;
	v_mfma_f32_16x16x32_bf16 v[52:55], v[192:195], v[144:147], v[52:55]
	v_mfma_f32_16x16x32_bf16 v[48:51], v[200:203], v[144:147], v[48:51]
	v_mfma_f32_16x16x32_bf16 v[36:39], v[192:195], v[152:155], v[36:39]
	v_mfma_f32_16x16x32_bf16 v[32:35], v[200:203], v[152:155], v[32:35]
	v_mfma_f32_16x16x32_bf16 v[20:23], v[192:195], v[160:163], v[20:23]
	v_mfma_f32_16x16x32_bf16 v[16:19], v[200:203], v[160:163], v[16:19]
	v_mfma_f32_16x16x32_bf16 v[4:7], v[192:195], v[168:171], v[4:7]
	v_mfma_f32_16x16x32_bf16 v[0:3], v[200:203], v[168:171], v[0:3]
	v_mfma_f32_16x16x32_bf16 v[52:55], v[196:199], v[148:151], v[52:55]
	v_mfma_f32_16x16x32_bf16 v[48:51], v[204:207], v[148:151], v[48:51]
	v_mfma_f32_16x16x32_bf16 v[36:39], v[196:199], v[156:159], v[36:39]
	v_mfma_f32_16x16x32_bf16 v[32:35], v[204:207], v[156:159], v[32:35]
	v_mfma_f32_16x16x32_bf16 v[20:23], v[196:199], v[164:167], v[20:23]
	v_mfma_f32_16x16x32_bf16 v[16:19], v[204:207], v[164:167], v[16:19]
	v_mfma_f32_16x16x32_bf16 v[4:7], v[196:199], v[172:175], v[4:7]
	v_mfma_f32_16x16x32_bf16 v[0:3], v[204:207], v[172:175], v[0:3]
	s_barrier
	s_setprio 0
	s_add_u32 s26, s26, 0x80000
	s_addc_u32 s27, s27, 0
	s_mov_b32 m0, s39
	ds_read_b128 v[144:147], v215 offset:32768
	ds_read_b128 v[152:155], v215 offset:34816
	ds_read_b128 v[160:163], v215 offset:36864
	ds_read_b128 v[168:171], v215 offset:38912
	ds_read_b128 v[148:151], v215 offset:33792
	ds_read_b128 v[156:159], v215 offset:35840
	ds_read_b128 v[164:167], v215 offset:37888
	ds_read_b128 v[172:175], v215 offset:39936
	global_load_lds_dwordx4 v182, s[26:27]
	s_mov_b32 m0, s40
	s_nop 0
	global_load_lds_dwordx4 v178, s[26:27]
	s_waitcnt lgkmcnt(8)
	s_setprio 1
	s_barrier
	s_waitcnt lgkmcnt(4)
	v_mfma_f32_16x16x32_bf16 v[124:127], v[128:131], v[144:147], v[124:127]
	v_mfma_f32_16x16x32_bf16 v[120:123], v[136:139], v[144:147], v[120:123]
	v_mfma_f32_16x16x32_bf16 v[108:111], v[128:131], v[152:155], v[108:111]
	v_mfma_f32_16x16x32_bf16 v[104:107], v[136:139], v[152:155], v[104:107]
	v_mfma_f32_16x16x32_bf16 v[92:95], v[128:131], v[160:163], v[92:95]
	v_mfma_f32_16x16x32_bf16 v[88:91], v[136:139], v[160:163], v[88:91]
	v_mfma_f32_16x16x32_bf16 v[76:79], v[128:131], v[168:171], v[76:79]
	v_mfma_f32_16x16x32_bf16 v[72:75], v[136:139], v[168:171], v[72:75]
	s_waitcnt lgkmcnt(0)
	v_mfma_f32_16x16x32_bf16 v[124:127], v[132:135], v[148:151], v[124:127]
	v_mfma_f32_16x16x32_bf16 v[120:123], v[140:143], v[148:151], v[120:123]
	v_mfma_f32_16x16x32_bf16 v[108:111], v[132:135], v[156:159], v[108:111]
	v_mfma_f32_16x16x32_bf16 v[104:107], v[140:143], v[156:159], v[104:107]
	v_mfma_f32_16x16x32_bf16 v[92:95], v[132:135], v[164:167], v[92:95]
	v_mfma_f32_16x16x32_bf16 v[88:91], v[140:143], v[164:167], v[88:91]
	v_mfma_f32_16x16x32_bf16 v[76:79], v[132:135], v[172:175], v[76:79]
	v_mfma_f32_16x16x32_bf16 v[72:75], v[140:143], v[172:175], v[72:75]
	s_barrier
	s_setprio 0
	s_add_i32 s26, 0, 0x1c000
	s_add_i32 s27, s55, s35
	v_add_u32_e32 v204, s26, v212
	s_mov_b32 m0, s27
	ds_read_b128 v[192:195], v204
	ds_read_b128 v[196:199], v204 offset:1024
	ds_read_b128 v[200:203], v204 offset:2048
	ds_read_b128 v[204:207], v204 offset:3072
	global_load_lds_dwordx4 v180, s[98:99]
	s_add_i32 m0, s27, 0x2000
	s_nop 0
	global_load_lds_dwordx4 v176, s[98:99]
	s_setprio 1
	s_barrier
	s_waitcnt lgkmcnt(0)
	v_mfma_f32_16x16x32_bf16 v[116:119], v[192:195], v[144:147], v[116:119]
	v_mfma_f32_16x16x32_bf16 v[112:115], v[200:203], v[144:147], v[112:115]
	v_mfma_f32_16x16x32_bf16 v[100:103], v[192:195], v[152:155], v[100:103]
	v_mfma_f32_16x16x32_bf16 v[96:99], v[200:203], v[152:155], v[96:99]
	v_mfma_f32_16x16x32_bf16 v[84:87], v[192:195], v[160:163], v[84:87]
	v_mfma_f32_16x16x32_bf16 v[80:83], v[200:203], v[160:163], v[80:83]
	v_mfma_f32_16x16x32_bf16 v[68:71], v[192:195], v[168:171], v[68:71]
	v_mfma_f32_16x16x32_bf16 v[64:67], v[200:203], v[168:171], v[64:67]
	v_mfma_f32_16x16x32_bf16 v[116:119], v[196:199], v[148:151], v[116:119]
	v_mfma_f32_16x16x32_bf16 v[112:115], v[204:207], v[148:151], v[112:115]
	v_mfma_f32_16x16x32_bf16 v[100:103], v[196:199], v[156:159], v[100:103]
	v_mfma_f32_16x16x32_bf16 v[96:99], v[204:207], v[156:159], v[96:99]
	v_mfma_f32_16x16x32_bf16 v[84:87], v[196:199], v[164:167], v[84:87]
	v_mfma_f32_16x16x32_bf16 v[80:83], v[204:207], v[164:167], v[80:83]
	v_mfma_f32_16x16x32_bf16 v[68:71], v[196:199], v[172:175], v[68:71]
	v_mfma_f32_16x16x32_bf16 v[64:67], v[204:207], v[172:175], v[64:67]
	s_barrier
	s_setprio 0
	s_mov_b32 m0, s44
	ds_read_b128 v[144:147], v215 offset:49152
	ds_read_b128 v[152:155], v215 offset:51200
	ds_read_b128 v[160:163], v215 offset:53248
	ds_read_b128 v[168:171], v215 offset:55296
	ds_read_b128 v[148:151], v215 offset:50176
	ds_read_b128 v[156:159], v215 offset:52224
	ds_read_b128 v[164:167], v215 offset:54272
	ds_read_b128 v[172:175], v215 offset:56320
	global_load_lds_dwordx4 v182, s[100:101]
	s_mov_b32 m0, s45
	s_nop 0
	global_load_lds_dwordx4 v178, s[100:101]
	s_waitcnt vmcnt(10)
	s_setprio 1
	s_barrier
	s_waitcnt lgkmcnt(4)
	v_mfma_f32_16x16x32_bf16 v[60:63], v[128:131], v[144:147], v[60:63]
	v_mfma_f32_16x16x32_bf16 v[56:59], v[136:139], v[144:147], v[56:59]
	v_mfma_f32_16x16x32_bf16 v[44:47], v[128:131], v[152:155], v[44:47]
	v_mfma_f32_16x16x32_bf16 v[40:43], v[136:139], v[152:155], v[40:43]
	v_mfma_f32_16x16x32_bf16 v[28:31], v[128:131], v[160:163], v[28:31]
	v_mfma_f32_16x16x32_bf16 v[24:27], v[136:139], v[160:163], v[24:27]
	v_mfma_f32_16x16x32_bf16 v[12:15], v[128:131], v[168:171], v[12:15]
	v_mfma_f32_16x16x32_bf16 v[8:11], v[136:139], v[168:171], v[8:11]
	s_waitcnt lgkmcnt(0)
	v_mfma_f32_16x16x32_bf16 v[60:63], v[132:135], v[148:151], v[60:63]
	v_mfma_f32_16x16x32_bf16 v[56:59], v[140:143], v[148:151], v[56:59]
	v_mfma_f32_16x16x32_bf16 v[44:47], v[132:135], v[156:159], v[44:47]
	v_mfma_f32_16x16x32_bf16 v[40:43], v[140:143], v[156:159], v[40:43]
	v_mfma_f32_16x16x32_bf16 v[28:31], v[132:135], v[164:167], v[28:31]
	v_mfma_f32_16x16x32_bf16 v[24:27], v[140:143], v[164:167], v[24:27]
	v_mfma_f32_16x16x32_bf16 v[12:15], v[132:135], v[172:175], v[12:15]
	v_mfma_f32_16x16x32_bf16 v[8:11], v[140:143], v[172:175], v[8:11]
	s_barrier
; DI unsigned pack2(float lo, float hi) { f32x2 v = {lo, hi}; bf16v2 r = __builtin_convertvector(v, bf16v2); return __builtin_bit_cast(unsigned, r); }
; #define PG8_STAGE(bufoff, gbase, voff) do { _Pragma("unroll") for (int _i = 0; _i < 2; ++_i) \
;     __builtin_amdgcn_global_load_lds((const unsigned*)((const char*)(gbase) + (voff)[_i]), (LAS unsigned*)(lds + (bufoff) + ldsw + _i * 8192), 16, 0, 0); } while (0)
; #define PG8_WAIT_V(n) asm volatile("s_waitcnt vmcnt(" #n ")" ::: "memory")
; #define PG8_BAR __builtin_amdgcn_s_barrier()
;   DI void operator()(const f32x4 (&acc)[2][2][4][2], const Unit& u, int wr, int wc, int fr, int fq) const {
;     const int row0 = u.pm * BM + wr * 64 + fr, col0 = u.pn * BM + wc * 32 + 8 * fq;
; #pragma unroll
;     for (int ai = 0; ai < 2; ++ai) {
;       f32x4 bv[4][2][2];
; #pragma unroll
;       for (int m = 0; m < 4; ++m)
; #pragma unroll
;         for (int bj = 0; bj < 2; ++bj) {
;           const float* bp = base + (size_t)(row0 + ai * HALF + m * 16) * 2048 + col0 + bj * HALF;
;           bv[m][bj][0] = *(const f32x4*)bp; bv[m][bj][1] = *(const f32x4*)(bp + 4);
;         }
; #pragma unroll
;       for (int m = 0; m < 4; ++m) {
;         const int row = row0 + ai * HALF + m * 16;
;         const size_t off = (size_t)row * 2048 + col0;
;         float ss = 0.f;
; #pragma unroll
;         for (int bj = 0; bj < 2; ++bj) {
;           const f32x4 v0 = acc[ai][bj][m][0] + bv[m][bj][0], v1 = acc[ai][bj][m][1] + bv[m][bj][1];
;           *(f32x4*)(C + off + bj * HALF) = v0; *(f32x4*)(C + off + bj * HALF + 4) = v1;
;           if (xb) {
;             u32x4 w; w.x = pack2(v0[0], v0[1]); w.y = pack2(v0[2], v0[3]); w.z = pack2(v1[0], v1[1]); w.w = pack2(v1[2], v1[3]);
;             *(u32x4*)(xb + off + bj * HALF) = w;
;             ss += v0[0] * v0[0] + v0[1] * v0[1] + v0[2] * v0[2] + v0[3] * v0[3] + v1[0] * v1[0] + v1[1] * v1[1] + v1[2] * v1[2] + v1[3] * v1[3];
;           }
;         }
;         if (xb) {
;           ss += __shfl_xor(ss, 16); ss += __shfl_xor(ss, 32);
;           if (fq == 0) ssq[(size_t)row * 32 + u.pn * 4 + wc] = ss;
; template <class Epi, class Sched = StaticOrder>
; DI void gemm_phase(LAS unsigned char* lds, const Gemm g, const Sched& S, const Epi& E) {
;     ...
;       PG8_STAGE(PG8_SB(1, 1), b3 + hstep, voffB);
;       PG8_WAIT_V(6); PG8_BAR; PG8_MMA(1, 1, At, B1); PG8_BAR;
;     }
	s_setprio 0
	s_add_u32 s24, s24, 0x80080
	s_addc_u32 s25, s25, 0
	s_add_i32 s26, s26, s35
	s_mov_b32 m0, s26
	s_nop 0
	global_load_lds_dwordx4 v180, s[24:25]
	s_add_i32 m0, s26, 0x2000
	s_nop 0
	global_load_lds_dwordx4 v176, s[24:25]
	ds_read_b128 v[128:131], v214
	ds_read_b128 v[132:135], v214 offset:1024
	ds_read_b128 v[136:139], v214 offset:2048
	ds_read_b128 v[140:143], v214 offset:3072
	s_waitcnt vmcnt(6)
	s_setprio 1
	s_barrier
	v_mfma_f32_16x16x32_bf16 v[52:55], v[192:195], v[144:147], v[52:55]
	v_mfma_f32_16x16x32_bf16 v[48:51], v[200:203], v[144:147], v[48:51]
	v_mfma_f32_16x16x32_bf16 v[36:39], v[192:195], v[152:155], v[36:39]
	v_mfma_f32_16x16x32_bf16 v[32:35], v[200:203], v[152:155], v[32:35]
	v_mfma_f32_16x16x32_bf16 v[20:23], v[192:195], v[160:163], v[20:23]
	v_mfma_f32_16x16x32_bf16 v[16:19], v[200:203], v[160:163], v[16:19]
	v_mfma_f32_16x16x32_bf16 v[4:7], v[192:195], v[168:171], v[4:7]
	v_mfma_f32_16x16x32_bf16 v[0:3], v[200:203], v[168:171], v[0:3]
	v_mfma_f32_16x16x32_bf16 v[52:55], v[196:199], v[148:151], v[52:55]
	v_mfma_f32_16x16x32_bf16 v[48:51], v[204:207], v[148:151], v[48:51]
	v_mfma_f32_16x16x32_bf16 v[36:39], v[196:199], v[156:159], v[36:39]
	v_mfma_f32_16x16x32_bf16 v[32:35], v[204:207], v[156:159], v[32:35]
	v_mfma_f32_16x16x32_bf16 v[20:23], v[196:199], v[164:167], v[20:23]
	v_mfma_f32_16x16x32_bf16 v[16:19], v[204:207], v[164:167], v[16:19]
	v_mfma_f32_16x16x32_bf16 v[4:7], v[196:199], v[172:175], v[4:7]
	v_mfma_f32_16x16x32_bf16 v[0:3], v[204:207], v[172:175], v[0:3]
	s_add_i32 s54, s54, 2
	s_add_u32 s22, s22, 0x100
	s_addc_u32 s23, s23, 0
	s_add_u32 s52, s52, 0x100
	s_addc_u32 s53, s53, 0
	s_cmp_gt_u32 s54, 29
	s_barrier
	s_setprio 0
	s_cbranch_scc0 .LBB0_1194
	s_waitcnt lgkmcnt(0)
	v_lshl_add_u32 v194, s12, 8, v211
	v_lshl_or_b32 v192, s42, 8, v213
	v_readlane_b32 s52, v243, 3
	v_ashrrev_i32_e32 v193, 31, v192
	v_readlane_b32 s66, v243, 17
	v_readlane_b32 s67, v243, 18
	v_ashrrev_i32_e32 v195, 31, v194
	v_lshlrev_b64 v[128:129], 13, v[194:195]
	v_lshl_add_u64 v[196:197], v[192:193], 2, s[66:67]
	v_lshl_add_u64 v[236:237], v[196:197], 0, v[128:129]
	global_load_dwordx4 v[220:223], v[236:237], off
	global_load_dwordx4 v[224:227], v[236:237], off offset:16
	global_load_dwordx4 v[228:231], v[236:237], off offset:512
	global_load_dwordx4 v[232:235], v[236:237], off offset:528
	v_or_b32_e32 v206, 16, v194
	v_or_b32_e32 v202, 32, v194
	v_or_b32_e32 v198, 48, v194
	v_ashrrev_i32_e32 v207, 31, v206
	v_ashrrev_i32_e32 v203, 31, v202
	v_ashrrev_i32_e32 v199, 31, v198
	v_lshlrev_b64 v[128:129], 13, v[206:207]
	v_lshlrev_b64 v[130:131], 13, v[202:203]
	v_lshlrev_b64 v[132:133], 13, v[198:199]
	v_lshl_add_u64 v[208:209], v[196:197], 0, v[128:129]
	v_lshl_add_u64 v[204:205], v[196:197], 0, v[130:131]
	v_lshl_add_u64 v[200:201], v[196:197], 0, v[132:133]
	global_load_dwordx4 v[168:171], v[208:209], off offset:16
	global_load_dwordx4 v[172:175], v[208:209], off
	global_load_dwordx4 v[160:163], v[208:209], off offset:528
	global_load_dwordx4 v[164:167], v[208:209], off offset:512
	global_load_dwordx4 v[152:155], v[204:205], off offset:16
	global_load_dwordx4 v[156:159], v[204:205], off
	global_load_dwordx4 v[144:147], v[204:205], off offset:528
	global_load_dwordx4 v[148:151], v[204:205], off offset:512
	global_load_dwordx4 v[136:139], v[200:201], off offset:16
	global_load_dwordx4 v[140:143], v[200:201], off
	global_load_dwordx4 v[128:131], v[200:201], off offset:528
	global_load_dwordx4 v[132:135], v[200:201], off offset:512
	v_and_b32_e32 v218, 64, v217
	v_xor_b32_e32 v238, 16, v217
	v_add_u32_e32 v240, 64, v218
	v_xor_b32_e32 v239, 32, v217
	v_cmp_lt_i32_e32 vcc, v238, v240
	v_lshlrev_b64 v[218:219], 11, v[194:195]
	s_lshl_b32 s22, s42, 2
	v_cndmask_b32_e32 v241, v217, v238, vcc
	v_cmp_lt_i32_e32 vcc, v239, v240
	s_ashr_i32 s23, s22, 31
	v_readlane_b32 s53, v243, 4
	v_cndmask_b32_e32 v240, v217, v239, vcc
	v_lshl_add_u64 v[238:239], v[218:219], 0, v[192:193]
	v_lshlrev_b32_e32 v218, 2, v241
	v_lshl_add_u64 v[238:239], v[238:239], 1, s[2:3]
	v_readlane_b32 s54, v243, 5
	v_readlane_b32 s55, v243, 6
	v_readlane_b32 s56, v243, 7
	v_readlane_b32 s57, v243, 8
	v_readlane_b32 s58, v243, 9
	v_readlane_b32 s59, v243, 10
	v_readlane_b32 s60, v243, 11
	v_readlane_b32 s61, v243, 12
	v_readlane_b32 s62, v243, 13
	v_readlane_b32 s63, v243, 14
	v_readlane_b32 s64, v243, 15
	v_readlane_b32 s65, v243, 16
	s_waitcnt vmcnt(0)
	v_pk_add_f32 v[126:127], v[126:127], v[222:223]
	v_pk_add_f32 v[124:125], v[124:125], v[220:221]
	v_pk_add_f32 v[116:117], v[116:117], v[228:229]
	v_pk_add_f32 v[122:123], v[122:123], v[226:227]
	v_pk_add_f32 v[120:121], v[120:121], v[224:225]
	v_pk_add_f32 v[220:221], v[112:113], v[232:233]
	global_store_dwordx4 v[236:237], v[124:127], off
	global_store_dwordx4 v[236:237], v[120:123], off offset:16
	v_cvt_pk_bf16_f32 v112, v124, v125
	v_mul_f32_e32 v125, v125, v125
	v_mul_f32_e32 v219, v117, v117
	v_pk_add_f32 v[118:119], v[118:119], v[230:231]
	v_fmac_f32_e32 v125, v124, v124
	v_fmac_f32_e32 v219, v116, v116
	v_fmac_f32_e32 v125, v126, v126
	v_fmac_f32_e32 v219, v118, v118
	v_fmac_f32_e32 v125, v127, v127
	v_fmac_f32_e32 v219, v119, v119
	v_fmac_f32_e32 v125, v120, v120
	v_fmac_f32_e32 v219, v220, v220
	v_pk_add_f32 v[222:223], v[114:115], v[234:235]
	v_fmac_f32_e32 v125, v121, v121
	v_fmac_f32_e32 v219, v221, v221
	v_fmac_f32_e32 v125, v122, v122
	v_fmac_f32_e32 v219, v222, v222
	v_fmac_f32_e32 v125, v123, v123
	v_fmac_f32_e32 v219, v223, v223
	v_cvt_pk_bf16_f32 v114, v120, v121
	v_add_f32_e32 v121, v125, v219
	v_cvt_pk_bf16_f32 v115, v122, v123
	ds_bpermute_b32 v122, v218, v121
	v_cvt_pk_bf16_f32 v113, v126, v127
	global_store_dwordx4 v[238:239], v[112:115], off
	global_store_dwordx4 v[236:237], v[116:119], off offset:512
	global_store_dwordx4 v[236:237], v[220:223], off offset:528
	v_lshlrev_b32_e32 v126, 2, v240
	v_cvt_pk_bf16_f32 v120, v116, v117
	s_waitcnt lgkmcnt(0)
	v_add_f32_e32 v112, v121, v122
	ds_bpermute_b32 v113, v126, v112
	v_cvt_pk_bf16_f32 v121, v118, v119
	v_cvt_pk_bf16_f32 v122, v220, v221
	v_cvt_pk_bf16_f32 v123, v222, v223
	global_store_dwordx4 v[238:239], v[120:123], off offset:256
	s_and_saveexec_b64 s[24:25], s[0:1]
	s_cbranch_execz .LBB0_1197
	s_waitcnt lgkmcnt(0)
	v_add_f32_e32 v114, v112, v113
	v_lshlrev_b64 v[112:113], 7, v[194:195]
	v_lshl_add_u64 v[112:113], s[8:9], 0, v[112:113]
	v_lshl_add_u64 v[112:113], s[22:23], 2, v[112:113]
	s_lshl_b32 s12, s41, 2
	v_lshl_add_u64 v[112:113], v[112:113], 0, s[12:13]
	global_store_dword v[112:113], v114, off

; #define PG8_STAGE(bufoff, gbase, voff) do { _Pragma("unroll") for (int _i = 0; _i < 2; ++_i) \
;     __builtin_amdgcn_global_load_lds((const unsigned*)((const char*)(gbase) + (voff)[_i]), (LAS unsigned*)(lds + (bufoff) + ldsw + _i * 8192), 16, 0, 0); } while (0)
; #define PG8_LDA(dst, b, h) do { _Pragma("unroll") for (int m = 0; m < 4; ++m) _Pragma("unroll") for (int k = 0; k < 2; ++k) dst[m][k] = *(const LAS bf16x8*)(lds + PG8_SA(b, h) + aoff + m * 2048 + k * 1024); } while (0)
; #define PG8_LDB(dst, b, h) do { _Pragma("unroll") for (int n = 0; n < 2; ++n) _Pragma("unroll") for (int k = 0; k < 2; ++k) dst[n][k] = *(const LAS bf16x8*)(lds + PG8_SB(b, h) + boff + n * 2048 + k * 1024); } while (0)
; #define PG8_MMA(ai, bj, At, Bt) do { __builtin_amdgcn_s_setprio(1); _Pragma("unroll") for (int m = 0; m < 4; ++m) _Pragma("unroll") for (int n = 0; n < 2; ++n) _Pragma("unroll") for (int k = 0; k < 2; ++k) \
;     acc[ai][bj][m][n] = __builtin_amdgcn_mfma_f32_16x16x32_bf16(Bt[n][k], At[m][k], acc[ai][bj][m][n], 0, 0, 0); __builtin_amdgcn_s_setprio(0); } while (0)
; #define PG8_WAIT_V(n) asm volatile("s_waitcnt vmcnt(" #n ")" ::: "memory")
; #define PG8_WAIT_L(n) asm volatile("s_waitcnt lgkmcnt(" #n ")" ::: "memory")
; template <class Epi, class Sched = StaticOrder>
; DI void gemm_phase(LAS unsigned char* lds, const Gemm g, const Sched& S, const Epi& E) {
;     ...
;     for (int t = 0; t < nt; t += 2) {
;       const bool last = (t == nt - 2);
;       const char* a1 = cA + (size_t)(t + 1) * kstep;
;       const char* a2 = last ? nA : cA + (size_t)(t + 2) * kstep; const char* b2 = last ? nB : cB + (size_t)(t + 2) * kstep;
;       const char* a3 = a2 + kstep; const char* b3 = b2 + kstep;
;       PG8_LDB(B0, 0, 0); PG8_SCHED; PG8_LDA(At, 0, 0); PG8_STAGE(PG8_SA(1, 1), a1 + hstep, voffA);
;       PG8_WAIT_L(8); PG8_BAR; PG8_WAIT_L(0); PG8_MMA(0, 0, At, B0); PG8_BAR; PG8_SCHED;
;       PG8_LDB(B1, 0, 1); PG8_STAGE(PG8_SB(0, 0), b2, voffB);
;       PG8_BAR; PG8_WAIT_L(0); PG8_MMA(0, 1, At, B1); PG8_BAR;
;       PG8_LDA(At, 0, 1); PG8_STAGE(PG8_SA(0, 0), a2, voffA);
;       PG8_BAR; PG8_WAIT_L(0); PG8_MMA(1, 0, At, B0); PG8_BAR; PG8_SCHED;
;       PG8_STAGE(PG8_SB(0, 1), b2 + hstep, voffB);
;       PG8_WAIT_V(6); PG8_BAR; PG8_MMA(1, 1, At, B1); PG8_BAR;
;       PG8_LDB(B0, 1, 0); PG8_SCHED; PG8_LDA(At, 1, 0); PG8_STAGE(PG8_SA(0, 1), a2 + hstep, voffA);
.LBB0_1277:
	s_add_u32 s48, s14, 0xfff80080
	s_addc_u32 s49, s15, -1
	s_cmp_eq_u32 s58, 28
	s_cselect_b32 s51, s41, s49
	s_cselect_b32 s50, s42, s48
	s_cselect_b32 s49, s39, s53
	s_cselect_b32 s48, s43, s52
	s_add_i32 m0, s64, 0xc000
	ds_read_b128 v[80:83], v202
	ds_read_b128 v[88:91], v202 offset:2048
	ds_read_b128 v[180:183], v202 offset:4096
	ds_read_b128 v[188:191], v202 offset:6144
	ds_read_b128 v[84:87], v202 offset:1024
	ds_read_b128 v[92:95], v202 offset:3072
	ds_read_b128 v[184:187], v202 offset:5120
	ds_read_b128 v[192:195], v202 offset:7168
	global_load_lds_dwordx4 v170, s[14:15]
	s_add_i32 m0, s64, 0xe000
	s_nop 0
	global_load_lds_dwordx4 v172, s[14:15]
	s_waitcnt lgkmcnt(8)
	s_setprio 1
	s_barrier
	s_waitcnt lgkmcnt(4)
	v_mfma_f32_16x16x32_bf16 v[156:159], v[64:67], v[80:83], v[156:159]
	v_mfma_f32_16x16x32_bf16 v[144:147], v[72:75], v[80:83], v[144:147]
	v_mfma_f32_16x16x32_bf16 v[140:143], v[64:67], v[88:91], v[140:143]
	v_mfma_f32_16x16x32_bf16 v[132:135], v[72:75], v[88:91], v[132:135]
	v_mfma_f32_16x16x32_bf16 v[124:127], v[64:67], v[180:183], v[124:127]
	v_mfma_f32_16x16x32_bf16 v[116:119], v[72:75], v[180:183], v[116:119]
	v_mfma_f32_16x16x32_bf16 v[112:115], v[64:67], v[188:191], v[112:115]
	v_mfma_f32_16x16x32_bf16 v[108:111], v[72:75], v[188:191], v[108:111]
	s_waitcnt lgkmcnt(0)
	v_mfma_f32_16x16x32_bf16 v[156:159], v[68:71], v[84:87], v[156:159]
	v_mfma_f32_16x16x32_bf16 v[144:147], v[76:79], v[84:87], v[144:147]
	v_mfma_f32_16x16x32_bf16 v[140:143], v[68:71], v[92:95], v[140:143]
	v_mfma_f32_16x16x32_bf16 v[132:135], v[76:79], v[92:95], v[132:135]
	v_mfma_f32_16x16x32_bf16 v[124:127], v[68:71], v[184:187], v[124:127]
	v_mfma_f32_16x16x32_bf16 v[116:119], v[76:79], v[184:187], v[116:119]
	v_mfma_f32_16x16x32_bf16 v[112:115], v[68:71], v[192:195], v[112:115]
	v_mfma_f32_16x16x32_bf16 v[108:111], v[76:79], v[192:195], v[108:111]
	s_barrier
	s_setprio 0
	s_add_i32 s59, s72, s62
	s_add_u32 s98, s48, 0x80
	s_addc_u32 s99, s49, 0
	s_add_u32 s100, s50, 0x80
	s_addc_u32 s101, s51, 0
	s_mov_b32 m0, s59
	ds_read_b128 v[206:209], v203
	ds_read_b128 v[212:215], v203 offset:1024
	ds_read_b128 v[216:219], v203 offset:2048
	ds_read_b128 v[220:223], v203 offset:3072
	global_load_lds_dwordx4 v164, s[48:49]
	s_add_i32 m0, s59, 0x2000
	s_nop 0
	global_load_lds_dwordx4 v160, s[48:49]
	s_setprio 1
	s_barrier
	s_waitcnt lgkmcnt(0)
	v_mfma_f32_16x16x32_bf16 v[152:155], v[206:209], v[80:83], v[152:155]
	v_mfma_f32_16x16x32_bf16 v[80:83], v[216:219], v[80:83], v[148:151]
	v_mfma_f32_16x16x32_bf16 v[152:155], v[212:215], v[84:87], v[152:155]
	v_mfma_f32_16x16x32_bf16 v[80:83], v[220:223], v[84:87], v[80:83]
	v_mfma_f32_16x16x32_bf16 v[84:87], v[206:209], v[88:91], v[136:139]
	v_mfma_f32_16x16x32_bf16 v[88:91], v[216:219], v[88:91], v[128:131]
	v_mfma_f32_16x16x32_bf16 v[104:107], v[216:219], v[180:183], v[104:107]
	v_mfma_f32_16x16x32_bf16 v[100:103], v[206:209], v[188:191], v[100:103]
	v_mfma_f32_16x16x32_bf16 v[96:99], v[216:219], v[188:191], v[96:99]
	v_mfma_f32_16x16x32_bf16 v[84:87], v[212:215], v[92:95], v[84:87]
	v_mfma_f32_16x16x32_bf16 v[88:91], v[220:223], v[92:95], v[88:91]
	v_mfma_f32_16x16x32_bf16 v[92:95], v[206:209], v[180:183], v[120:123]
	v_mfma_f32_16x16x32_bf16 v[104:107], v[220:223], v[184:187], v[104:107]
	v_mfma_f32_16x16x32_bf16 v[100:103], v[212:215], v[192:195], v[100:103]
	v_mfma_f32_16x16x32_bf16 v[96:99], v[220:223], v[192:195], v[96:99]
	v_mfma_f32_16x16x32_bf16 v[92:95], v[212:215], v[184:187], v[92:95]
	s_barrier
	s_setprio 0
	s_mov_b32 m0, s64
	ds_read_b128 v[120:123], v202 offset:16384
	ds_read_b128 v[136:139], v202 offset:18432
	ds_read_b128 v[180:183], v202 offset:20480
	ds_read_b128 v[188:191], v202 offset:22528
	ds_read_b128 v[128:131], v202 offset:17408
	ds_read_b128 v[148:151], v202 offset:19456
	ds_read_b128 v[184:187], v202 offset:21504
	ds_read_b128 v[192:195], v202 offset:23552
	global_load_lds_dwordx4 v166, s[50:51]
	s_mov_b32 m0, s65
	s_nop 0
	global_load_lds_dwordx4 v162, s[50:51]
	s_waitcnt vmcnt(10)
	s_setprio 1
	s_barrier
	s_waitcnt lgkmcnt(4)
	v_mfma_f32_16x16x32_bf16 v[60:63], v[64:67], v[120:123], v[60:63]
	v_mfma_f32_16x16x32_bf16 v[48:51], v[72:75], v[120:123], v[48:51]
	v_mfma_f32_16x16x32_bf16 v[44:47], v[64:67], v[136:139], v[44:47]
	v_mfma_f32_16x16x32_bf16 v[36:39], v[72:75], v[136:139], v[36:39]
	v_mfma_f32_16x16x32_bf16 v[28:31], v[64:67], v[180:183], v[28:31]
	v_mfma_f32_16x16x32_bf16 v[20:23], v[72:75], v[180:183], v[20:23]
	v_mfma_f32_16x16x32_bf16 v[16:19], v[64:67], v[188:191], v[16:19]
	v_mfma_f32_16x16x32_bf16 v[12:15], v[72:75], v[188:191], v[12:15]
	s_waitcnt lgkmcnt(0)
	v_mfma_f32_16x16x32_bf16 v[60:63], v[68:71], v[128:131], v[60:63]
	v_mfma_f32_16x16x32_bf16 v[48:51], v[76:79], v[128:131], v[48:51]
	v_mfma_f32_16x16x32_bf16 v[44:47], v[68:71], v[148:151], v[44:47]
	v_mfma_f32_16x16x32_bf16 v[36:39], v[76:79], v[148:151], v[36:39]
	v_mfma_f32_16x16x32_bf16 v[28:31], v[68:71], v[184:187], v[28:31]
	v_mfma_f32_16x16x32_bf16 v[20:23], v[76:79], v[184:187], v[20:23]
	v_mfma_f32_16x16x32_bf16 v[16:19], v[68:71], v[192:195], v[16:19]
	v_mfma_f32_16x16x32_bf16 v[12:15], v[76:79], v[192:195], v[12:15]
	s_barrier
	s_setprio 0
	s_add_u32 s78, s48, 0x80000
	s_addc_u32 s79, s49, 0
	s_add_i32 s59, s73, s62
	s_mov_b32 m0, s59
	s_nop 0
	global_load_lds_dwordx4 v164, s[78:79]
	s_add_i32 m0, s59, 0x2000
	s_nop 0
	global_load_lds_dwordx4 v160, s[78:79]
	s_add_i32 s59, 0, 0x18000
	v_add_u32_e32 v76, s59, v198
	ds_read_b128 v[64:67], v76
	ds_read_b128 v[68:71], v76 offset:1024
	ds_read_b128 v[72:75], v76 offset:2048
	ds_read_b128 v[76:79], v76 offset:3072
	s_waitcnt vmcnt(6)
	s_setprio 1
	s_barrier
; #define PG8_STAGE(bufoff, gbase, voff) do { _Pragma("unroll") for (int _i = 0; _i < 2; ++_i) \
;     __builtin_amdgcn_global_load_lds((const unsigned*)((const char*)(gbase) + (voff)[_i]), (LAS unsigned*)(lds + (bufoff) + ldsw + _i * 8192), 16, 0, 0); } while (0)
; #define PG8_LDA(dst, b, h) do { _Pragma("unroll") for (int m = 0; m < 4; ++m) _Pragma("unroll") for (int k = 0; k < 2; ++k) dst[m][k] = *(const LAS bf16x8*)(lds + PG8_SA(b, h) + aoff + m * 2048 + k * 1024); } while (0)
; #define PG8_LDB(dst, b, h) do { _Pragma("unroll") for (int n = 0; n < 2; ++n) _Pragma("unroll") for (int k = 0; k < 2; ++k) dst[n][k] = *(const LAS bf16x8*)(lds + PG8_SB(b, h) + boff + n * 2048 + k * 1024); } while (0)
; #define PG8_MMA(ai, bj, At, Bt) do { __builtin_amdgcn_s_setprio(1); _Pragma("unroll") for (int m = 0; m < 4; ++m) _Pragma("unroll") for (int n = 0; n < 2; ++n) _Pragma("unroll") for (int k = 0; k < 2; ++k) \
;     acc[ai][bj][m][n] = __builtin_amdgcn_mfma_f32_16x16x32_bf16(Bt[n][k], At[m][k], acc[ai][bj][m][n], 0, 0, 0); __builtin_amdgcn_s_setprio(0); } while (0)
; #define PG8_WAIT_V(n) asm volatile("s_waitcnt vmcnt(" #n ")" ::: "memory")
; #define PG8_WAIT_L(n) asm volatile("s_waitcnt lgkmcnt(" #n ")" ::: "memory")
; #define PG8_BAR __builtin_amdgcn_s_barrier()
; #define PG8_SCHED __builtin_amdgcn_sched_barrier(0)
; template <class Epi, class Sched = StaticOrder>
; DI void gemm_phase(LAS unsigned char* lds, const Gemm g, const Sched& S, const Epi& E) {
;     ...
;       PG8_WAIT_V(6); PG8_BAR; PG8_MMA(1, 1, At, B1); PG8_BAR;
;       PG8_LDB(B0, 1, 0); PG8_SCHED; PG8_LDA(At, 1, 0); PG8_STAGE(PG8_SA(0, 1), a2 + hstep, voffA);
;       PG8_WAIT_L(8); PG8_BAR; PG8_WAIT_L(0); PG8_MMA(0, 0, At, B0); PG8_BAR; PG8_SCHED;
;       PG8_LDB(B1, 1, 1); PG8_STAGE(PG8_SB(1, 0), b3, voffB);
;       PG8_BAR; PG8_WAIT_L(0); PG8_MMA(0, 1, At, B1); PG8_BAR;
;       PG8_LDA(At, 1, 1); PG8_STAGE(PG8_SA(1, 0), a3, voffA);
;       PG8_BAR; PG8_WAIT_L(0); PG8_MMA(1, 0, At, B0); PG8_BAR; PG8_SCHED;
	v_mfma_f32_16x16x32_bf16 v[56:59], v[206:209], v[120:123], v[56:59]
	v_mfma_f32_16x16x32_bf16 v[52:55], v[216:219], v[120:123], v[52:55]
	v_mfma_f32_16x16x32_bf16 v[40:43], v[206:209], v[136:139], v[40:43]
	v_mfma_f32_16x16x32_bf16 v[32:35], v[216:219], v[136:139], v[32:35]
	v_mfma_f32_16x16x32_bf16 v[24:27], v[206:209], v[180:183], v[24:27]
	v_mfma_f32_16x16x32_bf16 v[8:11], v[216:219], v[180:183], v[8:11]
	v_mfma_f32_16x16x32_bf16 v[4:7], v[206:209], v[188:191], v[4:7]
	v_mfma_f32_16x16x32_bf16 v[0:3], v[216:219], v[188:191], v[0:3]
	v_mfma_f32_16x16x32_bf16 v[56:59], v[212:215], v[128:131], v[56:59]
	v_mfma_f32_16x16x32_bf16 v[52:55], v[220:223], v[128:131], v[52:55]
	v_mfma_f32_16x16x32_bf16 v[40:43], v[212:215], v[148:151], v[40:43]
	v_mfma_f32_16x16x32_bf16 v[32:35], v[220:223], v[148:151], v[32:35]
	v_mfma_f32_16x16x32_bf16 v[24:27], v[212:215], v[184:187], v[24:27]
	v_mfma_f32_16x16x32_bf16 v[8:11], v[220:223], v[184:187], v[8:11]
	v_mfma_f32_16x16x32_bf16 v[4:7], v[212:215], v[192:195], v[4:7]
	v_mfma_f32_16x16x32_bf16 v[0:3], v[220:223], v[192:195], v[0:3]
	s_barrier
	s_setprio 0
	s_add_u32 s50, s50, 0x80000
	s_addc_u32 s51, s51, 0
	s_mov_b32 m0, s66
	ds_read_b128 v[120:123], v202 offset:32768
	ds_read_b128 v[128:131], v202 offset:33792
	ds_read_b128 v[180:183], v202 offset:34816
	ds_read_b128 v[188:191], v202 offset:36864
	ds_read_b128 v[184:187], v202 offset:35840
	ds_read_b128 v[192:195], v202 offset:37888
	ds_read_b128 v[206:209], v202 offset:38912
	ds_read_b128 v[212:215], v202 offset:39936
	global_load_lds_dwordx4 v166, s[50:51]
	s_mov_b32 m0, s67
	s_nop 0
	global_load_lds_dwordx4 v162, s[50:51]
	s_waitcnt lgkmcnt(8)
	s_setprio 1
	s_barrier
	s_waitcnt lgkmcnt(4)
	v_mfma_f32_16x16x32_bf16 v[136:139], v[64:67], v[120:123], v[156:159]
	v_mfma_f32_16x16x32_bf16 v[156:159], v[68:71], v[128:131], v[136:139]
	v_mfma_f32_16x16x32_bf16 v[136:139], v[72:75], v[120:123], v[144:147]
	v_mfma_f32_16x16x32_bf16 v[144:147], v[76:79], v[128:131], v[136:139]
	v_mfma_f32_16x16x32_bf16 v[136:139], v[64:67], v[180:183], v[140:143]
	v_mfma_f32_16x16x32_bf16 v[132:135], v[72:75], v[180:183], v[132:135]
	v_mfma_f32_16x16x32_bf16 v[124:127], v[64:67], v[188:191], v[124:127]
	v_mfma_f32_16x16x32_bf16 v[116:119], v[72:75], v[188:191], v[116:119]
	s_waitcnt lgkmcnt(0)
	v_mfma_f32_16x16x32_bf16 v[112:115], v[64:67], v[206:209], v[112:115]
	v_mfma_f32_16x16x32_bf16 v[108:111], v[72:75], v[206:209], v[108:111]
	v_mfma_f32_16x16x32_bf16 v[140:143], v[68:71], v[184:187], v[136:139]
	v_mfma_f32_16x16x32_bf16 v[132:135], v[76:79], v[184:187], v[132:135]
	v_mfma_f32_16x16x32_bf16 v[124:127], v[68:71], v[192:195], v[124:127]
	v_mfma_f32_16x16x32_bf16 v[116:119], v[76:79], v[192:195], v[116:119]
	v_mfma_f32_16x16x32_bf16 v[112:115], v[68:71], v[212:215], v[112:115]
	v_mfma_f32_16x16x32_bf16 v[108:111], v[76:79], v[212:215], v[108:111]
	s_barrier
	s_setprio 0
	s_add_i32 s50, 0, 0x1c000
	v_add_u32_e32 v136, s50, v198
	s_add_i32 s51, s59, s62
	ds_read_b128 v[216:219], v136
	ds_read_b128 v[220:223], v136 offset:1024
	ds_read_b128 v[224:227], v136 offset:2048
	ds_read_b128 v[228:231], v136 offset:3072
	s_mov_b32 m0, s51
	s_nop 0
	global_load_lds_dwordx4 v164, s[98:99]
	s_add_i32 m0, s51, 0x2000
	s_nop 0
	global_load_lds_dwordx4 v160, s[98:99]
	s_setprio 1
	s_barrier
	s_waitcnt lgkmcnt(0)
	v_mfma_f32_16x16x32_bf16 v[80:83], v[224:227], v[120:123], v[80:83]
	v_mfma_f32_16x16x32_bf16 v[136:139], v[216:219], v[120:123], v[152:155]
	v_mfma_f32_16x16x32_bf16 v[148:151], v[228:231], v[128:131], v[80:83]
	v_mfma_f32_16x16x32_bf16 v[80:83], v[216:219], v[180:183], v[84:87]
	v_mfma_f32_16x16x32_bf16 v[152:155], v[220:223], v[128:131], v[136:139]
	v_mfma_f32_16x16x32_bf16 v[136:139], v[220:223], v[184:187], v[80:83]
	v_mfma_f32_16x16x32_bf16 v[80:83], v[224:227], v[180:183], v[88:91]
	v_mfma_f32_16x16x32_bf16 v[128:131], v[228:231], v[184:187], v[80:83]
	v_mfma_f32_16x16x32_bf16 v[80:83], v[216:219], v[188:191], v[92:95]
	v_mfma_f32_16x16x32_bf16 v[120:123], v[220:223], v[192:195], v[80:83]
	v_mfma_f32_16x16x32_bf16 v[80:83], v[224:227], v[188:191], v[104:107]
	v_mfma_f32_16x16x32_bf16 v[104:107], v[228:231], v[192:195], v[80:83]
	v_mfma_f32_16x16x32_bf16 v[80:83], v[216:219], v[206:209], v[100:103]
	v_mfma_f32_16x16x32_bf16 v[100:103], v[220:223], v[212:215], v[80:83]
	v_mfma_f32_16x16x32_bf16 v[80:83], v[224:227], v[206:209], v[96:99]
	v_mfma_f32_16x16x32_bf16 v[96:99], v[228:231], v[212:215], v[80:83]
	s_barrier
	s_setprio 0
	s_mov_b32 m0, s55
	s_nop 2
	ds_read_b128 v[80:83], v202 offset:49152
	ds_read_b128 v[88:91], v202 offset:51200
	ds_read_b128 v[180:183], v202 offset:53248
	ds_read_b128 v[188:191], v202 offset:55296
	ds_read_b128 v[84:87], v202 offset:50176
	ds_read_b128 v[92:95], v202 offset:52224
	ds_read_b128 v[184:187], v202 offset:54272
	ds_read_b128 v[192:195], v202 offset:56320
	global_load_lds_dwordx4 v166, s[100:101]
	s_mov_b32 m0, s68
	s_nop 0
	global_load_lds_dwordx4 v162, s[100:101]
	s_waitcnt vmcnt(10)
	s_setprio 1
	s_barrier
	s_waitcnt lgkmcnt(4)
	v_mfma_f32_16x16x32_bf16 v[60:63], v[64:67], v[80:83], v[60:63]
	v_mfma_f32_16x16x32_bf16 v[48:51], v[72:75], v[80:83], v[48:51]
	v_mfma_f32_16x16x32_bf16 v[44:47], v[64:67], v[88:91], v[44:47]
	v_mfma_f32_16x16x32_bf16 v[36:39], v[72:75], v[88:91], v[36:39]
	v_mfma_f32_16x16x32_bf16 v[28:31], v[64:67], v[180:183], v[28:31]
	v_mfma_f32_16x16x32_bf16 v[20:23], v[72:75], v[180:183], v[20:23]
	v_mfma_f32_16x16x32_bf16 v[16:19], v[64:67], v[188:191], v[16:19]
	v_mfma_f32_16x16x32_bf16 v[12:15], v[72:75], v[188:191], v[12:15]
	s_waitcnt lgkmcnt(0)
	v_mfma_f32_16x16x32_bf16 v[60:63], v[68:71], v[84:87], v[60:63]
	v_mfma_f32_16x16x32_bf16 v[48:51], v[76:79], v[84:87], v[48:51]
	v_mfma_f32_16x16x32_bf16 v[44:47], v[68:71], v[92:95], v[44:47]
	v_mfma_f32_16x16x32_bf16 v[36:39], v[76:79], v[92:95], v[36:39]
	v_mfma_f32_16x16x32_bf16 v[28:31], v[68:71], v[184:187], v[28:31]
	v_mfma_f32_16x16x32_bf16 v[20:23], v[76:79], v[184:187], v[20:23]
	v_mfma_f32_16x16x32_bf16 v[16:19], v[68:71], v[192:195], v[16:19]
	v_mfma_f32_16x16x32_bf16 v[12:15], v[76:79], v[192:195], v[12:15]
	s_barrier
; #define PG8_STAGE(bufoff, gbase, voff) do { _Pragma("unroll") for (int _i = 0; _i < 2; ++_i) \
;     __builtin_amdgcn_global_load_lds((const unsigned*)((const char*)(gbase) + (voff)[_i]), (LAS unsigned*)(lds + (bufoff) + ldsw + _i * 8192), 16, 0, 0); } while (0)
; #define PG8_LDA(dst, b, h) do { _Pragma("unroll") for (int m = 0; m < 4; ++m) _Pragma("unroll") for (int k = 0; k < 2; ++k) dst[m][k] = *(const LAS bf16x8*)(lds + PG8_SA(b, h) + aoff + m * 2048 + k * 1024); } while (0)
; #define PG8_LDB(dst, b, h) do { _Pragma("unroll") for (int n = 0; n < 2; ++n) _Pragma("unroll") for (int k = 0; k < 2; ++k) dst[n][k] = *(const LAS bf16x8*)(lds + PG8_SB(b, h) + boff + n * 2048 + k * 1024); } while (0)
; #define PG8_WAIT_V(n) asm volatile("s_waitcnt vmcnt(" #n ")" ::: "memory")
; #define PG8_WAIT_L(n) asm volatile("s_waitcnt lgkmcnt(" #n ")" ::: "memory")
; #define PG8_BAR __builtin_amdgcn_s_barrier()
; #define PG8_SCHED __builtin_amdgcn_sched_barrier(0)
;   DI void operator()(const f32x4 (&acc)[2][2][4][2], const Unit& u, int wr, int wc, int fr, int fq) const {
;     const int col = u.pn * 128 + wc * 32 + 8 * fq;
;     float w0[8], w1[8], w2[8], bb[8];
; #pragma unroll
;     for (int e = 0; e < 8; ++e) { w0[e] = cw[col + e]; w1[e] = cw[5632 + col + e]; w2[e] = cw[2 * 5632 + col + e]; bb[e] = cb[col + e]; }
; #pragma unroll
;     for (int ai = 0; ai < 2; ++ai) {
;       const int row0 = u.pm * BM + ai * HALF + wr * 64, span = row0 >> 6;
;       float rsv[4];
; #pragma unroll
;       for (int m = 0; m < 4; ++m) rsv[m] = row_rstd(ssq, row0 + 16 * m + fr, fq);
; template <class Epi, class Sched = StaticOrder>
; DI void gemm_phase(LAS unsigned char* lds, const Gemm g, const Sched& S, const Epi& E) {
;     ...
;       PG8_LDB(B0, 1, 0); PG8_SCHED; PG8_LDA(At, 1, 0); PG8_STAGE(PG8_SA(0, 1), a2 + hstep, voffA);
;       PG8_WAIT_L(8); PG8_BAR; PG8_WAIT_L(0); PG8_MMA(0, 0, At, B0); PG8_BAR; PG8_SCHED;
;       PG8_LDB(B1, 1, 1); PG8_STAGE(PG8_SB(1, 0), b3, voffB);
;       PG8_BAR; PG8_WAIT_L(0); PG8_MMA(0, 1, At, B1); PG8_BAR;
;       PG8_LDA(At, 1, 1); PG8_STAGE(PG8_SA(1, 0), a3, voffA);
;       PG8_BAR; PG8_WAIT_L(0); PG8_MMA(1, 0, At, B0); PG8_BAR; PG8_SCHED;
;       PG8_STAGE(PG8_SB(1, 1), b3 + hstep, voffB);
;       PG8_WAIT_V(6); PG8_BAR; PG8_MMA(1, 1, At, B1); PG8_BAR;
	s_setprio 0
	s_add_u32 s48, s48, 0x80080
	s_addc_u32 s49, s49, 0
	s_add_i32 s50, s50, s62
	s_mov_b32 m0, s50
	s_nop 0
	global_load_lds_dwordx4 v164, s[48:49]
	s_add_i32 m0, s50, 0x2000
	s_nop 0
	global_load_lds_dwordx4 v160, s[48:49]
	ds_read_b128 v[64:67], v201
	ds_read_b128 v[68:71], v201 offset:1024
	ds_read_b128 v[72:75], v201 offset:2048
	ds_read_b128 v[76:79], v201 offset:3072
	s_waitcnt vmcnt(6)
	s_setprio 1
	s_barrier
	v_mfma_f32_16x16x32_bf16 v[56:59], v[216:219], v[80:83], v[56:59]
	v_mfma_f32_16x16x32_bf16 v[52:55], v[224:227], v[80:83], v[52:55]
	v_mfma_f32_16x16x32_bf16 v[40:43], v[216:219], v[88:91], v[40:43]
	v_mfma_f32_16x16x32_bf16 v[32:35], v[224:227], v[88:91], v[32:35]
	v_mfma_f32_16x16x32_bf16 v[24:27], v[216:219], v[180:183], v[24:27]
	v_mfma_f32_16x16x32_bf16 v[8:11], v[224:227], v[180:183], v[8:11]
	v_mfma_f32_16x16x32_bf16 v[4:7], v[216:219], v[188:191], v[4:7]
	v_mfma_f32_16x16x32_bf16 v[0:3], v[224:227], v[188:191], v[0:3]
	v_mfma_f32_16x16x32_bf16 v[56:59], v[220:223], v[84:87], v[56:59]
	v_mfma_f32_16x16x32_bf16 v[52:55], v[228:231], v[84:87], v[52:55]
	v_mfma_f32_16x16x32_bf16 v[40:43], v[220:223], v[92:95], v[40:43]
	v_mfma_f32_16x16x32_bf16 v[32:35], v[228:231], v[92:95], v[32:35]
	v_mfma_f32_16x16x32_bf16 v[24:27], v[220:223], v[184:187], v[24:27]
	v_mfma_f32_16x16x32_bf16 v[8:11], v[228:231], v[184:187], v[8:11]
	v_mfma_f32_16x16x32_bf16 v[4:7], v[220:223], v[192:195], v[4:7]
	v_mfma_f32_16x16x32_bf16 v[0:3], v[228:231], v[192:195], v[0:3]
	s_add_i32 s58, s58, 2
	s_add_u32 s14, s14, 0x100
	s_addc_u32 s15, s15, 0
	s_add_u32 s52, s52, 0x100
	s_addc_u32 s53, s53, 0
	s_cmp_gt_u32 s58, 29
	s_barrier
	s_setprio 0
	s_cbranch_scc0 .LBB0_1277
	s_waitcnt lgkmcnt(0)
	s_lshl_b32 s39, s12, 8
	s_add_i32 s39, s39, s54
	v_or_b32_e32 v190, s39, v179
	v_ashrrev_i32_e32 v191, 31, v190
	v_lshlrev_b64 v[64:65], 7, v[190:191]
	v_or_b32_e32 v188, 16, v190
	v_lshl_add_u64 v[64:65], v[168:169], 0, v[64:65]
	v_ashrrev_i32_e32 v189, 31, v188
	global_load_dwordx4 v[192:195], v[64:65], off
	global_load_dwordx4 v[206:209], v[64:65], off offset:16
	v_lshlrev_b64 v[64:65], 7, v[188:189]
	v_lshl_add_u64 v[64:65], v[168:169], 0, v[64:65]
	global_load_dwordx4 v[212:215], v[64:65], off
	global_load_dwordx4 v[216:219], v[64:65], off offset:16
	v_or_b32_e32 v186, 32, v190
	v_ashrrev_i32_e32 v187, 31, v186
	v_lshlrev_b64 v[64:65], 7, v[186:187]
	v_or_b32_e32 v184, 48, v190
	v_lshl_add_u64 v[64:65], v[168:169], 0, v[64:65]
	v_ashrrev_i32_e32 v185, 31, v184
	global_load_dwordx4 v[220:223], v[64:65], off
	global_load_dwordx4 v[224:227], v[64:65], off offset:16
	v_lshlrev_b64 v[64:65], 7, v[184:185]
	v_lshl_add_u64 v[64:65], v[168:169], 0, v[64:65]
	global_load_dwordx4 v[228:231], v[64:65], off
	global_load_dwordx4 v[232:235], v[64:65], off offset:16
	v_lshl_or_b32 v180, s13, 7, v200
	v_and_b32_e32 v65, 64, v204
	v_xor_b32_e32 v64, 16, v204
	v_ashrrev_i32_e32 v181, 31, v180
	v_add_u32_e32 v65, 64, v65
	v_xor_b32_e32 v66, 32, v204
	v_lshlrev_b64 v[182:183], 2, v[180:181]
	v_cmp_lt_i32_e32 vcc, v64, v65
	v_lshl_add_u64 v[88:89], s[16:17], 0, v[182:183]
	v_lshl_add_u64 v[72:73], s[18:19], 0, v[182:183]
	v_cndmask_b32_e32 v64, v204, v64, vcc
	v_cmp_lt_i32_e32 vcc, v66, v65
	v_lshl_add_u64 v[74:75], v[88:89], 0, s[30:31]
	v_lshl_add_u64 v[76:77], v[88:89], 0, s[34:35]
	v_cndmask_b32_e32 v65, v204, v66, vcc
	v_add_co_u32_e32 v90, vcc, 0x5000, v88
	v_lshlrev_b32_e32 v187, 2, v64
	s_nop 0
	v_addc_co_u32_e32 v91, vcc, 0, v89, vcc
	v_add_co_u32_e32 v92, vcc, 0xb000, v88
	v_lshlrev_b32_e32 v185, 2, v65
	s_nop 0
	v_addc_co_u32_e32 v93, vcc, 0, v89, vcc
	global_load_dwordx4 v[64:67], v[88:89], off offset:16
	global_load_dwordx4 v[80:83], v[88:89], off
	global_load_dwordx4 v[68:71], v[72:73], off offset:16
	global_load_dwordx4 v[84:87], v[72:73], off
	s_nop 0
	global_load_dwordx4 v[72:75], v[74:75], off offset:16
	s_nop 0
	global_load_dwordx4 v[76:79], v[76:77], off offset:16
	s_nop 0
	global_load_dwordx4 v[88:91], v[90:91], off offset:2048
	s_nop 0
	global_load_dwordx4 v[92:95], v[92:93], off
	v_mov_b32_e32 v211, 0
	v_mov_b32_e32 v205, 0
	s_waitcnt vmcnt(0)
	v_mov_b32_e32 v196, v192
	v_mov_b32_e32 v197, v206
	v_mov_b32_e32 v206, v193
	v_mov_b32_e32 v192, v194
	v_mov_b32_e32 v193, v208
	v_mov_b32_e32 v208, v195
	v_pk_add_f32 v[194:195], v[196:197], v[206:207]
	v_pk_add_f32 v[192:193], v[192:193], v[208:209]
	v_mov_b32_e32 v196, v212
	v_mov_b32_e32 v197, v216
	v_mov_b32_e32 v216, v213
	v_mov_b32_e32 v206, v214
	v_mov_b32_e32 v207, v218
	v_mov_b32_e32 v218, v215
	v_pk_add_f32 v[192:193], v[194:195], v[192:193]
	v_pk_add_f32 v[194:195], v[196:197], v[216:217]
	v_pk_add_f32 v[196:197], v[206:207], v[218:219]
	v_mov_b32_e32 v208, v220
	v_pk_add_f32 v[194:195], v[194:195], v[196:197]
	v_mov_b32_e32 v197, v192
	v_mov_b32_e32 v196, v194
	v_mov_b32_e32 v192, v195
	v_pk_add_f32 v[192:193], v[196:197], v[192:193]
	ds_bpermute_b32 v195, v187, v193
	ds_bpermute_b32 v194, v187, v192
	v_mov_b32_e32 v209, v224
	v_mov_b32_e32 v224, v221
	v_mov_b32_e32 v212, v222
	v_mov_b32_e32 v213, v226
	s_waitcnt lgkmcnt(0)
	v_pk_add_f32 v[192:193], v[192:193], v[194:195]
	ds_bpermute_b32 v195, v185, v193
	ds_bpermute_b32 v194, v185, v192
	v_mov_b32_e32 v226, v223
	v_mov_b32_e32 v196, v228
	v_mov_b32_e32 v197, v232
	v_mov_b32_e32 v232, v229
	s_waitcnt lgkmcnt(0)
; DI unsigned pack2(float lo, float hi) { f32x2 v = {lo, hi}; bf16v2 r = __builtin_convertvector(v, bf16v2); return __builtin_bit_cast(unsigned, r); }
; DI float silu_f(float x) { return x * sigmoid_f(x); }
; DI float dpp_ror1(float v) { return __int_as_float(__builtin_amdgcn_update_dpp(0, __float_as_int(v), 0x121, 0xf, 0xf, false)); }
; DI float dpp_ror2(float v) { return __int_as_float(__builtin_amdgcn_update_dpp(0, __float_as_int(v), 0x122, 0xf, 0xf, false)); }
;   DI void operator()(const f32x4 (&acc)[2][2][4][2], const Unit& u, int wr, int wc, int fr, int fq) const {
;     ...
;       for (int m = 0; m < 4; ++m) rsv[m] = row_rstd(ssq, row0 + 16 * m + fr, fq);
;       float p1[8], p2[8];
; #pragma unroll
;       for (int e = 0; e < 8; ++e) { p1[e] = 0.f; p2[e] = 0.f; }
; #pragma unroll
;       for (int m = 0; m < 4; ++m) {
;         float g[8], uu[8], a[8];
;         const float rs = rsv[m];
; #pragma unroll
;         for (int e = 0; e < 4; ++e) { g[e] = acc[ai][0][m][0][e] * rs; g[4 + e] = acc[ai][0][m][1][e] * rs; uu[e] = acc[ai][1][m][0][e] * rs; uu[4 + e] = acc[ai][1][m][1][e] * rs; }
; #pragma unroll
;         for (int e = 0; e < 8; ++e) {
;           const float x1 = dpp_ror1(g[e]), x2 = dpp_ror2(g[e]);
;           const float pr1 = (fr == 0) ? p1[e] : x1, pr2 = (fr < 2) ? p2[e] : x2;
;           a[e] = w2[e] * g[e] + w1[e] * pr1 + w0[e] * pr2 + bb[e];
;           p1[e] = x1; p2[e] = x2;
;         }
;         if (m == 0 && fr < 2) {
;           float* ha = headA + (size_t)(span * 2 + fr) * 5632 + col; float* hu = headU + (size_t)(span * 2 + fr) * 5632 + col;
;           *(f32x4*)ha = (f32x4){a[0], a[1], a[2], a[3]}; *(f32x4*)(ha + 4) = (f32x4){a[4], a[5], a[6], a[7]};
;           *(f32x4*)hu = (f32x4){uu[0], uu[1], uu[2], uu[3]}; *(f32x4*)(hu + 4) = (f32x4){uu[4], uu[5], uu[6], uu[7]};
;         } else {
;           u32x4 w;
;           w.x = pack2(silu_f(a[0]) * uu[0], silu_f(a[1]) * uu[1]);
;           w.y = pack2(silu_f(a[2]) * uu[2], silu_f(a[3]) * uu[3]);
;           w.z = pack2(silu_f(a[4]) * uu[4], silu_f(a[5]) * uu[5]);
;           w.w = pack2(silu_f(a[6]) * uu[6], silu_f(a[7]) * uu[7]);
;           *(u32x4*)(H + (size_t)(row0 + 16 * m + fr) * 5632 + col) = w;
;         }
	v_pk_add_f32 v[192:193], v[192:193], v[194:195]
	v_mov_b32_e32 v206, v230
	v_pk_fma_f32 v[192:193], v[192:193], s[36:37], v[178:179] op_sel_hi:[1,0,0]
	v_mov_b32_e32 v207, v234
	v_mul_f32_e32 v189, 0x4b800000, v193
	v_cmp_gt_f32_e64 s[12:13], s74, v193
	v_mov_b32_e32 v234, v231
	v_pk_add_f32 v[208:209], v[208:209], v[224:225]
	v_cndmask_b32_e64 v189, v193, v189, s[12:13]
	v_rsq_f32_e32 v189, v189
	v_pk_add_f32 v[212:213], v[212:213], v[226:227]
	v_pk_add_f32 v[196:197], v[196:197], v[232:233]
	v_pk_add_f32 v[194:195], v[206:207], v[234:235]
	v_mul_f32_e32 v191, 0x45800000, v189
	v_cndmask_b32_e64 v220, v189, v191, s[12:13]
	v_pk_add_f32 v[208:209], v[208:209], v[212:213]
	v_pk_add_f32 v[194:195], v[196:197], v[194:195]
	v_pk_mul_f32 v[156:157], v[156:157], v[220:221] op_sel_hi:[1,0]
	v_mov_b32_e32 v216, 0
	v_mov_b32_e32 v218, 0
	v_mov_b32_e32 v196, v194
	v_mov_b32_e32 v197, v208
	v_mov_b32_e32 v208, v195
	v_mov_b32_dpp v216, v156 row_ror:1 row_mask:0xf bank_mask:0xf
	v_mov_b32_dpp v218, v157 row_ror:1 row_mask:0xf bank_mask:0xf
	v_pk_add_f32 v[194:195], v[196:197], v[208:209]
	v_cndmask_b32_e64 v207, v218, 0, s[0:1]
	v_cndmask_b32_e64 v206, v216, 0, s[0:1]
	v_pk_mul_f32 v[158:159], v[158:159], v[220:221] op_sel_hi:[1,0]
	v_mov_b32_e32 v212, 0
	v_mov_b32_e32 v214, 0
	ds_bpermute_b32 v197, v187, v195
	ds_bpermute_b32 v196, v187, v194
	v_mov_b32_e32 v215, 0
	v_mov_b32_e32 v217, 0
	v_pk_mul_f32 v[206:207], v[88:89], v[206:207]
	v_mov_b32_dpp v212, v158 row_ror:1 row_mask:0xf bank_mask:0xf
	v_mov_b32_dpp v214, v159 row_ror:1 row_mask:0xf bank_mask:0xf
	v_mov_b32_dpp v215, v156 row_ror:2 row_mask:0xf bank_mask:0xf
	v_mov_b32_dpp v217, v157 row_ror:2 row_mask:0xf bank_mask:0xf
	v_pk_fma_f32 v[156:157], v[92:93], v[156:157], v[206:207]
	v_mov_b32_e32 v213, 0
	v_cndmask_b32_e64 v207, v214, 0, s[0:1]
	v_cndmask_b32_e64 v206, v212, 0, s[0:1]
	v_cndmask_b32_e64 v209, v217, 0, s[4:5]
	v_cndmask_b32_e64 v208, v215, 0, s[4:5]
	v_mov_b32_dpp v211, v158 row_ror:2 row_mask:0xf bank_mask:0xf
	v_mov_b32_dpp v213, v159 row_ror:2 row_mask:0xf bank_mask:0xf
	v_pk_mul_f32 v[206:207], v[90:91], v[206:207]
	v_pk_fma_f32 v[156:157], v[80:81], v[208:209], v[156:157]
	v_cndmask_b32_e64 v209, v213, 0, s[4:5]
	v_cndmask_b32_e64 v208, v211, 0, s[4:5]
	v_pk_fma_f32 v[158:159], v[94:95], v[158:159], v[206:207]
	v_pk_mul_f32 v[144:145], v[144:145], v[220:221] op_sel_hi:[1,0]
	v_pk_fma_f32 v[158:159], v[82:83], v[208:209], v[158:159]
	v_mov_b32_e32 v207, 0
	v_mov_b32_e32 v209, 0
	v_pk_mul_f32 v[146:147], v[146:147], v[220:221] op_sel_hi:[1,0]
	v_mov_b32_e32 v191, 0
	s_waitcnt lgkmcnt(0)
	v_pk_add_f32 v[194:195], v[194:195], v[196:197]
	v_mov_b32_dpp v207, v144 row_ror:1 row_mask:0xf bank_mask:0xf
	v_mov_b32_dpp v209, v145 row_ror:1 row_mask:0xf bank_mask:0xf
	v_mov_b32_dpp v191, v146 row_ror:1 row_mask:0xf bank_mask:0xf
	v_mov_b32_dpp v205, v147 row_ror:1 row_mask:0xf bank_mask:0xf
	ds_bpermute_b32 v197, v185, v195
	ds_bpermute_b32 v196, v185, v194
	v_pk_mul_f32 v[152:153], v[152:153], v[220:221] op_sel_hi:[1,0]
	v_pk_mul_f32 v[148:149], v[148:149], v[220:221] op_sel_hi:[1,0]
	v_pk_mul_f32 v[154:155], v[154:155], v[220:221] op_sel_hi:[1,0]
	v_pk_mul_f32 v[150:151], v[150:151], v[220:221] op_sel_hi:[1,0]
	v_mov_b32_e32 v206, 0
	v_mov_b32_e32 v208, 0
	v_cndmask_b32_e64 v223, v209, 0, s[0:1]
	v_cndmask_b32_e64 v222, v207, 0, s[0:1]
	v_mov_b32_e32 v189, 0
	v_mov_b32_e32 v193, 0
	v_cndmask_b32_e64 v221, v205, 0, s[0:1]
	v_cndmask_b32_e64 v220, v191, 0, s[0:1]
	v_mov_b32_dpp v206, v144 row_ror:2 row_mask:0xf bank_mask:0xf
	v_mov_b32_dpp v208, v145 row_ror:2 row_mask:0xf bank_mask:0xf
	v_pk_mul_f32 v[222:223], v[72:73], v[222:223]
	v_mov_b32_dpp v189, v146 row_ror:2 row_mask:0xf bank_mask:0xf
	v_mov_b32_dpp v193, v147 row_ror:2 row_mask:0xf bank_mask:0xf
	v_pk_mul_f32 v[220:221], v[74:75], v[220:221]
	v_cndmask_b32_e64 v225, v208, 0, s[4:5]
	v_cndmask_b32_e64 v224, v206, 0, s[4:5]
	v_pk_fma_f32 v[144:145], v[76:77], v[144:145], v[222:223]
	v_cndmask_b32_e64 v223, v193, 0, s[4:5]
	v_cndmask_b32_e64 v222, v189, 0, s[4:5]
	v_pk_fma_f32 v[146:147], v[78:79], v[146:147], v[220:221]
	v_pk_fma_f32 v[144:145], v[64:65], v[224:225], v[144:145]
	v_pk_fma_f32 v[146:147], v[66:67], v[222:223], v[146:147]
	v_cmp_gt_f32_e32 vcc, s74, v192
	v_pk_add_f32 v[156:157], v[84:85], v[156:157]
	v_pk_add_f32 v[158:159], v[86:87], v[158:159]
	v_pk_add_f32 v[144:145], v[68:69], v[144:145]
	v_pk_add_f32 v[146:147], v[70:71], v[146:147]
	s_and_saveexec_b64 s[12:13], s[10:11]
	s_xor_b64 s[12:13], exec, s[12:13]
	s_cbranch_execz .LBB0_1280
	v_mul_f32_e32 v219, 0xbfb8aa3b, v156
	v_exp_f32_e32 v219, v219
	v_mul_f32_e32 v220, 0xbfb8aa3b, v157
	v_exp_f32_e32 v220, v220
	v_mul_f32_e32 v222, 0xbfb8aa3b, v159
	v_add_f32_e32 v219, 1.0, v219
	v_exp_f32_e32 v223, v222
	v_add_f32_e32 v221, 1.0, v220
	v_rcp_f32_e32 v220, v219
	v_mul_f32_e32 v219, 0xbfb8aa3b, v158
	v_exp_f32_e32 v219, v219
	v_rcp_f32_e32 v221, v221
	v_add_f32_e32 v219, 1.0, v219
	v_rcp_f32_e32 v222, v219
	v_add_f32_e32 v219, 1.0, v223
	v_rcp_f32_e32 v223, v219
	v_pk_mul_f32 v[156:157], v[156:157], v[220:221]
	s_nop 0
	v_pk_mul_f32 v[152:153], v[152:153], v[156:157]
	v_pk_mul_f32 v[156:157], v[158:159], v[222:223]
	v_cvt_pk_bf16_f32 v152, v152, v153
	v_mul_f32_e32 v153, 0xbfb8aa3b, v144
	v_pk_mul_f32 v[154:155], v[154:155], v[156:157]
	v_exp_f32_e32 v156, v153
	v_mul_f32_e32 v153, 0xbfb8aa3b, v145
	v_exp_f32_e32 v157, v153
	v_cvt_pk_bf16_f32 v153, v154, v155
	v_add_f32_e32 v154, 1.0, v156
	v_mul_f32_e32 v156, 0xbfb8aa3b, v146
	v_add_f32_e32 v155, 1.0, v157
	v_mul_f32_e32 v157, 0xbfb8aa3b, v147
	v_exp_f32_e32 v156, v156
	v_exp_f32_e32 v157, v157
	v_rcp_f32_e32 v154, v154
	v_rcp_f32_e32 v155, v155
	v_add_f32_e32 v156, 1.0, v156
	v_add_f32_e32 v157, 1.0, v157
	v_rcp_f32_e32 v156, v156
	v_rcp_f32_e32 v157, v157
	v_pk_mul_f32 v[144:145], v[144:145], v[154:155]
	s_nop 0
	v_pk_mul_f32 v[144:145], v[148:149], v[144:145]
	s_nop 0
	v_cvt_pk_bf16_f32 v154, v144, v145
	v_pk_mul_f32 v[144:145], v[146:147], v[156:157]
	s_nop 0
	v_pk_mul_f32 v[144:145], v[150:151], v[144:145]
	s_nop 0
	v_cvt_pk_bf16_f32 v155, v144, v145
	v_mov_b64_e32 v[144:145], s[20:21]
	v_mad_i64_i32 v[144:145], s[14:15], v190, s75, v[144:145]
	v_lshl_add_u64 v[144:145], v[180:181], 1, v[144:145]
	global_store_dwordx4 v[144:145], v[152:155], off

; #define PG8_STAGE(bufoff, gbase, voff) do { _Pragma("unroll") for (int _i = 0; _i < 2; ++_i) \
;     __builtin_amdgcn_global_load_lds((const unsigned*)((const char*)(gbase) + (voff)[_i]), (LAS unsigned*)(lds + (bufoff) + ldsw + _i * 8192), 16, 0, 0); } while (0)
; #define PG8_LDA(dst, b, h) do { _Pragma("unroll") for (int m = 0; m < 4; ++m) _Pragma("unroll") for (int k = 0; k < 2; ++k) dst[m][k] = *(const LAS bf16x8*)(lds + PG8_SA(b, h) + aoff + m * 2048 + k * 1024); } while (0)
; #define PG8_LDB(dst, b, h) do { _Pragma("unroll") for (int n = 0; n < 2; ++n) _Pragma("unroll") for (int k = 0; k < 2; ++k) dst[n][k] = *(const LAS bf16x8*)(lds + PG8_SB(b, h) + boff + n * 2048 + k * 1024); } while (0)
; #define PG8_MMA(ai, bj, At, Bt) do { __builtin_amdgcn_s_setprio(1); _Pragma("unroll") for (int m = 0; m < 4; ++m) _Pragma("unroll") for (int n = 0; n < 2; ++n) _Pragma("unroll") for (int k = 0; k < 2; ++k) \
;     acc[ai][bj][m][n] = __builtin_amdgcn_mfma_f32_16x16x32_bf16(Bt[n][k], At[m][k], acc[ai][bj][m][n], 0, 0, 0); __builtin_amdgcn_s_setprio(0); } while (0)
; #define PG8_WAIT_V(n) asm volatile("s_waitcnt vmcnt(" #n ")" ::: "memory")
; #define PG8_WAIT_L(n) asm volatile("s_waitcnt lgkmcnt(" #n ")" ::: "memory")
; #define PG8_BAR __builtin_amdgcn_s_barrier()
; #define PG8_SCHED __builtin_amdgcn_sched_barrier(0)
; template <class Epi, class Sched = StaticOrder>
; DI void gemm_phase(LAS unsigned char* lds, const Gemm g, const Sched& S, const Epi& E) {
;     ...
;       PG8_LDB(B0, 0, 0); PG8_SCHED; PG8_LDA(At, 0, 0); PG8_STAGE(PG8_SA(1, 1), a1 + hstep, voffA);
;       PG8_WAIT_L(8); PG8_BAR; PG8_WAIT_L(0); PG8_MMA(0, 0, At, B0); PG8_BAR; PG8_SCHED;
;       PG8_LDB(B1, 0, 1); PG8_STAGE(PG8_SB(0, 0), b2, voffB);
;       PG8_BAR; PG8_WAIT_L(0); PG8_MMA(0, 1, At, B1); PG8_BAR;
;       PG8_LDA(At, 0, 1); PG8_STAGE(PG8_SA(0, 0), a2, voffA);
;       PG8_BAR; PG8_WAIT_L(0); PG8_MMA(1, 0, At, B0); PG8_BAR; PG8_SCHED;
;       PG8_STAGE(PG8_SB(0, 1), b2 + hstep, voffB);
;       PG8_WAIT_V(6); PG8_BAR; PG8_MMA(1, 1, At, B1); PG8_BAR;
;       PG8_LDB(B0, 1, 0); PG8_SCHED; PG8_LDA(At, 1, 0); PG8_STAGE(PG8_SA(0, 1), a2 + hstep, voffA);
;       PG8_WAIT_L(8); PG8_BAR; PG8_WAIT_L(0); PG8_MMA(0, 0, At, B0); PG8_BAR; PG8_SCHED;
;       PG8_LDB(B1, 1, 1); PG8_STAGE(PG8_SB(1, 0), b3, voffB);
;       PG8_BAR; PG8_WAIT_L(0); PG8_MMA(0, 1, At, B1); PG8_BAR;
.LBB0_1424:
	s_add_u32 s18, s16, 0xffea0080
	s_addc_u32 s19, s17, -1
	s_cmpk_eq_i32 s47, 0x54
	s_cselect_b32 s21, s3, s19
	s_cselect_b32 s20, s2, s18
	s_cselect_b32 s19, s5, s46
	s_cselect_b32 s18, s4, s45
	s_add_i32 m0, s30, 0xc000
	ds_read_b128 v[166:169], v160
	ds_read_b128 v[174:177], v160 offset:2048
	ds_read_b128 v[182:185], v160 offset:4096
	ds_read_b128 v[190:193], v160 offset:6144
	ds_read_b128 v[170:173], v160 offset:1024
	ds_read_b128 v[178:181], v160 offset:3072
	ds_read_b128 v[186:189], v160 offset:5120
	ds_read_b128 v[194:197], v160 offset:7168
	global_load_lds_dwordx4 v136, s[16:17]
	s_add_i32 m0, s30, 0xe000
	s_nop 0
	global_load_lds_dwordx4 v138, s[16:17]
	s_waitcnt lgkmcnt(8)
	s_setprio 1
	s_barrier
	s_waitcnt lgkmcnt(4)
	v_mfma_f32_16x16x32_bf16 v[124:127], v[144:147], v[166:169], v[124:127]
	v_mfma_f32_16x16x32_bf16 v[120:123], v[152:155], v[166:169], v[120:123]
	v_mfma_f32_16x16x32_bf16 v[116:119], v[144:147], v[174:177], v[116:119]
	v_mfma_f32_16x16x32_bf16 v[112:115], v[152:155], v[174:177], v[112:115]
	v_mfma_f32_16x16x32_bf16 v[104:107], v[144:147], v[182:185], v[104:107]
	v_mfma_f32_16x16x32_bf16 v[96:99], v[152:155], v[182:185], v[96:99]
	v_mfma_f32_16x16x32_bf16 v[88:91], v[144:147], v[190:193], v[88:91]
	v_mfma_f32_16x16x32_bf16 v[80:83], v[152:155], v[190:193], v[80:83]
	s_waitcnt lgkmcnt(0)
	v_mfma_f32_16x16x32_bf16 v[124:127], v[148:151], v[170:173], v[124:127]
	v_mfma_f32_16x16x32_bf16 v[120:123], v[162:165], v[170:173], v[120:123]
	v_mfma_f32_16x16x32_bf16 v[116:119], v[148:151], v[178:181], v[116:119]
	v_mfma_f32_16x16x32_bf16 v[112:115], v[162:165], v[178:181], v[112:115]
	v_mfma_f32_16x16x32_bf16 v[104:107], v[148:151], v[186:189], v[104:107]
	v_mfma_f32_16x16x32_bf16 v[96:99], v[162:165], v[186:189], v[96:99]
	v_mfma_f32_16x16x32_bf16 v[88:91], v[148:151], v[194:197], v[88:91]
	v_mfma_f32_16x16x32_bf16 v[80:83], v[162:165], v[194:197], v[80:83]
	s_barrier
	s_setprio 0
	s_add_i32 s48, s39, s28
	s_add_u32 s98, s18, 0x80
	s_addc_u32 s99, s19, 0
	s_add_u32 s100, s20, 0x80
	s_addc_u32 s101, s21, 0
	s_mov_b32 m0, s48
	ds_read_b128 v[198:201], v161
	ds_read_b128 v[202:205], v161 offset:1024
	ds_read_b128 v[206:209], v161 offset:2048
	ds_read_b128 v[210:213], v161 offset:3072
	global_load_lds_dwordx4 v132, s[18:19]
	s_add_i32 m0, s48, 0x2000
	s_nop 0
	global_load_lds_dwordx4 v128, s[18:19]
	s_setprio 1
	s_barrier
	s_waitcnt lgkmcnt(0)
	v_mfma_f32_16x16x32_bf16 v[108:111], v[198:201], v[166:169], v[108:111]
	v_mfma_f32_16x16x32_bf16 v[100:103], v[206:209], v[166:169], v[100:103]
	v_mfma_f32_16x16x32_bf16 v[92:95], v[198:201], v[174:177], v[92:95]
	v_mfma_f32_16x16x32_bf16 v[84:87], v[206:209], v[174:177], v[84:87]
	v_mfma_f32_16x16x32_bf16 v[76:79], v[198:201], v[182:185], v[76:79]
	v_mfma_f32_16x16x32_bf16 v[72:75], v[206:209], v[182:185], v[72:75]
	v_mfma_f32_16x16x32_bf16 v[68:71], v[198:201], v[190:193], v[68:71]
	v_mfma_f32_16x16x32_bf16 v[64:67], v[206:209], v[190:193], v[64:67]
	v_mfma_f32_16x16x32_bf16 v[108:111], v[202:205], v[170:173], v[108:111]
	v_mfma_f32_16x16x32_bf16 v[100:103], v[210:213], v[170:173], v[100:103]
	v_mfma_f32_16x16x32_bf16 v[92:95], v[202:205], v[178:181], v[92:95]
	v_mfma_f32_16x16x32_bf16 v[84:87], v[210:213], v[178:181], v[84:87]
	v_mfma_f32_16x16x32_bf16 v[76:79], v[202:205], v[186:189], v[76:79]
	v_mfma_f32_16x16x32_bf16 v[72:75], v[210:213], v[186:189], v[72:75]
	v_mfma_f32_16x16x32_bf16 v[68:71], v[202:205], v[194:197], v[68:71]
	v_mfma_f32_16x16x32_bf16 v[64:67], v[210:213], v[194:197], v[64:67]
	s_barrier
	s_setprio 0
	s_mov_b32 m0, s30
	ds_read_b128 v[166:169], v160 offset:16384
	ds_read_b128 v[174:177], v160 offset:18432
	ds_read_b128 v[182:185], v160 offset:20480
	ds_read_b128 v[190:193], v160 offset:22528
	ds_read_b128 v[170:173], v160 offset:17408
	ds_read_b128 v[178:181], v160 offset:19456
	ds_read_b128 v[186:189], v160 offset:21504
	ds_read_b128 v[194:197], v160 offset:23552
	global_load_lds_dwordx4 v134, s[20:21]
	s_mov_b32 m0, s31
	s_nop 0
	global_load_lds_dwordx4 v130, s[20:21]
	s_waitcnt vmcnt(10)
	s_setprio 1
	s_barrier
	s_waitcnt lgkmcnt(4)
	v_mfma_f32_16x16x32_bf16 v[60:63], v[144:147], v[166:169], v[60:63]
	v_mfma_f32_16x16x32_bf16 v[56:59], v[152:155], v[166:169], v[56:59]
	v_mfma_f32_16x16x32_bf16 v[52:55], v[144:147], v[174:177], v[52:55]
	v_mfma_f32_16x16x32_bf16 v[44:47], v[152:155], v[174:177], v[44:47]
	v_mfma_f32_16x16x32_bf16 v[36:39], v[144:147], v[182:185], v[36:39]
	v_mfma_f32_16x16x32_bf16 v[28:31], v[152:155], v[182:185], v[28:31]
	v_mfma_f32_16x16x32_bf16 v[20:23], v[144:147], v[190:193], v[20:23]
	v_mfma_f32_16x16x32_bf16 v[12:15], v[152:155], v[190:193], v[12:15]
	s_waitcnt lgkmcnt(0)
	v_mfma_f32_16x16x32_bf16 v[60:63], v[148:151], v[170:173], v[60:63]
	v_mfma_f32_16x16x32_bf16 v[56:59], v[162:165], v[170:173], v[56:59]
	v_mfma_f32_16x16x32_bf16 v[52:55], v[148:151], v[178:181], v[52:55]
	v_mfma_f32_16x16x32_bf16 v[44:47], v[162:165], v[178:181], v[44:47]
	v_mfma_f32_16x16x32_bf16 v[36:39], v[148:151], v[186:189], v[36:39]
	v_mfma_f32_16x16x32_bf16 v[28:31], v[162:165], v[186:189], v[28:31]
	v_mfma_f32_16x16x32_bf16 v[20:23], v[148:151], v[194:197], v[20:23]
	v_mfma_f32_16x16x32_bf16 v[12:15], v[162:165], v[194:197], v[12:15]
	s_barrier
	s_setprio 0
	s_add_u32 s48, s18, 0x160000
	s_addc_u32 s49, s19, 0
	s_add_i32 s50, s40, s28
	s_mov_b32 m0, s50
	s_nop 0
	global_load_lds_dwordx4 v132, s[48:49]
	s_add_i32 m0, s50, 0x2000
	s_nop 0
	global_load_lds_dwordx4 v128, s[48:49]
	s_add_i32 s48, 0, 0x18000
	v_add_u32_e32 v162, s48, v157
	ds_read_b128 v[144:147], v162
	ds_read_b128 v[148:151], v162 offset:1024
	ds_read_b128 v[152:155], v162 offset:2048
	ds_read_b128 v[162:165], v162 offset:3072
	s_waitcnt vmcnt(6)
	s_setprio 1
	s_barrier
; #define PG8_STAGE(bufoff, gbase, voff) do { _Pragma("unroll") for (int _i = 0; _i < 2; ++_i) \
;     __builtin_amdgcn_global_load_lds((const unsigned*)((const char*)(gbase) + (voff)[_i]), (LAS unsigned*)(lds + (bufoff) + ldsw + _i * 8192), 16, 0, 0); } while (0)
; #define PG8_LDA(dst, b, h) do { _Pragma("unroll") for (int m = 0; m < 4; ++m) _Pragma("unroll") for (int k = 0; k < 2; ++k) dst[m][k] = *(const LAS bf16x8*)(lds + PG8_SA(b, h) + aoff + m * 2048 + k * 1024); } while (0)
; #define PG8_LDB(dst, b, h) do { _Pragma("unroll") for (int n = 0; n < 2; ++n) _Pragma("unroll") for (int k = 0; k < 2; ++k) dst[n][k] = *(const LAS bf16x8*)(lds + PG8_SB(b, h) + boff + n * 2048 + k * 1024); } while (0)
; #define PG8_MMA(ai, bj, At, Bt) do { __builtin_amdgcn_s_setprio(1); _Pragma("unroll") for (int m = 0; m < 4; ++m) _Pragma("unroll") for (int n = 0; n < 2; ++n) _Pragma("unroll") for (int k = 0; k < 2; ++k) \
;     acc[ai][bj][m][n] = __builtin_amdgcn_mfma_f32_16x16x32_bf16(Bt[n][k], At[m][k], acc[ai][bj][m][n], 0, 0, 0); __builtin_amdgcn_s_setprio(0); } while (0)
; #define PG8_WAIT_V(n) asm volatile("s_waitcnt vmcnt(" #n ")" ::: "memory")
; #define PG8_WAIT_L(n) asm volatile("s_waitcnt lgkmcnt(" #n ")" ::: "memory")
; #define PG8_BAR __builtin_amdgcn_s_barrier()
; #define PG8_SCHED __builtin_amdgcn_sched_barrier(0)
; template <class Epi, class Sched = StaticOrder>
; DI void gemm_phase(LAS unsigned char* lds, const Gemm g, const Sched& S, const Epi& E) {
;     ...
;       PG8_LDA(At, 0, 1); PG8_STAGE(PG8_SA(0, 0), a2, voffA);
;       PG8_BAR; PG8_WAIT_L(0); PG8_MMA(1, 0, At, B0); PG8_BAR; PG8_SCHED;
;       PG8_STAGE(PG8_SB(0, 1), b2 + hstep, voffB);
;       PG8_WAIT_V(6); PG8_BAR; PG8_MMA(1, 1, At, B1); PG8_BAR;
;       PG8_LDB(B0, 1, 0); PG8_SCHED; PG8_LDA(At, 1, 0); PG8_STAGE(PG8_SA(0, 1), a2 + hstep, voffA);
;       PG8_WAIT_L(8); PG8_BAR; PG8_WAIT_L(0); PG8_MMA(0, 0, At, B0); PG8_BAR; PG8_SCHED;
;       PG8_LDB(B1, 1, 1); PG8_STAGE(PG8_SB(1, 0), b3, voffB);
;       PG8_BAR; PG8_WAIT_L(0); PG8_MMA(0, 1, At, B1); PG8_BAR;
;       PG8_LDA(At, 1, 1); PG8_STAGE(PG8_SA(1, 0), a3, voffA);
;       PG8_BAR; PG8_WAIT_L(0); PG8_MMA(1, 0, At, B0); PG8_BAR; PG8_SCHED;
	v_mfma_f32_16x16x32_bf16 v[48:51], v[198:201], v[166:169], v[48:51]
	v_mfma_f32_16x16x32_bf16 v[40:43], v[206:209], v[166:169], v[40:43]
	v_mfma_f32_16x16x32_bf16 v[32:35], v[198:201], v[174:177], v[32:35]
	v_mfma_f32_16x16x32_bf16 v[24:27], v[206:209], v[174:177], v[24:27]
	v_mfma_f32_16x16x32_bf16 v[16:19], v[198:201], v[182:185], v[16:19]
	v_mfma_f32_16x16x32_bf16 v[8:11], v[206:209], v[182:185], v[8:11]
	v_mfma_f32_16x16x32_bf16 v[4:7], v[198:201], v[190:193], v[4:7]
	v_mfma_f32_16x16x32_bf16 v[0:3], v[206:209], v[190:193], v[0:3]
	v_mfma_f32_16x16x32_bf16 v[48:51], v[202:205], v[170:173], v[48:51]
	v_mfma_f32_16x16x32_bf16 v[40:43], v[210:213], v[170:173], v[40:43]
	v_mfma_f32_16x16x32_bf16 v[32:35], v[202:205], v[178:181], v[32:35]
	v_mfma_f32_16x16x32_bf16 v[24:27], v[210:213], v[178:181], v[24:27]
	v_mfma_f32_16x16x32_bf16 v[16:19], v[202:205], v[186:189], v[16:19]
	v_mfma_f32_16x16x32_bf16 v[8:11], v[210:213], v[186:189], v[8:11]
	v_mfma_f32_16x16x32_bf16 v[4:7], v[202:205], v[194:197], v[4:7]
	v_mfma_f32_16x16x32_bf16 v[0:3], v[210:213], v[194:197], v[0:3]
	s_barrier
	s_setprio 0
	s_add_u32 s20, s20, 0x160000
	s_addc_u32 s21, s21, 0
	s_mov_b32 m0, s33
	ds_read_b128 v[166:169], v160 offset:32768
	ds_read_b128 v[174:177], v160 offset:34816
	ds_read_b128 v[182:185], v160 offset:36864
	ds_read_b128 v[190:193], v160 offset:38912
	ds_read_b128 v[170:173], v160 offset:33792
	ds_read_b128 v[178:181], v160 offset:35840
	ds_read_b128 v[186:189], v160 offset:37888
	ds_read_b128 v[194:197], v160 offset:39936
	global_load_lds_dwordx4 v134, s[20:21]
	s_mov_b32 m0, s34
	s_nop 0
	global_load_lds_dwordx4 v130, s[20:21]
	s_waitcnt lgkmcnt(8)
	s_setprio 1
	s_barrier
	s_waitcnt lgkmcnt(4)
	v_mfma_f32_16x16x32_bf16 v[124:127], v[144:147], v[166:169], v[124:127]
	v_mfma_f32_16x16x32_bf16 v[120:123], v[152:155], v[166:169], v[120:123]
	v_mfma_f32_16x16x32_bf16 v[116:119], v[144:147], v[174:177], v[116:119]
	v_mfma_f32_16x16x32_bf16 v[112:115], v[152:155], v[174:177], v[112:115]
	v_mfma_f32_16x16x32_bf16 v[104:107], v[144:147], v[182:185], v[104:107]
	v_mfma_f32_16x16x32_bf16 v[96:99], v[152:155], v[182:185], v[96:99]
	v_mfma_f32_16x16x32_bf16 v[88:91], v[144:147], v[190:193], v[88:91]
	v_mfma_f32_16x16x32_bf16 v[80:83], v[152:155], v[190:193], v[80:83]
	s_waitcnt lgkmcnt(0)
	v_mfma_f32_16x16x32_bf16 v[124:127], v[148:151], v[170:173], v[124:127]
	v_mfma_f32_16x16x32_bf16 v[120:123], v[162:165], v[170:173], v[120:123]
	v_mfma_f32_16x16x32_bf16 v[116:119], v[148:151], v[178:181], v[116:119]
	v_mfma_f32_16x16x32_bf16 v[112:115], v[162:165], v[178:181], v[112:115]
	v_mfma_f32_16x16x32_bf16 v[104:107], v[148:151], v[186:189], v[104:107]
	v_mfma_f32_16x16x32_bf16 v[96:99], v[162:165], v[186:189], v[96:99]
	v_mfma_f32_16x16x32_bf16 v[88:91], v[148:151], v[194:197], v[88:91]
	v_mfma_f32_16x16x32_bf16 v[80:83], v[162:165], v[194:197], v[80:83]
	s_barrier
	s_setprio 0
	s_add_i32 s20, 0, 0x1c000
	s_add_i32 s21, s48, s28
	v_add_u32_e32 v210, s20, v157
	s_mov_b32 m0, s21
	ds_read_b128 v[198:201], v210
	ds_read_b128 v[202:205], v210 offset:1024
	ds_read_b128 v[206:209], v210 offset:2048
	ds_read_b128 v[210:213], v210 offset:3072
	global_load_lds_dwordx4 v132, s[98:99]
	s_add_i32 m0, s21, 0x2000
	s_nop 0
	global_load_lds_dwordx4 v128, s[98:99]
	s_setprio 1
	s_barrier
	s_waitcnt lgkmcnt(0)
	v_mfma_f32_16x16x32_bf16 v[108:111], v[198:201], v[166:169], v[108:111]
	v_mfma_f32_16x16x32_bf16 v[100:103], v[206:209], v[166:169], v[100:103]
	v_mfma_f32_16x16x32_bf16 v[92:95], v[198:201], v[174:177], v[92:95]
	v_mfma_f32_16x16x32_bf16 v[84:87], v[206:209], v[174:177], v[84:87]
	v_mfma_f32_16x16x32_bf16 v[76:79], v[198:201], v[182:185], v[76:79]
	v_mfma_f32_16x16x32_bf16 v[72:75], v[206:209], v[182:185], v[72:75]
	v_mfma_f32_16x16x32_bf16 v[68:71], v[198:201], v[190:193], v[68:71]
	v_mfma_f32_16x16x32_bf16 v[64:67], v[206:209], v[190:193], v[64:67]
	v_mfma_f32_16x16x32_bf16 v[108:111], v[202:205], v[170:173], v[108:111]
	v_mfma_f32_16x16x32_bf16 v[100:103], v[210:213], v[170:173], v[100:103]
	v_mfma_f32_16x16x32_bf16 v[92:95], v[202:205], v[178:181], v[92:95]
	v_mfma_f32_16x16x32_bf16 v[84:87], v[210:213], v[178:181], v[84:87]
	v_mfma_f32_16x16x32_bf16 v[76:79], v[202:205], v[186:189], v[76:79]
	v_mfma_f32_16x16x32_bf16 v[72:75], v[210:213], v[186:189], v[72:75]
	v_mfma_f32_16x16x32_bf16 v[68:71], v[202:205], v[194:197], v[68:71]
	v_mfma_f32_16x16x32_bf16 v[64:67], v[210:213], v[194:197], v[64:67]
	s_barrier
	s_setprio 0
	s_mov_b32 m0, s35
	ds_read_b128 v[166:169], v160 offset:49152
	ds_read_b128 v[174:177], v160 offset:51200
	ds_read_b128 v[182:185], v160 offset:53248
	ds_read_b128 v[190:193], v160 offset:55296
	ds_read_b128 v[170:173], v160 offset:50176
	ds_read_b128 v[178:181], v160 offset:52224
	ds_read_b128 v[186:189], v160 offset:54272
	ds_read_b128 v[194:197], v160 offset:56320
	global_load_lds_dwordx4 v134, s[100:101]
	s_mov_b32 m0, s36
	s_nop 0
	global_load_lds_dwordx4 v130, s[100:101]
	s_waitcnt vmcnt(10)
	s_setprio 1
	s_barrier
	s_waitcnt lgkmcnt(4)
	v_mfma_f32_16x16x32_bf16 v[60:63], v[144:147], v[166:169], v[60:63]
	v_mfma_f32_16x16x32_bf16 v[56:59], v[152:155], v[166:169], v[56:59]
	v_mfma_f32_16x16x32_bf16 v[52:55], v[144:147], v[174:177], v[52:55]
	v_mfma_f32_16x16x32_bf16 v[44:47], v[152:155], v[174:177], v[44:47]
	v_mfma_f32_16x16x32_bf16 v[36:39], v[144:147], v[182:185], v[36:39]
	v_mfma_f32_16x16x32_bf16 v[28:31], v[152:155], v[182:185], v[28:31]
	v_mfma_f32_16x16x32_bf16 v[20:23], v[144:147], v[190:193], v[20:23]
	v_mfma_f32_16x16x32_bf16 v[12:15], v[152:155], v[190:193], v[12:15]
	s_waitcnt lgkmcnt(0)
	v_mfma_f32_16x16x32_bf16 v[60:63], v[148:151], v[170:173], v[60:63]
	v_mfma_f32_16x16x32_bf16 v[56:59], v[162:165], v[170:173], v[56:59]
	v_mfma_f32_16x16x32_bf16 v[52:55], v[148:151], v[178:181], v[52:55]
	v_mfma_f32_16x16x32_bf16 v[44:47], v[162:165], v[178:181], v[44:47]
	v_mfma_f32_16x16x32_bf16 v[36:39], v[148:151], v[186:189], v[36:39]
	v_mfma_f32_16x16x32_bf16 v[28:31], v[162:165], v[186:189], v[28:31]
	v_mfma_f32_16x16x32_bf16 v[20:23], v[148:151], v[194:197], v[20:23]
	v_mfma_f32_16x16x32_bf16 v[12:15], v[162:165], v[194:197], v[12:15]
	s_barrier
; #define PG8_STAGE(bufoff, gbase, voff) do { _Pragma("unroll") for (int _i = 0; _i < 2; ++_i) \
;     __builtin_amdgcn_global_load_lds((const unsigned*)((const char*)(gbase) + (voff)[_i]), (LAS unsigned*)(lds + (bufoff) + ldsw + _i * 8192), 16, 0, 0); } while (0)
; #define PG8_LDA(dst, b, h) do { _Pragma("unroll") for (int m = 0; m < 4; ++m) _Pragma("unroll") for (int k = 0; k < 2; ++k) dst[m][k] = *(const LAS bf16x8*)(lds + PG8_SA(b, h) + aoff + m * 2048 + k * 1024); } while (0)
; #define PG8_LDB(dst, b, h) do { _Pragma("unroll") for (int n = 0; n < 2; ++n) _Pragma("unroll") for (int k = 0; k < 2; ++k) dst[n][k] = *(const LAS bf16x8*)(lds + PG8_SB(b, h) + boff + n * 2048 + k * 1024); } while (0)
; #define PG8_MMA(ai, bj, At, Bt) do { __builtin_amdgcn_s_setprio(1); _Pragma("unroll") for (int m = 0; m < 4; ++m) _Pragma("unroll") for (int n = 0; n < 2; ++n) _Pragma("unroll") for (int k = 0; k < 2; ++k) \
;     acc[ai][bj][m][n] = __builtin_amdgcn_mfma_f32_16x16x32_bf16(Bt[n][k], At[m][k], acc[ai][bj][m][n], 0, 0, 0); __builtin_amdgcn_s_setprio(0); } while (0)
; #define PG8_WAIT_V(n) asm volatile("s_waitcnt vmcnt(" #n ")" ::: "memory")
; #define PG8_WAIT_L(n) asm volatile("s_waitcnt lgkmcnt(" #n ")" ::: "memory")
; #define PG8_BAR __builtin_amdgcn_s_barrier()
;   DI void operator()(const f32x4 (&acc)[2][2][4][2], const Unit& u, int wr, int wc, int fr, int fq) const {
;     const int row0 = u.pm * BM + wr * 64 + fr, col0 = u.pn * BM + wc * 32 + 8 * fq;
; #pragma unroll
;     for (int ai = 0; ai < 2; ++ai) {
;       f32x4 bv[4][2][2];
; #pragma unroll
;       for (int m = 0; m < 4; ++m)
; #pragma unroll
;         for (int bj = 0; bj < 2; ++bj) {
;           const float* bp = base + (size_t)(row0 + ai * HALF + m * 16) * 2048 + col0 + bj * HALF;
;           bv[m][bj][0] = *(const f32x4*)bp; bv[m][bj][1] = *(const f32x4*)(bp + 4);
;         }
; template <class Epi, class Sched = StaticOrder>
; DI void gemm_phase(LAS unsigned char* lds, const Gemm g, const Sched& S, const Epi& E) {
;     ...
;       PG8_LDB(B1, 1, 1); PG8_STAGE(PG8_SB(1, 0), b3, voffB);
;       PG8_BAR; PG8_WAIT_L(0); PG8_MMA(0, 1, At, B1); PG8_BAR;
;       PG8_LDA(At, 1, 1); PG8_STAGE(PG8_SA(1, 0), a3, voffA);
;       PG8_BAR; PG8_WAIT_L(0); PG8_MMA(1, 0, At, B0); PG8_BAR; PG8_SCHED;
;       PG8_STAGE(PG8_SB(1, 1), b3 + hstep, voffB);
;       PG8_WAIT_V(6); PG8_BAR; PG8_MMA(1, 1, At, B1); PG8_BAR;
	s_setprio 0
	s_add_u32 s18, s18, 0x160080
	s_addc_u32 s19, s19, 0
	s_add_i32 s20, s20, s28
	s_mov_b32 m0, s20
	s_nop 0
	global_load_lds_dwordx4 v132, s[18:19]
	s_add_i32 m0, s20, 0x2000
	s_nop 0
	global_load_lds_dwordx4 v128, s[18:19]
	ds_read_b128 v[144:147], v159
	ds_read_b128 v[148:151], v159 offset:1024
	ds_read_b128 v[152:155], v159 offset:2048
	ds_read_b128 v[162:165], v159 offset:3072
	s_waitcnt vmcnt(6)
	s_setprio 1
	s_barrier
	v_mfma_f32_16x16x32_bf16 v[48:51], v[198:201], v[166:169], v[48:51]
	v_mfma_f32_16x16x32_bf16 v[40:43], v[206:209], v[166:169], v[40:43]
	v_mfma_f32_16x16x32_bf16 v[32:35], v[198:201], v[174:177], v[32:35]
	v_mfma_f32_16x16x32_bf16 v[24:27], v[206:209], v[174:177], v[24:27]
	v_mfma_f32_16x16x32_bf16 v[16:19], v[198:201], v[182:185], v[16:19]
	v_mfma_f32_16x16x32_bf16 v[8:11], v[206:209], v[182:185], v[8:11]
	v_mfma_f32_16x16x32_bf16 v[4:7], v[198:201], v[190:193], v[4:7]
	v_mfma_f32_16x16x32_bf16 v[0:3], v[206:209], v[190:193], v[0:3]
	v_mfma_f32_16x16x32_bf16 v[48:51], v[202:205], v[170:173], v[48:51]
	v_mfma_f32_16x16x32_bf16 v[40:43], v[210:213], v[170:173], v[40:43]
	v_mfma_f32_16x16x32_bf16 v[32:35], v[202:205], v[178:181], v[32:35]
	v_mfma_f32_16x16x32_bf16 v[24:27], v[210:213], v[178:181], v[24:27]
	v_mfma_f32_16x16x32_bf16 v[16:19], v[202:205], v[186:189], v[16:19]
	v_mfma_f32_16x16x32_bf16 v[8:11], v[210:213], v[186:189], v[8:11]
	v_mfma_f32_16x16x32_bf16 v[4:7], v[202:205], v[194:197], v[4:7]
	v_mfma_f32_16x16x32_bf16 v[0:3], v[210:213], v[194:197], v[0:3]
	s_add_i32 s47, s47, 2
	s_add_u32 s16, s16, 0x100
	s_addc_u32 s17, s17, 0
	s_add_u32 s45, s45, 0x100
	s_addc_u32 s46, s46, 0
	s_cmpk_gt_u32 s47, 0x55
	s_barrier
	s_setprio 0
	s_cbranch_scc0 .LBB0_1424
	s_waitcnt lgkmcnt(0)
	v_lshl_or_b32 v144, s44, 8, v158
	v_lshl_add_u32 v154, s43, 8, v156
	v_ashrrev_i32_e32 v145, 31, v144
	v_lshlrev_b64 v[144:145], 2, v[144:145]
	v_ashrrev_i32_e32 v155, 31, v154
	v_lshl_add_u64 v[146:147], s[54:55], 0, v[144:145]
	v_lshlrev_b64 v[148:149], 13, v[154:155]
	v_or_b32_e32 v174, 16, v154
	v_lshl_add_u64 v[170:171], v[146:147], 0, v[148:149]
	v_ashrrev_i32_e32 v175, 31, v174
	global_load_dwordx4 v[150:153], v[170:171], off offset:16
	global_load_dwordx4 v[162:165], v[170:171], off
	global_load_dwordx4 v[166:169], v[170:171], off offset:528
	s_nop 0
	global_load_dwordx4 v[170:173], v[170:171], off offset:512
	v_lshlrev_b64 v[222:223], 13, v[174:175]
	v_or_b32_e32 v190, 32, v154
	v_lshl_add_u64 v[186:187], v[146:147], 0, v[222:223]
	v_ashrrev_i32_e32 v191, 31, v190
	global_load_dwordx4 v[174:177], v[186:187], off offset:16
	global_load_dwordx4 v[178:181], v[186:187], off
	global_load_dwordx4 v[182:185], v[186:187], off offset:528
	s_nop 0
	global_load_dwordx4 v[186:189], v[186:187], off offset:512
	v_lshlrev_b64 v[224:225], 13, v[190:191]
	v_or_b32_e32 v154, 48, v154
	v_lshl_add_u64 v[202:203], v[146:147], 0, v[224:225]
	v_ashrrev_i32_e32 v155, 31, v154
	global_load_dwordx4 v[190:193], v[202:203], off offset:16
	global_load_dwordx4 v[194:197], v[202:203], off
	global_load_dwordx4 v[198:201], v[202:203], off offset:528
	s_nop 0
	global_load_dwordx4 v[202:205], v[202:203], off offset:512
	v_lshlrev_b64 v[154:155], 13, v[154:155]
	v_lshl_add_u64 v[218:219], v[146:147], 0, v[154:155]
	global_load_dwordx4 v[206:209], v[218:219], off offset:16
	global_load_dwordx4 v[210:213], v[218:219], off
	global_load_dwordx4 v[214:217], v[218:219], off offset:528
	s_nop 0
	global_load_dwordx4 v[218:221], v[218:219], off offset:512
	s_and_b64 vcc, exec, s[0:1]
	s_mov_b32 s44, s41
	s_mov_b32 s43, s42
	s_mov_b64 s[18:19], s[4:5]
	s_mov_b64 s[16:17], s[2:3]
	s_waitcnt vmcnt(0)
; #define PG8_WAIT_V(n) asm volatile("s_waitcnt vmcnt(" #n ")" ::: "memory")
; #define PG8_BAR __builtin_amdgcn_s_barrier()
;   DI void operator()(const f32x4 (&acc)[2][2][4][2], const Unit& u, int wr, int wc, int fr, int fq) const {
;     ...
;     for (int ai = 0; ai < 2; ++ai) {
;       f32x4 bv[4][2][2];
; #pragma unroll
;       for (int m = 0; m < 4; ++m)
; #pragma unroll
;         for (int bj = 0; bj < 2; ++bj) {
;           const float* bp = base + (size_t)(row0 + ai * HALF + m * 16) * 2048 + col0 + bj * HALF;
;           bv[m][bj][0] = *(const f32x4*)bp; bv[m][bj][1] = *(const f32x4*)(bp + 4);
;         }
; #pragma unroll
;       for (int m = 0; m < 4; ++m) {
;         const int row = row0 + ai * HALF + m * 16;
;         const size_t off = (size_t)row * 2048 + col0;
;         float ss = 0.f;
; #pragma unroll
;         for (int bj = 0; bj < 2; ++bj) {
;           const f32x4 v0 = acc[ai][bj][m][0] + bv[m][bj][0], v1 = acc[ai][bj][m][1] + bv[m][bj][1];
;           *(f32x4*)(C + off + bj * HALF) = v0; *(f32x4*)(C + off + bj * HALF + 4) = v1;
; template <class Epi, class Sched = StaticOrder>
; DI void gemm_phase(LAS unsigned char* lds, const Gemm g, const Sched& S, const Epi& E) {
;     ...
;     E(acc, cur, wr, wc, fr, fq);
;     if (!has_next) break;
; #pragma unroll
;     for (int a = 0; a < 2; ++a)
; #pragma unroll
;       for (int b = 0; b < 2; ++b)
; #pragma unroll
;         for (int m = 0; m < 4; ++m)
; #pragma unroll
;           for (int n = 0; n < 2; ++n) acc[a][b][m][n] = (f32x4){0.f, 0.f, 0.f, 0.f};
;     cur = nxt; cA = nA; cB = nB; ++ui;
;   }
;   PG8_WAIT_V(0);
;   if (wr == 0) PG8_BAR;
;   PG8_BAR;
	v_pk_add_f32 v[120:121], v[120:121], v[150:151]
	v_lshl_add_u64 v[150:151], s[54:55], 0, v[148:149]
	v_pk_add_f32 v[126:127], v[126:127], v[164:165]
	v_pk_add_f32 v[124:125], v[124:125], v[162:163]
	v_lshl_add_u64 v[150:151], v[150:151], 0, v[144:145]
	v_pk_add_f32 v[110:111], v[110:111], v[172:173]
	v_pk_add_f32 v[108:109], v[108:109], v[170:171]
	v_pk_add_f32 v[122:123], v[122:123], v[152:153]
	global_store_dwordx4 v[150:151], v[124:127], off
	global_store_dwordx4 v[150:151], v[120:123], off offset:16
	v_pk_add_f32 v[102:103], v[102:103], v[168:169]
	v_pk_add_f32 v[100:101], v[100:101], v[166:167]
	global_store_dwordx4 v[150:151], v[108:111], off offset:512
	global_store_dwordx4 v[150:151], v[100:103], off offset:528
	v_pk_add_f32 v[94:95], v[94:95], v[188:189]
	v_pk_add_f32 v[108:109], v[112:113], v[174:175]
	v_lshl_add_u64 v[112:113], s[54:55], 0, v[222:223]
	v_pk_add_f32 v[102:103], v[118:119], v[180:181]
	v_pk_add_f32 v[100:101], v[116:117], v[178:179]
	v_lshl_add_u64 v[112:113], v[112:113], 0, v[144:145]
	v_pk_add_f32 v[92:93], v[92:93], v[186:187]
	v_pk_add_f32 v[110:111], v[114:115], v[176:177]
	global_store_dwordx4 v[112:113], v[100:103], off
	global_store_dwordx4 v[112:113], v[108:111], off offset:16
	v_pk_add_f32 v[86:87], v[86:87], v[184:185]
	v_pk_add_f32 v[84:85], v[84:85], v[182:183]
	global_store_dwordx4 v[112:113], v[92:95], off offset:512
	global_store_dwordx4 v[112:113], v[84:87], off offset:528
	v_pk_add_f32 v[78:79], v[78:79], v[204:205]
	v_pk_add_f32 v[92:93], v[96:97], v[190:191]
	v_lshl_add_u64 v[96:97], s[54:55], 0, v[224:225]
	v_pk_add_f32 v[86:87], v[106:107], v[196:197]
	v_pk_add_f32 v[84:85], v[104:105], v[194:195]
	v_lshl_add_u64 v[96:97], v[96:97], 0, v[144:145]
	v_pk_add_f32 v[76:77], v[76:77], v[202:203]
	v_pk_add_f32 v[94:95], v[98:99], v[192:193]
	global_store_dwordx4 v[96:97], v[84:87], off
	global_store_dwordx4 v[96:97], v[92:95], off offset:16
	v_pk_add_f32 v[74:75], v[74:75], v[200:201]
	v_pk_add_f32 v[72:73], v[72:73], v[198:199]
	global_store_dwordx4 v[96:97], v[76:79], off offset:512
	global_store_dwordx4 v[96:97], v[72:75], off offset:528
	v_pk_add_f32 v[70:71], v[70:71], v[220:221]
	v_pk_add_f32 v[76:77], v[80:81], v[206:207]
	v_lshl_add_u64 v[80:81], s[54:55], 0, v[154:155]
	v_pk_add_f32 v[74:75], v[90:91], v[212:213]
	v_pk_add_f32 v[72:73], v[88:89], v[210:211]
	v_lshl_add_u64 v[80:81], v[80:81], 0, v[144:145]
	v_pk_add_f32 v[68:69], v[68:69], v[218:219]
	v_pk_add_f32 v[64:65], v[64:65], v[214:215]
	v_lshl_add_u64 v[154:155], v[148:149], 0, s[10:11]
	v_pk_add_f32 v[78:79], v[82:83], v[208:209]
	global_store_dwordx4 v[80:81], v[72:75], off
	global_store_dwordx4 v[80:81], v[76:79], off offset:16
	v_pk_add_f32 v[66:67], v[66:67], v[216:217]
	global_store_dwordx4 v[80:81], v[68:71], off offset:512
	global_store_dwordx4 v[80:81], v[64:67], off offset:528
	v_lshl_add_u64 v[152:153], v[148:149], 0, s[12:13]
	v_lshl_add_u64 v[150:151], v[148:149], 0, s[14:15]
	v_lshl_add_u64 v[64:65], v[146:147], 0, v[154:155]
	global_load_dwordx4 v[108:111], v[64:65], off offset:16
	global_load_dwordx4 v[120:123], v[64:65], off
	global_load_dwordx4 v[92:95], v[64:65], off offset:528
	global_load_dwordx4 v[100:103], v[64:65], off offset:512
	v_lshl_add_u64 v[64:65], v[146:147], 0, v[152:153]
	global_load_dwordx4 v[88:91], v[64:65], off offset:16
	global_load_dwordx4 v[96:99], v[64:65], off
	global_load_dwordx4 v[76:79], v[64:65], off offset:528
	global_load_dwordx4 v[84:87], v[64:65], off offset:512
	v_lshl_add_u64 v[68:69], v[146:147], 0, v[150:151]
	global_load_dwordx4 v[72:75], v[68:69], off offset:16
	global_load_dwordx4 v[80:83], v[68:69], off
	global_load_dwordx4 v[64:67], v[68:69], off offset:528
	s_nop 0
	global_load_dwordx4 v[68:71], v[68:69], off offset:512
	v_lshl_add_u64 v[148:149], v[148:149], 0, s[6:7]
	v_lshl_add_u64 v[112:113], v[146:147], 0, v[148:149]
	global_load_dwordx4 v[116:119], v[112:113], off offset:16
	global_load_dwordx4 v[124:127], v[112:113], off
	global_load_dwordx4 v[104:107], v[112:113], off offset:528
	s_nop 0
	global_load_dwordx4 v[112:115], v[112:113], off offset:512
	s_waitcnt vmcnt(0)
	v_pk_add_f32 v[56:57], v[56:57], v[108:109]
	v_lshl_add_u64 v[108:109], s[54:55], 0, v[154:155]
	v_pk_add_f32 v[62:63], v[62:63], v[122:123]
	v_pk_add_f32 v[60:61], v[60:61], v[120:121]
	v_lshl_add_u64 v[108:109], v[108:109], 0, v[144:145]
	v_pk_add_f32 v[50:51], v[50:51], v[102:103]
	v_pk_add_f32 v[48:49], v[48:49], v[100:101]
	v_pk_add_f32 v[58:59], v[58:59], v[110:111]
	global_store_dwordx4 v[108:109], v[60:63], off
	global_store_dwordx4 v[108:109], v[56:59], off offset:16
	v_pk_add_f32 v[42:43], v[42:43], v[94:95]
	v_pk_add_f32 v[40:41], v[40:41], v[92:93]
	global_store_dwordx4 v[108:109], v[48:51], off offset:512
	global_store_dwordx4 v[108:109], v[40:43], off offset:528
	v_pk_add_f32 v[34:35], v[34:35], v[86:87]
	v_lshl_add_u64 v[48:49], s[54:55], 0, v[152:153]
	v_pk_add_f32 v[42:43], v[54:55], v[98:99]
	v_pk_add_f32 v[40:41], v[52:53], v[96:97]
	v_lshl_add_u64 v[48:49], v[48:49], 0, v[144:145]
	v_pk_add_f32 v[32:33], v[32:33], v[84:85]
	v_pk_add_f32 v[46:47], v[46:47], v[90:91]
	v_pk_add_f32 v[44:45], v[44:45], v[88:89]
	global_store_dwordx4 v[48:49], v[40:43], off
	global_store_dwordx4 v[48:49], v[44:47], off offset:16
	v_pk_add_f32 v[26:27], v[26:27], v[78:79]
	v_pk_add_f32 v[24:25], v[24:25], v[76:77]
	global_store_dwordx4 v[48:49], v[32:35], off offset:512
	global_store_dwordx4 v[48:49], v[24:27], off offset:528
	v_pk_add_f32 v[18:19], v[18:19], v[70:71]
	v_lshl_add_u64 v[32:33], s[54:55], 0, v[150:151]
	v_pk_add_f32 v[26:27], v[38:39], v[82:83]
	v_pk_add_f32 v[24:25], v[36:37], v[80:81]
	v_lshl_add_u64 v[32:33], v[32:33], 0, v[144:145]
	v_pk_add_f32 v[16:17], v[16:17], v[68:69]
	v_pk_add_f32 v[30:31], v[30:31], v[74:75]
	v_pk_add_f32 v[28:29], v[28:29], v[72:73]
	global_store_dwordx4 v[32:33], v[24:27], off
	global_store_dwordx4 v[32:33], v[28:31], off offset:16
	v_pk_add_f32 v[10:11], v[10:11], v[66:67]
	v_pk_add_f32 v[8:9], v[8:9], v[64:65]
	global_store_dwordx4 v[32:33], v[16:19], off offset:512
	global_store_dwordx4 v[32:33], v[8:11], off offset:528
	v_pk_add_f32 v[6:7], v[6:7], v[114:115]
	v_lshl_add_u64 v[16:17], s[54:55], 0, v[148:149]
	v_pk_add_f32 v[10:11], v[22:23], v[126:127]
	v_pk_add_f32 v[8:9], v[20:21], v[124:125]
	v_lshl_add_u64 v[16:17], v[16:17], 0, v[144:145]
	v_pk_add_f32 v[4:5], v[4:5], v[112:113]
	v_pk_add_f32 v[14:15], v[14:15], v[118:119]
	v_pk_add_f32 v[12:13], v[12:13], v[116:117]
	global_store_dwordx4 v[16:17], v[8:11], off
	global_store_dwordx4 v[16:17], v[12:15], off offset:16
	v_pk_add_f32 v[2:3], v[2:3], v[106:107]
	v_pk_add_f32 v[0:1], v[0:1], v[104:105]
	global_store_dwordx4 v[16:17], v[4:7], off offset:512
	global_store_dwordx4 v[16:17], v[0:3], off offset:528
	s_cbranch_vccz .LBB0_1417
	s_waitcnt vmcnt(0)
	s_cmpk_gt_u32 s23, 0xff
	s_cbranch_scc1 .LBB0_1428
	s_barrier
